# hand-written SSD output item (B slab and decay vectors by LDS-DMA, all first-stage loads issued up front, pipelined mask/MFMA), static one item per workgroup, sp4 queue removed
# speedup vs baseline: 1.2900x; 1.0312x over previous
.Ls5l_back:
	s_cmp_eq_u32 s5, 4
	s_cbranch_scc1 .Lssd_entry

.Lssd_entry:
	s_cmpk_ge_u32 s63, 0xc0
	s_cbranch_scc1 .Lssd_back
	v_and_b32_e32 v227, 63, v206
	v_lshrrev_b32_e32 v228, 6, v206
	v_and_b32_e32 v0, 15, v227
	v_readfirstlane_b32 s40, v228
	v_lshrrev_b32_e32 v1, 4, v227
	s_lshr_b32 s42, s63, 2
	s_and_b32 s43, s63, 3
	s_lshr_b32 s41, s40, 2
	s_lshl_b32 s34, s42, 7
	s_lshl_b32 s35, s43, 5
	s_add_u32 s34, s34, s35
	s_lshl_b32 s100, s42, 4
	s_add_u32 s100, s100, s40
	s_lshl_b32 s100, s100, 9
	s_add_u32 s101, s100, 0xcae4000
	s_add_u32 s48, s96, s101
	s_addc_u32 s49, s97, 0
	s_add_u32 s101, s100, 0xca84000
	s_add_u32 s50, s96, s101
	s_addc_u32 s51, s97, 0
	v_lshrrev_b32_e32 v229, 5, v227
	v_and_b32_e32 v230, 31, v227
	v_lshlrev_b32_e32 v229, 12, v229
	v_lshl_add_u32 v229, v230, 4, v229
	s_lshl_b32 s38, s40, 11
	s_add_u32 s38, s38, 0x10000
	s_mov_b32 m0, s38
	s_nop 0
	global_load_lds_dwordx4 v229, s[48:49]
	s_add_u32 m0, s38, 0x400
	s_nop 0
	global_load_lds_dwordx4 v229, s[50:51]
	s_lshl_b32 s100, s34, 9
	s_lshl_b32 s101, s41, 8
	s_add_u32 s100, s100, s101
	s_add_u32 s100, s100, 0xbb84000
	s_add_u32 s44, s96, s100
	s_addc_u32 s45, s97, 0
	v_lshlrev_b32_e32 v230, 9, v0
	v_lshl_add_u32 v230, v1, 4, v230
	v_add_u32_e32 v231, 0x2000, v230
	global_load_dwordx4 v[4:7], v230, s[44:45]
	global_load_dwordx4 v[8:11], v230, s[44:45] offset:64
	global_load_dwordx4 v[12:15], v230, s[44:45] offset:128
	global_load_dwordx4 v[16:19], v230, s[44:45] offset:192
	global_load_dwordx4 v[20:23], v231, s[44:45]
	global_load_dwordx4 v[24:27], v231, s[44:45] offset:64
	global_load_dwordx4 v[28:31], v231, s[44:45] offset:128
	global_load_dwordx4 v[32:35], v231, s[44:45] offset:192
	s_and_b32 s100, s40, 3
	s_lshl_b32 s101, s100, 5
	s_lshl_b32 s39, s42, 7
	s_add_u32 s101, s101, s39
	s_lshl_b32 s101, s101, 9
	s_lshl_b32 s39, s41, 8
	s_add_u32 s101, s101, s39
	s_add_u32 s101, s101, 0xb884000
	s_add_u32 s46, s96, s101
	s_addc_u32 s47, s97, 0
	s_lshl_b32 s39, s41, 15
	s_lshl_b32 s100, s100, 13
	s_add_u32 s39, s39, s100
	v_and_b32_e32 v230, 15, v227
	v_add_u32_e32 v231, 0, v1
	v_xor_b32_e32 v231, v231, v230
	v_lshlrev_b32_e32 v231, 4, v231
	v_lshl_add_u32 v199, v1, 9, v231
	v_add_u32_e32 v231, 4, v1
	v_xor_b32_e32 v231, v231, v230
	v_lshlrev_b32_e32 v231, 4, v231
	v_lshl_add_u32 v200, v1, 9, v231
	v_add_u32_e32 v231, 8, v1
	v_xor_b32_e32 v231, v231, v230
	v_lshlrev_b32_e32 v231, 4, v231
	v_lshl_add_u32 v201, v1, 9, v231
	v_add_u32_e32 v231, 12, v1
	v_xor_b32_e32 v231, v231, v230
	v_lshlrev_b32_e32 v231, 4, v231
	v_lshl_add_u32 v202, v1, 9, v231
	s_add_u32 m0, s39, 0x0
	s_nop 0
	global_load_lds_dwordx4 v199, s[46:47]
	s_add_u32 s46, s46, 0x800
	s_addc_u32 s47, s47, 0
	s_add_u32 m0, s39, 0x400
	s_nop 0
	global_load_lds_dwordx4 v200, s[46:47]
	s_add_u32 s46, s46, 0x800
	s_addc_u32 s47, s47, 0
	s_add_u32 m0, s39, 0x800
	s_nop 0
	global_load_lds_dwordx4 v201, s[46:47]
	s_add_u32 s46, s46, 0x800
	s_addc_u32 s47, s47, 0
	s_add_u32 m0, s39, 0xc00
	s_nop 0
	global_load_lds_dwordx4 v202, s[46:47]
	s_add_u32 s46, s46, 0x800
	s_addc_u32 s47, s47, 0
	s_add_u32 m0, s39, 0x1000
	s_nop 0
	global_load_lds_dwordx4 v199, s[46:47]
	s_add_u32 s46, s46, 0x800
	s_addc_u32 s47, s47, 0
	s_add_u32 m0, s39, 0x1400
	s_nop 0
	global_load_lds_dwordx4 v200, s[46:47]
	s_add_u32 s46, s46, 0x800
	s_addc_u32 s47, s47, 0
	s_add_u32 m0, s39, 0x1800
	s_nop 0
	global_load_lds_dwordx4 v201, s[46:47]
	s_add_u32 s46, s46, 0x800
	s_addc_u32 s47, s47, 0
	s_add_u32 m0, s39, 0x1c00
	s_nop 0
	global_load_lds_dwordx4 v202, s[46:47]
	v_readlane_b32 s98, v237, 27
	v_readlane_b32 s99, v237, 28
	s_lshl_b32 s100, s36, 11
	s_lshl_b32 s101, s40, 8
	s_add_u32 s100, s100, s101
	s_add_u32 s98, s98, s100
	s_addc_u32 s99, s99, 0
	v_lshlrev_b32_e32 v232, 2, v0
	s_nop 0
	global_load_dword v188, v232, s[98:99]
	global_load_dword v189, v232, s[98:99] offset:64
	global_load_dword v190, v232, s[98:99] offset:128
	global_load_dword v191, v232, s[98:99] offset:192
	v_readlane_b32 s98, v237, 25
	v_readlane_b32 s99, v237, 26
	s_lshl_b32 s100, s36, 3
	s_add_u32 s100, s100, s40
	s_lshl_b32 s100, s100, 2
	s_add_u32 s98, s98, s100
	s_addc_u32 s99, s99, 0
	s_load_dword s92, s[98:99], 0x0
	s_lshl_b32 s100, s42, 3
	s_add_u32 s100, s100, s40
	s_lshl_b32 s100, s100, 14
	s_add_u32 s100, s100, 0xc184000
	s_add_u32 s50, s96, s100
	s_addc_u32 s51, s97, 0
	s_lshl_b32 s100, s42, 4
	s_add_u32 s100, s100, s40
	s_lshl_b32 s100, s100, 14
	s_add_u32 s100, s100, 0xac84000
	s_add_u32 s52, s96, s100
	s_addc_u32 s53, s97, 0
	s_add_u32 s54, s52, 0x20000
	s_addc_u32 s55, s53, 0
	s_mul_i32 s100, s34, 0x2440
	s_lshl_b32 s101, s40, 8
	s_add_u32 s100, s100, s101
	s_add_u32 s100, s100, 0x3a24000
	s_add_u32 s56, s96, s100
	s_addc_u32 s57, s97, 0
	s_lshl_b32 s100, s34, 11
	s_lshl_b32 s101, s40, 7
	s_add_u32 s100, s100, s101
	s_add_u32 s100, s100, 0x7084000
	s_add_u32 s58, s96, s100
	s_addc_u32 s59, s97, 0
	v_lshlrev_b32_e32 v232, 8, v0
	v_lshl_add_u32 v204, v1, 3, v232
	v_lshl_add_u32 v205, v1, 4, v232
	v_mul_u32_u24_e32 v197, 0x9100, v1
	v_lshl_add_u32 v197, v0, 2, v197
	v_lshlrev_b32_e32 v221, 13, v1
	v_lshl_add_u32 v221, v0, 1, v221
	global_load_dwordx2 v[68:69], v204, s[50:51]
	global_load_dwordx2 v[70:71], v204, s[50:51] offset:32
	global_load_dwordx2 v[72:73], v204, s[50:51] offset:64
	global_load_dwordx2 v[74:75], v204, s[50:51] offset:96
	global_load_dwordx2 v[76:77], v204, s[50:51] offset:128
	global_load_dwordx2 v[78:79], v204, s[50:51] offset:160
	global_load_dwordx2 v[80:81], v204, s[50:51] offset:192
	global_load_dwordx2 v[82:83], v204, s[50:51] offset:224
	s_add_u32 s50, s50, 0x1000
	s_addc_u32 s51, s51, 0
	global_load_dwordx4 v[84:87], v205, s[52:53]
	global_load_dwordx4 v[88:91], v205, s[52:53] offset:64
	global_load_dwordx4 v[92:95], v205, s[52:53] offset:128
	global_load_dwordx4 v[96:99], v205, s[52:53] offset:192
	global_load_dwordx4 v[100:103], v205, s[54:55]
	global_load_dwordx4 v[104:107], v205, s[54:55] offset:64
	global_load_dwordx4 v[108:111], v205, s[54:55] offset:128
	global_load_dwordx4 v[112:115], v205, s[54:55] offset:192
	s_add_u32 s52, s52, 0x1000
	s_addc_u32 s53, s53, 0
	s_add_u32 s54, s54, 0x1000
	s_addc_u32 s55, s55, 0
	global_load_dword v180, v197, s[56:57]
	v_add_u32_e32 v233, 0x2440, v197
	global_load_dword v181, v233, s[56:57]
	v_add_u32_e32 v233, 0x4880, v197
	global_load_dword v182, v233, s[56:57]
	v_add_u32_e32 v233, 0x6cc0, v197
	global_load_dword v183, v233, s[56:57]
	v_add_u32_e32 v233, 0x24400, v197
	global_load_dword v184, v233, s[56:57]
	v_add_u32_e32 v233, 0x26840, v197
	global_load_dword v185, v233, s[56:57]
	v_add_u32_e32 v233, 0x28c80, v197
	global_load_dword v186, v233, s[56:57]
	v_add_u32_e32 v233, 0x2b0c0, v197
	global_load_dword v187, v233, s[56:57]
	v_sub_u32_e32 v3, v0, v1
	v_sub_u32_e32 v3, v3, v1
	v_sub_u32_e32 v3, v3, v1
	v_sub_u32_e32 v3, v3, v1
	s_lshl_b32 s39, s41, 15
	v_add_u32_e32 v231, 0, v1
	v_xor_b32_e32 v231, v231, v0
	v_lshlrev_b32_e32 v231, 4, v231
	v_lshl_add_u32 v199, v0, 8, v231
	v_add_u32_e32 v231, 4, v1
	v_xor_b32_e32 v231, v231, v0
	v_lshlrev_b32_e32 v231, 4, v231
	v_lshl_add_u32 v200, v0, 8, v231
	v_add_u32_e32 v231, 8, v1
	v_xor_b32_e32 v231, v231, v0
	v_lshlrev_b32_e32 v231, 4, v231
	v_lshl_add_u32 v201, v0, 8, v231
	v_add_u32_e32 v231, 12, v1
	v_xor_b32_e32 v231, v231, v0
	v_lshlrev_b32_e32 v231, 4, v231
	v_lshl_add_u32 v202, v0, 8, v231
	v_add_u32_e32 v199, s39, v199
	v_add_u32_e32 v200, s39, v200
	v_add_u32_e32 v201, s39, v201
	v_add_u32_e32 v202, s39, v202
	v_lshl_add_u32 v203, v1, 4, s38
	s_lshl_b32 s100, s40, 13
	v_lshl_add_u32 v225, v227, 4, s100
	s_lshl_b32 s100, s40, 2
	s_add_u32 s100, s100, 0x14000
	v_lshl_add_u32 v226, v1, 7, s100
	s_lshl_b32 s39, s43, 1
	s_waitcnt vmcnt(28) lgkmcnt(0)
	v_mov_b32_e32 v224, s92
	s_barrier
	s_lshl_b32 s100, s35, 2
	s_add_u32 s100, s100, s38
	v_lshl_add_u32 v232, v0, 2, s100
	s_nop 0
	ds_read_b32 v192, v232 offset:0
	ds_read_b32 v194, v232 offset:512
	ds_read_b32 v222, v232 offset:1024
	ds_read_b32 v227, v232 offset:1536
	ds_read_b32 v193, v232 offset:64
	ds_read_b32 v195, v232 offset:576
	ds_read_b32 v223, v232 offset:1088
	ds_read_b32 v228, v232 offset:1600
	ds_read_b128 v[132:135], v199 offset:0
	ds_read_b128 v[136:139], v200 offset:0
	ds_read_b128 v[140:143], v201 offset:0
	ds_read_b128 v[144:147], v202 offset:0
	ds_read_b128 v[148:151], v199 offset:4096
	ds_read_b128 v[152:155], v200 offset:4096
	ds_read_b128 v[156:159], v201 offset:4096
	ds_read_b128 v[160:163], v202 offset:4096
	ds_read_b128 v[164:167], v203 offset:0
	ds_read_b128 v[168:171], v203 offset:512
	ds_read_b128 v[172:175], v203 offset:1024
	ds_read_b128 v[176:179], v203 offset:1536
	s_waitcnt lgkmcnt(8)
	v_add_f32_e32 v222, v222, v227
	v_add_f32_e32 v223, v223, v228
	v_mfma_f32_16x16x32_bf16 v[116:119], v[132:135], v[4:7], 0
	v_mfma_f32_16x16x32_bf16 v[120:123], v[132:135], v[20:23], 0
	v_mfma_f32_16x16x32_bf16 v[116:119], v[136:139], v[8:11], v[116:119]
	v_mfma_f32_16x16x32_bf16 v[120:123], v[136:139], v[24:27], v[120:123]
	v_mfma_f32_16x16x32_bf16 v[116:119], v[140:143], v[12:15], v[116:119]
	v_mfma_f32_16x16x32_bf16 v[120:123], v[140:143], v[28:31], v[120:123]
	v_mfma_f32_16x16x32_bf16 v[116:119], v[144:147], v[16:19], v[116:119]
	v_mfma_f32_16x16x32_bf16 v[120:123], v[144:147], v[32:35], v[120:123]
	s_waitcnt lgkmcnt(4)
	v_mfma_f32_16x16x32_bf16 v[124:127], v[148:151], v[4:7], 0
	v_mfma_f32_16x16x32_bf16 v[128:131], v[148:151], v[20:23], 0
	v_mfma_f32_16x16x32_bf16 v[124:127], v[152:155], v[8:11], v[124:127]
	v_mfma_f32_16x16x32_bf16 v[128:131], v[152:155], v[24:27], v[128:131]
	v_mfma_f32_16x16x32_bf16 v[124:127], v[156:159], v[12:15], v[124:127]
	v_mfma_f32_16x16x32_bf16 v[128:131], v[156:159], v[28:31], v[128:131]
	v_mfma_f32_16x16x32_bf16 v[124:127], v[160:163], v[16:19], v[124:127]
	v_mfma_f32_16x16x32_bf16 v[128:131], v[160:163], v[32:35], v[128:131]
	ds_read_b128 v[132:135], v199 offset:8192
	ds_read_b128 v[136:139], v200 offset:8192
	ds_read_b128 v[140:143], v201 offset:8192
	ds_read_b128 v[144:147], v202 offset:8192
	s_waitcnt lgkmcnt(4)
	s_cmp_gt_u32 s39, 0
	s_cbranch_scc1 .Lssd_f0
	s_cmp_lt_u32 s39, 0
	s_cbranch_scc1 .Lssd_b0
	v_cmp_lt_i32_e32 vcc, 0, v3
	s_nop 1
	v_cndmask_b32_e32 v230, v168, v164, vcc
	v_cndmask_b32_e32 v231, v176, v172, vcc
	v_cndmask_b32_e32 v229, v194, v192, vcc
	v_sub_f32_e32 v229, v229, v230
	v_mul_f32_e32 v229, 0x3fb8aa3b, v229
	v_exp_f32_e32 v229, v229
	v_cmp_eq_u32_e32 vcc, 0, v3
	v_mul_f32_e32 v229, v229, v231
	s_nop 0
	v_cndmask_b32_e32 v229, v229, v222, vcc
	v_cndmask_b32_e32 v230, 0, v224, vcc
	v_fma_f32 v116, v116, v229, v230
	v_cmp_lt_i32_e32 vcc, 1, v3
	s_nop 1
	v_cndmask_b32_e32 v230, v169, v165, vcc
	v_cndmask_b32_e32 v231, v177, v173, vcc
	v_cndmask_b32_e32 v229, v194, v192, vcc
	v_sub_f32_e32 v229, v229, v230
	v_mul_f32_e32 v229, 0x3fb8aa3b, v229
	v_exp_f32_e32 v229, v229
	v_cmp_eq_u32_e32 vcc, 1, v3
	v_mul_f32_e32 v229, v229, v231
	s_nop 0
	v_cndmask_b32_e32 v229, v229, v222, vcc
	v_cndmask_b32_e32 v230, 0, v224, vcc
	v_fma_f32 v117, v117, v229, v230
	v_cmp_lt_i32_e32 vcc, 2, v3
	s_nop 1
	v_cndmask_b32_e32 v230, v170, v166, vcc
	v_cndmask_b32_e32 v231, v178, v174, vcc
	v_cndmask_b32_e32 v229, v194, v192, vcc
	v_sub_f32_e32 v229, v229, v230
	v_mul_f32_e32 v229, 0x3fb8aa3b, v229
	v_exp_f32_e32 v229, v229
	v_cmp_eq_u32_e32 vcc, 2, v3
	v_mul_f32_e32 v229, v229, v231
	s_nop 0
	v_cndmask_b32_e32 v229, v229, v222, vcc
	v_cndmask_b32_e32 v230, 0, v224, vcc
	v_fma_f32 v118, v118, v229, v230
	v_cmp_lt_i32_e32 vcc, 3, v3
	s_nop 1
	v_cndmask_b32_e32 v230, v171, v167, vcc
	v_cndmask_b32_e32 v231, v179, v175, vcc
	v_cndmask_b32_e32 v229, v194, v192, vcc
	v_sub_f32_e32 v229, v229, v230
	v_mul_f32_e32 v229, 0x3fb8aa3b, v229
	v_exp_f32_e32 v229, v229
	v_cmp_eq_u32_e32 vcc, 3, v3
	v_mul_f32_e32 v229, v229, v231
	s_nop 0
	v_cndmask_b32_e32 v229, v229, v222, vcc
	v_cndmask_b32_e32 v230, 0, v224, vcc
	v_fma_f32 v119, v119, v229, v230
	s_branch .Lssd_j0
.Lssd_f0:
	v_sub_f32_e32 v229, v192, v164
	v_sub_f32_e32 v230, v192, v165
	v_sub_f32_e32 v231, v192, v166
	v_sub_f32_e32 v232, v192, v167
	v_mul_f32_e32 v229, 0x3fb8aa3b, v229
	v_mul_f32_e32 v230, 0x3fb8aa3b, v230
	v_mul_f32_e32 v231, 0x3fb8aa3b, v231
	v_mul_f32_e32 v232, 0x3fb8aa3b, v232
	v_exp_f32_e32 v229, v229
	v_exp_f32_e32 v230, v230
	v_exp_f32_e32 v231, v231
	v_exp_f32_e32 v232, v232
	s_nop 0
	v_mul_f32_e32 v116, v116, v229
	v_mul_f32_e32 v117, v117, v230
	v_mul_f32_e32 v118, v118, v231
	v_mul_f32_e32 v119, v119, v232
	v_mul_f32_e32 v116, v116, v172
	v_mul_f32_e32 v117, v117, v173
	v_mul_f32_e32 v118, v118, v174
	v_mul_f32_e32 v119, v119, v175
	s_branch .Lssd_j0
.Lssd_b0:
	v_sub_f32_e32 v229, v194, v168
	v_sub_f32_e32 v230, v194, v169
	v_sub_f32_e32 v231, v194, v170
	v_sub_f32_e32 v232, v194, v171
	v_mul_f32_e32 v229, 0x3fb8aa3b, v229
	v_mul_f32_e32 v230, 0x3fb8aa3b, v230
	v_mul_f32_e32 v231, 0x3fb8aa3b, v231
	v_mul_f32_e32 v232, 0x3fb8aa3b, v232
	v_exp_f32_e32 v229, v229
	v_exp_f32_e32 v230, v230
	v_exp_f32_e32 v231, v231
	v_exp_f32_e32 v232, v232
	s_nop 0
	v_mul_f32_e32 v116, v116, v229
	v_mul_f32_e32 v117, v117, v230
	v_mul_f32_e32 v118, v118, v231
	v_mul_f32_e32 v119, v119, v232
	v_mul_f32_e32 v116, v116, v176
	v_mul_f32_e32 v117, v117, v177
	v_mul_f32_e32 v118, v118, v178
	v_mul_f32_e32 v119, v119, v179
.Lssd_j0:
	v_cvt_pk_bf16_f32 v36, v116, v117
	v_cvt_pk_bf16_f32 v37, v118, v119
	s_cmp_ge_u32 s39, 0
	s_cbranch_scc1 .Lssd_f1
	s_cmp_lt_u32 s39, 0
	s_cbranch_scc1 .Lssd_b1
	v_cmp_lt_i32_e32 vcc, 0, v3
	s_nop 1
	v_cndmask_b32_e32 v230, v168, v164, vcc
	v_cndmask_b32_e32 v231, v176, v172, vcc
	v_cndmask_b32_e32 v229, v195, v193, vcc
	v_sub_f32_e32 v229, v229, v230
	v_mul_f32_e32 v229, 0x3fb8aa3b, v229
	v_exp_f32_e32 v229, v229
	v_cmp_eq_u32_e32 vcc, 0, v3
	v_mul_f32_e32 v229, v229, v231
	s_nop 0
	v_cndmask_b32_e32 v229, v229, v223, vcc
	v_cndmask_b32_e32 v230, 0, v224, vcc
	v_fma_f32 v120, v120, v229, v230
	v_cmp_lt_i32_e32 vcc, 1, v3
	s_nop 1
	v_cndmask_b32_e32 v230, v169, v165, vcc
	v_cndmask_b32_e32 v231, v177, v173, vcc
	v_cndmask_b32_e32 v229, v195, v193, vcc
	v_sub_f32_e32 v229, v229, v230
	v_mul_f32_e32 v229, 0x3fb8aa3b, v229
	v_exp_f32_e32 v229, v229
	v_cmp_eq_u32_e32 vcc, 1, v3
	v_mul_f32_e32 v229, v229, v231
	s_nop 0
	v_cndmask_b32_e32 v229, v229, v223, vcc
	v_cndmask_b32_e32 v230, 0, v224, vcc
	v_fma_f32 v121, v121, v229, v230
	v_cmp_lt_i32_e32 vcc, 2, v3
	s_nop 1
	v_cndmask_b32_e32 v230, v170, v166, vcc
	v_cndmask_b32_e32 v231, v178, v174, vcc
	v_cndmask_b32_e32 v229, v195, v193, vcc
	v_sub_f32_e32 v229, v229, v230
	v_mul_f32_e32 v229, 0x3fb8aa3b, v229
	v_exp_f32_e32 v229, v229
	v_cmp_eq_u32_e32 vcc, 2, v3
	v_mul_f32_e32 v229, v229, v231
	s_nop 0
	v_cndmask_b32_e32 v229, v229, v223, vcc
	v_cndmask_b32_e32 v230, 0, v224, vcc
	v_fma_f32 v122, v122, v229, v230
	v_cmp_lt_i32_e32 vcc, 3, v3
	s_nop 1
	v_cndmask_b32_e32 v230, v171, v167, vcc
	v_cndmask_b32_e32 v231, v179, v175, vcc
	v_cndmask_b32_e32 v229, v195, v193, vcc
	v_sub_f32_e32 v229, v229, v230
	v_mul_f32_e32 v229, 0x3fb8aa3b, v229
	v_exp_f32_e32 v229, v229
	v_cmp_eq_u32_e32 vcc, 3, v3
	v_mul_f32_e32 v229, v229, v231
	s_nop 0
	v_cndmask_b32_e32 v229, v229, v223, vcc
	v_cndmask_b32_e32 v230, 0, v224, vcc
	v_fma_f32 v123, v123, v229, v230
	s_branch .Lssd_j1
.Lssd_f1:
	v_sub_f32_e32 v229, v193, v164
	v_sub_f32_e32 v230, v193, v165
	v_sub_f32_e32 v231, v193, v166
	v_sub_f32_e32 v232, v193, v167
	v_mul_f32_e32 v229, 0x3fb8aa3b, v229
	v_mul_f32_e32 v230, 0x3fb8aa3b, v230
	v_mul_f32_e32 v231, 0x3fb8aa3b, v231
	v_mul_f32_e32 v232, 0x3fb8aa3b, v232
	v_exp_f32_e32 v229, v229
	v_exp_f32_e32 v230, v230
	v_exp_f32_e32 v231, v231
	v_exp_f32_e32 v232, v232
	s_nop 0
	v_mul_f32_e32 v120, v120, v229
	v_mul_f32_e32 v121, v121, v230
	v_mul_f32_e32 v122, v122, v231
	v_mul_f32_e32 v123, v123, v232
	v_mul_f32_e32 v120, v120, v172
	v_mul_f32_e32 v121, v121, v173
	v_mul_f32_e32 v122, v122, v174
	v_mul_f32_e32 v123, v123, v175
	s_branch .Lssd_j1
.Lssd_b1:
	v_sub_f32_e32 v229, v195, v168
	v_sub_f32_e32 v230, v195, v169
	v_sub_f32_e32 v231, v195, v170
	v_sub_f32_e32 v232, v195, v171
	v_mul_f32_e32 v229, 0x3fb8aa3b, v229
	v_mul_f32_e32 v230, 0x3fb8aa3b, v230
	v_mul_f32_e32 v231, 0x3fb8aa3b, v231
	v_mul_f32_e32 v232, 0x3fb8aa3b, v232
	v_exp_f32_e32 v229, v229
	v_exp_f32_e32 v230, v230
	v_exp_f32_e32 v231, v231
	v_exp_f32_e32 v232, v232
	s_nop 0
	v_mul_f32_e32 v120, v120, v229
	v_mul_f32_e32 v121, v121, v230
	v_mul_f32_e32 v122, v122, v231
	v_mul_f32_e32 v123, v123, v232
	v_mul_f32_e32 v120, v120, v176
	v_mul_f32_e32 v121, v121, v177
	v_mul_f32_e32 v122, v122, v178
	v_mul_f32_e32 v123, v123, v179
.Lssd_j1:
	v_cvt_pk_bf16_f32 v52, v120, v121
	v_cvt_pk_bf16_f32 v53, v122, v123
	ds_read_b128 v[164:167], v203 offset:64
	ds_read_b128 v[168:171], v203 offset:576
	ds_read_b128 v[172:175], v203 offset:1088
	ds_read_b128 v[176:179], v203 offset:1600
	s_waitcnt lgkmcnt(4)
	v_mfma_f32_16x16x32_bf16 v[116:119], v[132:135], v[4:7], 0
	v_mfma_f32_16x16x32_bf16 v[120:123], v[132:135], v[20:23], 0
	v_mfma_f32_16x16x32_bf16 v[116:119], v[136:139], v[8:11], v[116:119]
	v_mfma_f32_16x16x32_bf16 v[120:123], v[136:139], v[24:27], v[120:123]
	v_mfma_f32_16x16x32_bf16 v[116:119], v[140:143], v[12:15], v[116:119]
	v_mfma_f32_16x16x32_bf16 v[120:123], v[140:143], v[28:31], v[120:123]
	v_mfma_f32_16x16x32_bf16 v[116:119], v[144:147], v[16:19], v[116:119]
	v_mfma_f32_16x16x32_bf16 v[120:123], v[144:147], v[32:35], v[120:123]
	ds_read_b128 v[148:151], v199 offset:12288
	ds_read_b128 v[152:155], v200 offset:12288
	ds_read_b128 v[156:159], v201 offset:12288
	ds_read_b128 v[160:163], v202 offset:12288
	s_waitcnt lgkmcnt(4)
	s_cmp_gt_u32 s39, 1
	s_cbranch_scc1 .Lssd_f2
	s_cmp_lt_u32 s39, 1
	s_cbranch_scc1 .Lssd_b2
	v_cmp_lt_i32_e32 vcc, 0, v3
	s_nop 1
	v_cndmask_b32_e32 v230, v168, v164, vcc
	v_cndmask_b32_e32 v231, v176, v172, vcc
	v_cndmask_b32_e32 v229, v194, v192, vcc
	v_sub_f32_e32 v229, v229, v230
	v_mul_f32_e32 v229, 0x3fb8aa3b, v229
	v_exp_f32_e32 v229, v229
	v_cmp_eq_u32_e32 vcc, 0, v3
	v_mul_f32_e32 v229, v229, v231
	s_nop 0
	v_cndmask_b32_e32 v229, v229, v222, vcc
	v_cndmask_b32_e32 v230, 0, v224, vcc
	v_fma_f32 v124, v124, v229, v230
	v_cmp_lt_i32_e32 vcc, 1, v3
	s_nop 1
	v_cndmask_b32_e32 v230, v169, v165, vcc
	v_cndmask_b32_e32 v231, v177, v173, vcc
	v_cndmask_b32_e32 v229, v194, v192, vcc
	v_sub_f32_e32 v229, v229, v230
	v_mul_f32_e32 v229, 0x3fb8aa3b, v229
	v_exp_f32_e32 v229, v229
	v_cmp_eq_u32_e32 vcc, 1, v3
	v_mul_f32_e32 v229, v229, v231
	s_nop 0
	v_cndmask_b32_e32 v229, v229, v222, vcc
	v_cndmask_b32_e32 v230, 0, v224, vcc
	v_fma_f32 v125, v125, v229, v230
	v_cmp_lt_i32_e32 vcc, 2, v3
	s_nop 1
	v_cndmask_b32_e32 v230, v170, v166, vcc
	v_cndmask_b32_e32 v231, v178, v174, vcc
	v_cndmask_b32_e32 v229, v194, v192, vcc
	v_sub_f32_e32 v229, v229, v230
	v_mul_f32_e32 v229, 0x3fb8aa3b, v229
	v_exp_f32_e32 v229, v229
	v_cmp_eq_u32_e32 vcc, 2, v3
	v_mul_f32_e32 v229, v229, v231
	s_nop 0
	v_cndmask_b32_e32 v229, v229, v222, vcc
	v_cndmask_b32_e32 v230, 0, v224, vcc
	v_fma_f32 v126, v126, v229, v230
	v_cmp_lt_i32_e32 vcc, 3, v3
	s_nop 1
	v_cndmask_b32_e32 v230, v171, v167, vcc
	v_cndmask_b32_e32 v231, v179, v175, vcc
	v_cndmask_b32_e32 v229, v194, v192, vcc
	v_sub_f32_e32 v229, v229, v230
	v_mul_f32_e32 v229, 0x3fb8aa3b, v229
	v_exp_f32_e32 v229, v229
	v_cmp_eq_u32_e32 vcc, 3, v3
	v_mul_f32_e32 v229, v229, v231
	s_nop 0
	v_cndmask_b32_e32 v229, v229, v222, vcc
	v_cndmask_b32_e32 v230, 0, v224, vcc
	v_fma_f32 v127, v127, v229, v230
	s_branch .Lssd_j2
.Lssd_f2:
	v_sub_f32_e32 v229, v192, v164
	v_sub_f32_e32 v230, v192, v165
	v_sub_f32_e32 v231, v192, v166
	v_sub_f32_e32 v232, v192, v167
	v_mul_f32_e32 v229, 0x3fb8aa3b, v229
	v_mul_f32_e32 v230, 0x3fb8aa3b, v230
	v_mul_f32_e32 v231, 0x3fb8aa3b, v231
	v_mul_f32_e32 v232, 0x3fb8aa3b, v232
	v_exp_f32_e32 v229, v229
	v_exp_f32_e32 v230, v230
	v_exp_f32_e32 v231, v231
	v_exp_f32_e32 v232, v232
	s_nop 0
	v_mul_f32_e32 v124, v124, v229
	v_mul_f32_e32 v125, v125, v230
	v_mul_f32_e32 v126, v126, v231
	v_mul_f32_e32 v127, v127, v232
	v_mul_f32_e32 v124, v124, v172
	v_mul_f32_e32 v125, v125, v173
	v_mul_f32_e32 v126, v126, v174
	v_mul_f32_e32 v127, v127, v175
	s_branch .Lssd_j2
.Lssd_b2:
	v_sub_f32_e32 v229, v194, v168
	v_sub_f32_e32 v230, v194, v169
	v_sub_f32_e32 v231, v194, v170
	v_sub_f32_e32 v232, v194, v171
	v_mul_f32_e32 v229, 0x3fb8aa3b, v229
	v_mul_f32_e32 v230, 0x3fb8aa3b, v230
	v_mul_f32_e32 v231, 0x3fb8aa3b, v231
	v_mul_f32_e32 v232, 0x3fb8aa3b, v232
	v_exp_f32_e32 v229, v229
	v_exp_f32_e32 v230, v230
	v_exp_f32_e32 v231, v231
	v_exp_f32_e32 v232, v232
	s_nop 0
	v_mul_f32_e32 v124, v124, v229
	v_mul_f32_e32 v125, v125, v230
	v_mul_f32_e32 v126, v126, v231
	v_mul_f32_e32 v127, v127, v232
	v_mul_f32_e32 v124, v124, v176
	v_mul_f32_e32 v125, v125, v177
	v_mul_f32_e32 v126, v126, v178
	v_mul_f32_e32 v127, v127, v179
.Lssd_j2:
	v_cvt_pk_bf16_f32 v38, v124, v125
	v_cvt_pk_bf16_f32 v39, v126, v127
	s_cmp_ge_u32 s39, 1
	s_cbranch_scc1 .Lssd_f3
	s_cmp_lt_u32 s39, 0
	s_cbranch_scc1 .Lssd_b3
	v_cmp_lt_i32_e32 vcc, 0, v3
	s_nop 1
	v_cndmask_b32_e32 v230, v168, v164, vcc
	v_cndmask_b32_e32 v231, v176, v172, vcc
	v_cndmask_b32_e32 v229, v195, v193, vcc
	v_sub_f32_e32 v229, v229, v230
	v_mul_f32_e32 v229, 0x3fb8aa3b, v229
	v_exp_f32_e32 v229, v229
	v_cmp_eq_u32_e32 vcc, 0, v3
	v_mul_f32_e32 v229, v229, v231
	s_nop 0
	v_cndmask_b32_e32 v229, v229, v223, vcc
	v_cndmask_b32_e32 v230, 0, v224, vcc
	v_fma_f32 v128, v128, v229, v230
	v_cmp_lt_i32_e32 vcc, 1, v3
	s_nop 1
	v_cndmask_b32_e32 v230, v169, v165, vcc
	v_cndmask_b32_e32 v231, v177, v173, vcc
	v_cndmask_b32_e32 v229, v195, v193, vcc
	v_sub_f32_e32 v229, v229, v230
	v_mul_f32_e32 v229, 0x3fb8aa3b, v229
	v_exp_f32_e32 v229, v229
	v_cmp_eq_u32_e32 vcc, 1, v3
	v_mul_f32_e32 v229, v229, v231
	s_nop 0
	v_cndmask_b32_e32 v229, v229, v223, vcc
	v_cndmask_b32_e32 v230, 0, v224, vcc
	v_fma_f32 v129, v129, v229, v230
	v_cmp_lt_i32_e32 vcc, 2, v3
	s_nop 1
	v_cndmask_b32_e32 v230, v170, v166, vcc
	v_cndmask_b32_e32 v231, v178, v174, vcc
	v_cndmask_b32_e32 v229, v195, v193, vcc
	v_sub_f32_e32 v229, v229, v230
	v_mul_f32_e32 v229, 0x3fb8aa3b, v229
	v_exp_f32_e32 v229, v229
	v_cmp_eq_u32_e32 vcc, 2, v3
	v_mul_f32_e32 v229, v229, v231
	s_nop 0
	v_cndmask_b32_e32 v229, v229, v223, vcc
	v_cndmask_b32_e32 v230, 0, v224, vcc
	v_fma_f32 v130, v130, v229, v230
	v_cmp_lt_i32_e32 vcc, 3, v3
	s_nop 1
	v_cndmask_b32_e32 v230, v171, v167, vcc
	v_cndmask_b32_e32 v231, v179, v175, vcc
	v_cndmask_b32_e32 v229, v195, v193, vcc
	v_sub_f32_e32 v229, v229, v230
	v_mul_f32_e32 v229, 0x3fb8aa3b, v229
	v_exp_f32_e32 v229, v229
	v_cmp_eq_u32_e32 vcc, 3, v3
	v_mul_f32_e32 v229, v229, v231
	s_nop 0
	v_cndmask_b32_e32 v229, v229, v223, vcc
	v_cndmask_b32_e32 v230, 0, v224, vcc
	v_fma_f32 v131, v131, v229, v230
	s_branch .Lssd_j3
.Lssd_f3:
	v_sub_f32_e32 v229, v193, v164
	v_sub_f32_e32 v230, v193, v165
	v_sub_f32_e32 v231, v193, v166
	v_sub_f32_e32 v232, v193, v167
	v_mul_f32_e32 v229, 0x3fb8aa3b, v229
	v_mul_f32_e32 v230, 0x3fb8aa3b, v230
	v_mul_f32_e32 v231, 0x3fb8aa3b, v231
	v_mul_f32_e32 v232, 0x3fb8aa3b, v232
	v_exp_f32_e32 v229, v229
	v_exp_f32_e32 v230, v230
	v_exp_f32_e32 v231, v231
	v_exp_f32_e32 v232, v232
	s_nop 0
	v_mul_f32_e32 v128, v128, v229
	v_mul_f32_e32 v129, v129, v230
	v_mul_f32_e32 v130, v130, v231
	v_mul_f32_e32 v131, v131, v232
	v_mul_f32_e32 v128, v128, v172
	v_mul_f32_e32 v129, v129, v173
	v_mul_f32_e32 v130, v130, v174
	v_mul_f32_e32 v131, v131, v175
	s_branch .Lssd_j3
.Lssd_b3:
	v_sub_f32_e32 v229, v195, v168
	v_sub_f32_e32 v230, v195, v169
	v_sub_f32_e32 v231, v195, v170
	v_sub_f32_e32 v232, v195, v171
	v_mul_f32_e32 v229, 0x3fb8aa3b, v229
	v_mul_f32_e32 v230, 0x3fb8aa3b, v230
	v_mul_f32_e32 v231, 0x3fb8aa3b, v231
	v_mul_f32_e32 v232, 0x3fb8aa3b, v232
	v_exp_f32_e32 v229, v229
	v_exp_f32_e32 v230, v230
	v_exp_f32_e32 v231, v231
	v_exp_f32_e32 v232, v232
	s_nop 0
	v_mul_f32_e32 v128, v128, v229
	v_mul_f32_e32 v129, v129, v230
	v_mul_f32_e32 v130, v130, v231
	v_mul_f32_e32 v131, v131, v232
	v_mul_f32_e32 v128, v128, v176
	v_mul_f32_e32 v129, v129, v177
	v_mul_f32_e32 v130, v130, v178
	v_mul_f32_e32 v131, v131, v179
.Lssd_j3:
	v_cvt_pk_bf16_f32 v54, v128, v129
	v_cvt_pk_bf16_f32 v55, v130, v131
	ds_read_b128 v[164:167], v203 offset:128
	ds_read_b128 v[168:171], v203 offset:640
	ds_read_b128 v[172:175], v203 offset:1152
	ds_read_b128 v[176:179], v203 offset:1664
	s_waitcnt lgkmcnt(4)
	v_mfma_f32_16x16x32_bf16 v[124:127], v[148:151], v[4:7], 0
	v_mfma_f32_16x16x32_bf16 v[128:131], v[148:151], v[20:23], 0
	v_mfma_f32_16x16x32_bf16 v[124:127], v[152:155], v[8:11], v[124:127]
	v_mfma_f32_16x16x32_bf16 v[128:131], v[152:155], v[24:27], v[128:131]
	v_mfma_f32_16x16x32_bf16 v[124:127], v[156:159], v[12:15], v[124:127]
	v_mfma_f32_16x16x32_bf16 v[128:131], v[156:159], v[28:31], v[128:131]
	v_mfma_f32_16x16x32_bf16 v[124:127], v[160:163], v[16:19], v[124:127]
	v_mfma_f32_16x16x32_bf16 v[128:131], v[160:163], v[32:35], v[128:131]
	ds_read_b128 v[132:135], v199 offset:16384
	ds_read_b128 v[136:139], v200 offset:16384
	ds_read_b128 v[140:143], v201 offset:16384
	ds_read_b128 v[144:147], v202 offset:16384
	s_waitcnt lgkmcnt(4)
	s_cmp_gt_u32 s39, 2
	s_cbranch_scc1 .Lssd_f4
	s_cmp_lt_u32 s39, 2
	s_cbranch_scc1 .Lssd_b4
	v_cmp_lt_i32_e32 vcc, 0, v3
	s_nop 1
	v_cndmask_b32_e32 v230, v168, v164, vcc
	v_cndmask_b32_e32 v231, v176, v172, vcc
	v_cndmask_b32_e32 v229, v194, v192, vcc
	v_sub_f32_e32 v229, v229, v230
	v_mul_f32_e32 v229, 0x3fb8aa3b, v229
	v_exp_f32_e32 v229, v229
	v_cmp_eq_u32_e32 vcc, 0, v3
	v_mul_f32_e32 v229, v229, v231
	s_nop 0
	v_cndmask_b32_e32 v229, v229, v222, vcc
	v_cndmask_b32_e32 v230, 0, v224, vcc
	v_fma_f32 v116, v116, v229, v230
	v_cmp_lt_i32_e32 vcc, 1, v3
	s_nop 1
	v_cndmask_b32_e32 v230, v169, v165, vcc
	v_cndmask_b32_e32 v231, v177, v173, vcc
	v_cndmask_b32_e32 v229, v194, v192, vcc
	v_sub_f32_e32 v229, v229, v230
	v_mul_f32_e32 v229, 0x3fb8aa3b, v229
	v_exp_f32_e32 v229, v229
	v_cmp_eq_u32_e32 vcc, 1, v3
	v_mul_f32_e32 v229, v229, v231
	s_nop 0
	v_cndmask_b32_e32 v229, v229, v222, vcc
	v_cndmask_b32_e32 v230, 0, v224, vcc
	v_fma_f32 v117, v117, v229, v230
	v_cmp_lt_i32_e32 vcc, 2, v3
	s_nop 1
	v_cndmask_b32_e32 v230, v170, v166, vcc
	v_cndmask_b32_e32 v231, v178, v174, vcc
	v_cndmask_b32_e32 v229, v194, v192, vcc
	v_sub_f32_e32 v229, v229, v230
	v_mul_f32_e32 v229, 0x3fb8aa3b, v229
	v_exp_f32_e32 v229, v229
	v_cmp_eq_u32_e32 vcc, 2, v3
	v_mul_f32_e32 v229, v229, v231
	s_nop 0
	v_cndmask_b32_e32 v229, v229, v222, vcc
	v_cndmask_b32_e32 v230, 0, v224, vcc
	v_fma_f32 v118, v118, v229, v230
	v_cmp_lt_i32_e32 vcc, 3, v3
	s_nop 1
	v_cndmask_b32_e32 v230, v171, v167, vcc
	v_cndmask_b32_e32 v231, v179, v175, vcc
	v_cndmask_b32_e32 v229, v194, v192, vcc
	v_sub_f32_e32 v229, v229, v230
	v_mul_f32_e32 v229, 0x3fb8aa3b, v229
	v_exp_f32_e32 v229, v229
	v_cmp_eq_u32_e32 vcc, 3, v3
	v_mul_f32_e32 v229, v229, v231
	s_nop 0
	v_cndmask_b32_e32 v229, v229, v222, vcc
	v_cndmask_b32_e32 v230, 0, v224, vcc
	v_fma_f32 v119, v119, v229, v230
	s_branch .Lssd_j4

.Lssd_j4:
	v_cvt_pk_bf16_f32 v40, v116, v117
	v_cvt_pk_bf16_f32 v41, v118, v119
	s_cmp_ge_u32 s39, 2
	s_cbranch_scc1 .Lssd_f5
	s_cmp_lt_u32 s39, 1
	s_cbranch_scc1 .Lssd_b5
	v_cmp_lt_i32_e32 vcc, 0, v3
	s_nop 1
	v_cndmask_b32_e32 v230, v168, v164, vcc
	v_cndmask_b32_e32 v231, v176, v172, vcc
	v_cndmask_b32_e32 v229, v195, v193, vcc
	v_sub_f32_e32 v229, v229, v230
	v_mul_f32_e32 v229, 0x3fb8aa3b, v229
	v_exp_f32_e32 v229, v229
	v_cmp_eq_u32_e32 vcc, 0, v3
	v_mul_f32_e32 v229, v229, v231
	s_nop 0
	v_cndmask_b32_e32 v229, v229, v223, vcc
	v_cndmask_b32_e32 v230, 0, v224, vcc
	v_fma_f32 v120, v120, v229, v230
	v_cmp_lt_i32_e32 vcc, 1, v3
	s_nop 1
	v_cndmask_b32_e32 v230, v169, v165, vcc
	v_cndmask_b32_e32 v231, v177, v173, vcc
	v_cndmask_b32_e32 v229, v195, v193, vcc
	v_sub_f32_e32 v229, v229, v230
	v_mul_f32_e32 v229, 0x3fb8aa3b, v229
	v_exp_f32_e32 v229, v229
	v_cmp_eq_u32_e32 vcc, 1, v3
	v_mul_f32_e32 v229, v229, v231
	s_nop 0
	v_cndmask_b32_e32 v229, v229, v223, vcc
	v_cndmask_b32_e32 v230, 0, v224, vcc
	v_fma_f32 v121, v121, v229, v230
	v_cmp_lt_i32_e32 vcc, 2, v3
	s_nop 1
	v_cndmask_b32_e32 v230, v170, v166, vcc
	v_cndmask_b32_e32 v231, v178, v174, vcc
	v_cndmask_b32_e32 v229, v195, v193, vcc
	v_sub_f32_e32 v229, v229, v230
	v_mul_f32_e32 v229, 0x3fb8aa3b, v229
	v_exp_f32_e32 v229, v229
	v_cmp_eq_u32_e32 vcc, 2, v3
	v_mul_f32_e32 v229, v229, v231
	s_nop 0
	v_cndmask_b32_e32 v229, v229, v223, vcc
	v_cndmask_b32_e32 v230, 0, v224, vcc
	v_fma_f32 v122, v122, v229, v230
	v_cmp_lt_i32_e32 vcc, 3, v3
	s_nop 1
	v_cndmask_b32_e32 v230, v171, v167, vcc
	v_cndmask_b32_e32 v231, v179, v175, vcc
	v_cndmask_b32_e32 v229, v195, v193, vcc
	v_sub_f32_e32 v229, v229, v230
	v_mul_f32_e32 v229, 0x3fb8aa3b, v229
	v_exp_f32_e32 v229, v229
	v_cmp_eq_u32_e32 vcc, 3, v3
	v_mul_f32_e32 v229, v229, v231
	s_nop 0
	v_cndmask_b32_e32 v229, v229, v223, vcc
	v_cndmask_b32_e32 v230, 0, v224, vcc
	v_fma_f32 v123, v123, v229, v230
	s_branch .Lssd_j5

.Lssd_j5:
	v_cvt_pk_bf16_f32 v56, v120, v121
	v_cvt_pk_bf16_f32 v57, v122, v123
	ds_read_b128 v[164:167], v203 offset:192
	ds_read_b128 v[168:171], v203 offset:704
	ds_read_b128 v[172:175], v203 offset:1216
	ds_read_b128 v[176:179], v203 offset:1728
	s_waitcnt lgkmcnt(4)
	v_mfma_f32_16x16x32_bf16 v[116:119], v[132:135], v[4:7], 0
	v_mfma_f32_16x16x32_bf16 v[120:123], v[132:135], v[20:23], 0
	v_mfma_f32_16x16x32_bf16 v[116:119], v[136:139], v[8:11], v[116:119]
	v_mfma_f32_16x16x32_bf16 v[120:123], v[136:139], v[24:27], v[120:123]
	v_mfma_f32_16x16x32_bf16 v[116:119], v[140:143], v[12:15], v[116:119]
	v_mfma_f32_16x16x32_bf16 v[120:123], v[140:143], v[28:31], v[120:123]
	v_mfma_f32_16x16x32_bf16 v[116:119], v[144:147], v[16:19], v[116:119]
	v_mfma_f32_16x16x32_bf16 v[120:123], v[144:147], v[32:35], v[120:123]
	ds_read_b128 v[148:151], v199 offset:20480
	ds_read_b128 v[152:155], v200 offset:20480
	ds_read_b128 v[156:159], v201 offset:20480
	ds_read_b128 v[160:163], v202 offset:20480
	s_waitcnt lgkmcnt(4)
	s_cmp_gt_u32 s39, 3
	s_cbranch_scc1 .Lssd_f6
	s_cmp_lt_u32 s39, 3
	s_cbranch_scc1 .Lssd_b6
	v_cmp_lt_i32_e32 vcc, 0, v3
	s_nop 1
	v_cndmask_b32_e32 v230, v168, v164, vcc
	v_cndmask_b32_e32 v231, v176, v172, vcc
	v_cndmask_b32_e32 v229, v194, v192, vcc
	v_sub_f32_e32 v229, v229, v230
	v_mul_f32_e32 v229, 0x3fb8aa3b, v229
	v_exp_f32_e32 v229, v229
	v_cmp_eq_u32_e32 vcc, 0, v3
	v_mul_f32_e32 v229, v229, v231
	s_nop 0
	v_cndmask_b32_e32 v229, v229, v222, vcc
	v_cndmask_b32_e32 v230, 0, v224, vcc
	v_fma_f32 v124, v124, v229, v230
	v_cmp_lt_i32_e32 vcc, 1, v3
	s_nop 1
	v_cndmask_b32_e32 v230, v169, v165, vcc
	v_cndmask_b32_e32 v231, v177, v173, vcc
	v_cndmask_b32_e32 v229, v194, v192, vcc
	v_sub_f32_e32 v229, v229, v230
	v_mul_f32_e32 v229, 0x3fb8aa3b, v229
	v_exp_f32_e32 v229, v229
	v_cmp_eq_u32_e32 vcc, 1, v3
	v_mul_f32_e32 v229, v229, v231
	s_nop 0
	v_cndmask_b32_e32 v229, v229, v222, vcc
	v_cndmask_b32_e32 v230, 0, v224, vcc
	v_fma_f32 v125, v125, v229, v230
	v_cmp_lt_i32_e32 vcc, 2, v3
	s_nop 1
	v_cndmask_b32_e32 v230, v170, v166, vcc
	v_cndmask_b32_e32 v231, v178, v174, vcc
	v_cndmask_b32_e32 v229, v194, v192, vcc
	v_sub_f32_e32 v229, v229, v230
	v_mul_f32_e32 v229, 0x3fb8aa3b, v229
	v_exp_f32_e32 v229, v229
	v_cmp_eq_u32_e32 vcc, 2, v3
	v_mul_f32_e32 v229, v229, v231
	s_nop 0
	v_cndmask_b32_e32 v229, v229, v222, vcc
	v_cndmask_b32_e32 v230, 0, v224, vcc
	v_fma_f32 v126, v126, v229, v230
	v_cmp_lt_i32_e32 vcc, 3, v3
	s_nop 1
	v_cndmask_b32_e32 v230, v171, v167, vcc
	v_cndmask_b32_e32 v231, v179, v175, vcc
	v_cndmask_b32_e32 v229, v194, v192, vcc
	v_sub_f32_e32 v229, v229, v230
	v_mul_f32_e32 v229, 0x3fb8aa3b, v229
	v_exp_f32_e32 v229, v229
	v_cmp_eq_u32_e32 vcc, 3, v3
	v_mul_f32_e32 v229, v229, v231
	s_nop 0
	v_cndmask_b32_e32 v229, v229, v222, vcc
	v_cndmask_b32_e32 v230, 0, v224, vcc
	v_fma_f32 v127, v127, v229, v230
	s_branch .Lssd_j6

.Lssd_j6:
	v_cvt_pk_bf16_f32 v42, v124, v125
	v_cvt_pk_bf16_f32 v43, v126, v127
	s_cmp_ge_u32 s39, 3
	s_cbranch_scc1 .Lssd_f7
	s_cmp_lt_u32 s39, 2
	s_cbranch_scc1 .Lssd_b7
	v_cmp_lt_i32_e32 vcc, 0, v3
	s_nop 1
	v_cndmask_b32_e32 v230, v168, v164, vcc
	v_cndmask_b32_e32 v231, v176, v172, vcc
	v_cndmask_b32_e32 v229, v195, v193, vcc
	v_sub_f32_e32 v229, v229, v230
	v_mul_f32_e32 v229, 0x3fb8aa3b, v229
	v_exp_f32_e32 v229, v229
	v_cmp_eq_u32_e32 vcc, 0, v3
	v_mul_f32_e32 v229, v229, v231
	s_nop 0
	v_cndmask_b32_e32 v229, v229, v223, vcc
	v_cndmask_b32_e32 v230, 0, v224, vcc
	v_fma_f32 v128, v128, v229, v230
	v_cmp_lt_i32_e32 vcc, 1, v3
	s_nop 1
	v_cndmask_b32_e32 v230, v169, v165, vcc
	v_cndmask_b32_e32 v231, v177, v173, vcc
	v_cndmask_b32_e32 v229, v195, v193, vcc
	v_sub_f32_e32 v229, v229, v230
	v_mul_f32_e32 v229, 0x3fb8aa3b, v229
	v_exp_f32_e32 v229, v229
	v_cmp_eq_u32_e32 vcc, 1, v3
	v_mul_f32_e32 v229, v229, v231
	s_nop 0
	v_cndmask_b32_e32 v229, v229, v223, vcc
	v_cndmask_b32_e32 v230, 0, v224, vcc
	v_fma_f32 v129, v129, v229, v230
	v_cmp_lt_i32_e32 vcc, 2, v3
	s_nop 1
	v_cndmask_b32_e32 v230, v170, v166, vcc
	v_cndmask_b32_e32 v231, v178, v174, vcc
	v_cndmask_b32_e32 v229, v195, v193, vcc
	v_sub_f32_e32 v229, v229, v230
	v_mul_f32_e32 v229, 0x3fb8aa3b, v229
	v_exp_f32_e32 v229, v229
	v_cmp_eq_u32_e32 vcc, 2, v3
	v_mul_f32_e32 v229, v229, v231
	s_nop 0
	v_cndmask_b32_e32 v229, v229, v223, vcc
	v_cndmask_b32_e32 v230, 0, v224, vcc
	v_fma_f32 v130, v130, v229, v230
	v_cmp_lt_i32_e32 vcc, 3, v3
	s_nop 1
	v_cndmask_b32_e32 v230, v171, v167, vcc
	v_cndmask_b32_e32 v231, v179, v175, vcc
	v_cndmask_b32_e32 v229, v195, v193, vcc
	v_sub_f32_e32 v229, v229, v230
	v_mul_f32_e32 v229, 0x3fb8aa3b, v229
	v_exp_f32_e32 v229, v229
	v_cmp_eq_u32_e32 vcc, 3, v3
	v_mul_f32_e32 v229, v229, v231
	s_nop 0
	v_cndmask_b32_e32 v229, v229, v223, vcc
	v_cndmask_b32_e32 v230, 0, v224, vcc
	v_fma_f32 v131, v131, v229, v230
	s_branch .Lssd_j7

.Lssd_j7:
	v_cvt_pk_bf16_f32 v58, v128, v129
	v_cvt_pk_bf16_f32 v59, v130, v131
	ds_read_b128 v[164:167], v203 offset:256
	ds_read_b128 v[168:171], v203 offset:768
	ds_read_b128 v[172:175], v203 offset:1280
	ds_read_b128 v[176:179], v203 offset:1792
	s_waitcnt lgkmcnt(4)
	v_mfma_f32_16x16x32_bf16 v[124:127], v[148:151], v[4:7], 0
	v_mfma_f32_16x16x32_bf16 v[128:131], v[148:151], v[20:23], 0
	v_mfma_f32_16x16x32_bf16 v[124:127], v[152:155], v[8:11], v[124:127]
	v_mfma_f32_16x16x32_bf16 v[128:131], v[152:155], v[24:27], v[128:131]
	v_mfma_f32_16x16x32_bf16 v[124:127], v[156:159], v[12:15], v[124:127]
	v_mfma_f32_16x16x32_bf16 v[128:131], v[156:159], v[28:31], v[128:131]
	v_mfma_f32_16x16x32_bf16 v[124:127], v[160:163], v[16:19], v[124:127]
	v_mfma_f32_16x16x32_bf16 v[128:131], v[160:163], v[32:35], v[128:131]
	ds_read_b128 v[132:135], v199 offset:24576
	ds_read_b128 v[136:139], v200 offset:24576
	ds_read_b128 v[140:143], v201 offset:24576
	ds_read_b128 v[144:147], v202 offset:24576
	s_waitcnt lgkmcnt(4)
	s_cmp_gt_u32 s39, 4
	s_cbranch_scc1 .Lssd_f8
	s_cmp_lt_u32 s39, 4
	s_cbranch_scc1 .Lssd_b8
	v_cmp_lt_i32_e32 vcc, 0, v3
	s_nop 1
	v_cndmask_b32_e32 v230, v168, v164, vcc
	v_cndmask_b32_e32 v231, v176, v172, vcc
	v_cndmask_b32_e32 v229, v194, v192, vcc
	v_sub_f32_e32 v229, v229, v230
	v_mul_f32_e32 v229, 0x3fb8aa3b, v229
	v_exp_f32_e32 v229, v229
	v_cmp_eq_u32_e32 vcc, 0, v3
	v_mul_f32_e32 v229, v229, v231
	s_nop 0
	v_cndmask_b32_e32 v229, v229, v222, vcc
	v_cndmask_b32_e32 v230, 0, v224, vcc
	v_fma_f32 v116, v116, v229, v230
	v_cmp_lt_i32_e32 vcc, 1, v3
	s_nop 1
	v_cndmask_b32_e32 v230, v169, v165, vcc
	v_cndmask_b32_e32 v231, v177, v173, vcc
	v_cndmask_b32_e32 v229, v194, v192, vcc
	v_sub_f32_e32 v229, v229, v230
	v_mul_f32_e32 v229, 0x3fb8aa3b, v229
	v_exp_f32_e32 v229, v229
	v_cmp_eq_u32_e32 vcc, 1, v3
	v_mul_f32_e32 v229, v229, v231
	s_nop 0
	v_cndmask_b32_e32 v229, v229, v222, vcc
	v_cndmask_b32_e32 v230, 0, v224, vcc
	v_fma_f32 v117, v117, v229, v230
	v_cmp_lt_i32_e32 vcc, 2, v3
	s_nop 1
	v_cndmask_b32_e32 v230, v170, v166, vcc
	v_cndmask_b32_e32 v231, v178, v174, vcc
	v_cndmask_b32_e32 v229, v194, v192, vcc
	v_sub_f32_e32 v229, v229, v230
	v_mul_f32_e32 v229, 0x3fb8aa3b, v229
	v_exp_f32_e32 v229, v229
	v_cmp_eq_u32_e32 vcc, 2, v3
	v_mul_f32_e32 v229, v229, v231
	s_nop 0
	v_cndmask_b32_e32 v229, v229, v222, vcc
	v_cndmask_b32_e32 v230, 0, v224, vcc
	v_fma_f32 v118, v118, v229, v230
	v_cmp_lt_i32_e32 vcc, 3, v3
	s_nop 1
	v_cndmask_b32_e32 v230, v171, v167, vcc
	v_cndmask_b32_e32 v231, v179, v175, vcc
	v_cndmask_b32_e32 v229, v194, v192, vcc
	v_sub_f32_e32 v229, v229, v230
	v_mul_f32_e32 v229, 0x3fb8aa3b, v229
	v_exp_f32_e32 v229, v229
	v_cmp_eq_u32_e32 vcc, 3, v3
	v_mul_f32_e32 v229, v229, v231
	s_nop 0
	v_cndmask_b32_e32 v229, v229, v222, vcc
	v_cndmask_b32_e32 v230, 0, v224, vcc
	v_fma_f32 v119, v119, v229, v230
	s_branch .Lssd_j8

.Lssd_j8:
	v_cvt_pk_bf16_f32 v44, v116, v117
	v_cvt_pk_bf16_f32 v45, v118, v119
	s_cmp_ge_u32 s39, 4
	s_cbranch_scc1 .Lssd_f9
	s_cmp_lt_u32 s39, 3
	s_cbranch_scc1 .Lssd_b9
	v_cmp_lt_i32_e32 vcc, 0, v3
	s_nop 1
	v_cndmask_b32_e32 v230, v168, v164, vcc
	v_cndmask_b32_e32 v231, v176, v172, vcc
	v_cndmask_b32_e32 v229, v195, v193, vcc
	v_sub_f32_e32 v229, v229, v230
	v_mul_f32_e32 v229, 0x3fb8aa3b, v229
	v_exp_f32_e32 v229, v229
	v_cmp_eq_u32_e32 vcc, 0, v3
	v_mul_f32_e32 v229, v229, v231
	s_nop 0
	v_cndmask_b32_e32 v229, v229, v223, vcc
	v_cndmask_b32_e32 v230, 0, v224, vcc
	v_fma_f32 v120, v120, v229, v230
	v_cmp_lt_i32_e32 vcc, 1, v3
	s_nop 1
	v_cndmask_b32_e32 v230, v169, v165, vcc
	v_cndmask_b32_e32 v231, v177, v173, vcc
	v_cndmask_b32_e32 v229, v195, v193, vcc
	v_sub_f32_e32 v229, v229, v230
	v_mul_f32_e32 v229, 0x3fb8aa3b, v229
	v_exp_f32_e32 v229, v229
	v_cmp_eq_u32_e32 vcc, 1, v3
	v_mul_f32_e32 v229, v229, v231
	s_nop 0
	v_cndmask_b32_e32 v229, v229, v223, vcc
	v_cndmask_b32_e32 v230, 0, v224, vcc
	v_fma_f32 v121, v121, v229, v230
	v_cmp_lt_i32_e32 vcc, 2, v3
	s_nop 1
	v_cndmask_b32_e32 v230, v170, v166, vcc
	v_cndmask_b32_e32 v231, v178, v174, vcc
	v_cndmask_b32_e32 v229, v195, v193, vcc
	v_sub_f32_e32 v229, v229, v230
	v_mul_f32_e32 v229, 0x3fb8aa3b, v229
	v_exp_f32_e32 v229, v229
	v_cmp_eq_u32_e32 vcc, 2, v3
	v_mul_f32_e32 v229, v229, v231
	s_nop 0
	v_cndmask_b32_e32 v229, v229, v223, vcc
	v_cndmask_b32_e32 v230, 0, v224, vcc
	v_fma_f32 v122, v122, v229, v230
	v_cmp_lt_i32_e32 vcc, 3, v3
	s_nop 1
	v_cndmask_b32_e32 v230, v171, v167, vcc
	v_cndmask_b32_e32 v231, v179, v175, vcc
	v_cndmask_b32_e32 v229, v195, v193, vcc
	v_sub_f32_e32 v229, v229, v230
	v_mul_f32_e32 v229, 0x3fb8aa3b, v229
	v_exp_f32_e32 v229, v229
	v_cmp_eq_u32_e32 vcc, 3, v3
	v_mul_f32_e32 v229, v229, v231
	s_nop 0
	v_cndmask_b32_e32 v229, v229, v223, vcc
	v_cndmask_b32_e32 v230, 0, v224, vcc
	v_fma_f32 v123, v123, v229, v230
	s_branch .Lssd_j9

.Lssd_j9:
	v_cvt_pk_bf16_f32 v60, v120, v121
	v_cvt_pk_bf16_f32 v61, v122, v123
	ds_read_b128 v[164:167], v203 offset:320
	ds_read_b128 v[168:171], v203 offset:832
	ds_read_b128 v[172:175], v203 offset:1344
	ds_read_b128 v[176:179], v203 offset:1856
	s_waitcnt lgkmcnt(4)
	v_mfma_f32_16x16x32_bf16 v[116:119], v[132:135], v[4:7], 0
	v_mfma_f32_16x16x32_bf16 v[120:123], v[132:135], v[20:23], 0
	v_mfma_f32_16x16x32_bf16 v[116:119], v[136:139], v[8:11], v[116:119]
	v_mfma_f32_16x16x32_bf16 v[120:123], v[136:139], v[24:27], v[120:123]
	v_mfma_f32_16x16x32_bf16 v[116:119], v[140:143], v[12:15], v[116:119]
	v_mfma_f32_16x16x32_bf16 v[120:123], v[140:143], v[28:31], v[120:123]
	v_mfma_f32_16x16x32_bf16 v[116:119], v[144:147], v[16:19], v[116:119]
	v_mfma_f32_16x16x32_bf16 v[120:123], v[144:147], v[32:35], v[120:123]
	ds_read_b128 v[148:151], v199 offset:28672
	ds_read_b128 v[152:155], v200 offset:28672
	ds_read_b128 v[156:159], v201 offset:28672
	ds_read_b128 v[160:163], v202 offset:28672
	s_waitcnt lgkmcnt(4)
	s_cmp_gt_u32 s39, 5
	s_cbranch_scc1 .Lssd_f10
	s_cmp_lt_u32 s39, 5
	s_cbranch_scc1 .Lssd_b10
	v_cmp_lt_i32_e32 vcc, 0, v3
	s_nop 1
	v_cndmask_b32_e32 v230, v168, v164, vcc
	v_cndmask_b32_e32 v231, v176, v172, vcc
	v_cndmask_b32_e32 v229, v194, v192, vcc
	v_sub_f32_e32 v229, v229, v230
	v_mul_f32_e32 v229, 0x3fb8aa3b, v229
	v_exp_f32_e32 v229, v229
	v_cmp_eq_u32_e32 vcc, 0, v3
	v_mul_f32_e32 v229, v229, v231
	s_nop 0
	v_cndmask_b32_e32 v229, v229, v222, vcc
	v_cndmask_b32_e32 v230, 0, v224, vcc
	v_fma_f32 v124, v124, v229, v230
	v_cmp_lt_i32_e32 vcc, 1, v3
	s_nop 1
	v_cndmask_b32_e32 v230, v169, v165, vcc
	v_cndmask_b32_e32 v231, v177, v173, vcc
	v_cndmask_b32_e32 v229, v194, v192, vcc
	v_sub_f32_e32 v229, v229, v230
	v_mul_f32_e32 v229, 0x3fb8aa3b, v229
	v_exp_f32_e32 v229, v229
	v_cmp_eq_u32_e32 vcc, 1, v3
	v_mul_f32_e32 v229, v229, v231
	s_nop 0
	v_cndmask_b32_e32 v229, v229, v222, vcc
	v_cndmask_b32_e32 v230, 0, v224, vcc
	v_fma_f32 v125, v125, v229, v230
	v_cmp_lt_i32_e32 vcc, 2, v3
	s_nop 1
	v_cndmask_b32_e32 v230, v170, v166, vcc
	v_cndmask_b32_e32 v231, v178, v174, vcc
	v_cndmask_b32_e32 v229, v194, v192, vcc
	v_sub_f32_e32 v229, v229, v230
	v_mul_f32_e32 v229, 0x3fb8aa3b, v229
	v_exp_f32_e32 v229, v229
	v_cmp_eq_u32_e32 vcc, 2, v3
	v_mul_f32_e32 v229, v229, v231
	s_nop 0
	v_cndmask_b32_e32 v229, v229, v222, vcc
	v_cndmask_b32_e32 v230, 0, v224, vcc
	v_fma_f32 v126, v126, v229, v230
	v_cmp_lt_i32_e32 vcc, 3, v3
	s_nop 1
	v_cndmask_b32_e32 v230, v171, v167, vcc
	v_cndmask_b32_e32 v231, v179, v175, vcc
	v_cndmask_b32_e32 v229, v194, v192, vcc
	v_sub_f32_e32 v229, v229, v230
	v_mul_f32_e32 v229, 0x3fb8aa3b, v229
	v_exp_f32_e32 v229, v229
	v_cmp_eq_u32_e32 vcc, 3, v3
	v_mul_f32_e32 v229, v229, v231
	s_nop 0
	v_cndmask_b32_e32 v229, v229, v222, vcc
	v_cndmask_b32_e32 v230, 0, v224, vcc
	v_fma_f32 v127, v127, v229, v230
	s_branch .Lssd_j10

.Lssd_j10:
	v_cvt_pk_bf16_f32 v46, v124, v125
	v_cvt_pk_bf16_f32 v47, v126, v127
	s_cmp_ge_u32 s39, 5
	s_cbranch_scc1 .Lssd_f11
	s_cmp_lt_u32 s39, 4
	s_cbranch_scc1 .Lssd_b11
	v_cmp_lt_i32_e32 vcc, 0, v3
	s_nop 1
	v_cndmask_b32_e32 v230, v168, v164, vcc
	v_cndmask_b32_e32 v231, v176, v172, vcc
	v_cndmask_b32_e32 v229, v195, v193, vcc
	v_sub_f32_e32 v229, v229, v230
	v_mul_f32_e32 v229, 0x3fb8aa3b, v229
	v_exp_f32_e32 v229, v229
	v_cmp_eq_u32_e32 vcc, 0, v3
	v_mul_f32_e32 v229, v229, v231
	s_nop 0
	v_cndmask_b32_e32 v229, v229, v223, vcc
	v_cndmask_b32_e32 v230, 0, v224, vcc
	v_fma_f32 v128, v128, v229, v230
	v_cmp_lt_i32_e32 vcc, 1, v3
	s_nop 1
	v_cndmask_b32_e32 v230, v169, v165, vcc
	v_cndmask_b32_e32 v231, v177, v173, vcc
	v_cndmask_b32_e32 v229, v195, v193, vcc
	v_sub_f32_e32 v229, v229, v230
	v_mul_f32_e32 v229, 0x3fb8aa3b, v229
	v_exp_f32_e32 v229, v229
	v_cmp_eq_u32_e32 vcc, 1, v3
	v_mul_f32_e32 v229, v229, v231
	s_nop 0
	v_cndmask_b32_e32 v229, v229, v223, vcc
	v_cndmask_b32_e32 v230, 0, v224, vcc
	v_fma_f32 v129, v129, v229, v230
	v_cmp_lt_i32_e32 vcc, 2, v3
	s_nop 1
	v_cndmask_b32_e32 v230, v170, v166, vcc
	v_cndmask_b32_e32 v231, v178, v174, vcc
	v_cndmask_b32_e32 v229, v195, v193, vcc
	v_sub_f32_e32 v229, v229, v230
	v_mul_f32_e32 v229, 0x3fb8aa3b, v229
	v_exp_f32_e32 v229, v229
	v_cmp_eq_u32_e32 vcc, 2, v3
	v_mul_f32_e32 v229, v229, v231
	s_nop 0
	v_cndmask_b32_e32 v229, v229, v223, vcc
	v_cndmask_b32_e32 v230, 0, v224, vcc
	v_fma_f32 v130, v130, v229, v230
	v_cmp_lt_i32_e32 vcc, 3, v3
	s_nop 1
	v_cndmask_b32_e32 v230, v171, v167, vcc
	v_cndmask_b32_e32 v231, v179, v175, vcc
	v_cndmask_b32_e32 v229, v195, v193, vcc
	v_sub_f32_e32 v229, v229, v230
	v_mul_f32_e32 v229, 0x3fb8aa3b, v229
	v_exp_f32_e32 v229, v229
	v_cmp_eq_u32_e32 vcc, 3, v3
	v_mul_f32_e32 v229, v229, v231
	s_nop 0
	v_cndmask_b32_e32 v229, v229, v223, vcc
	v_cndmask_b32_e32 v230, 0, v224, vcc
	v_fma_f32 v131, v131, v229, v230
	s_branch .Lssd_j11

.Lssd_j11:
	v_cvt_pk_bf16_f32 v62, v128, v129
	v_cvt_pk_bf16_f32 v63, v130, v131
	ds_read_b128 v[164:167], v203 offset:384
	ds_read_b128 v[168:171], v203 offset:896
	ds_read_b128 v[172:175], v203 offset:1408
	ds_read_b128 v[176:179], v203 offset:1920
	s_waitcnt lgkmcnt(4)
	v_mfma_f32_16x16x32_bf16 v[124:127], v[148:151], v[4:7], 0
	v_mfma_f32_16x16x32_bf16 v[128:131], v[148:151], v[20:23], 0
	v_mfma_f32_16x16x32_bf16 v[124:127], v[152:155], v[8:11], v[124:127]
	v_mfma_f32_16x16x32_bf16 v[128:131], v[152:155], v[24:27], v[128:131]
	v_mfma_f32_16x16x32_bf16 v[124:127], v[156:159], v[12:15], v[124:127]
	v_mfma_f32_16x16x32_bf16 v[128:131], v[156:159], v[28:31], v[128:131]
	v_mfma_f32_16x16x32_bf16 v[124:127], v[160:163], v[16:19], v[124:127]
	v_mfma_f32_16x16x32_bf16 v[128:131], v[160:163], v[32:35], v[128:131]
	s_waitcnt lgkmcnt(0)
	s_cmp_gt_u32 s39, 6
	s_cbranch_scc1 .Lssd_f12
	s_cmp_lt_u32 s39, 6
	s_cbranch_scc1 .Lssd_b12
	v_cmp_lt_i32_e32 vcc, 0, v3
	s_nop 1
	v_cndmask_b32_e32 v230, v168, v164, vcc
	v_cndmask_b32_e32 v231, v176, v172, vcc
	v_cndmask_b32_e32 v229, v194, v192, vcc
	v_sub_f32_e32 v229, v229, v230
	v_mul_f32_e32 v229, 0x3fb8aa3b, v229
	v_exp_f32_e32 v229, v229
	v_cmp_eq_u32_e32 vcc, 0, v3
	v_mul_f32_e32 v229, v229, v231
	s_nop 0
	v_cndmask_b32_e32 v229, v229, v222, vcc
	v_cndmask_b32_e32 v230, 0, v224, vcc
	v_fma_f32 v116, v116, v229, v230
	v_cmp_lt_i32_e32 vcc, 1, v3
	s_nop 1
	v_cndmask_b32_e32 v230, v169, v165, vcc
	v_cndmask_b32_e32 v231, v177, v173, vcc
	v_cndmask_b32_e32 v229, v194, v192, vcc
	v_sub_f32_e32 v229, v229, v230
	v_mul_f32_e32 v229, 0x3fb8aa3b, v229
	v_exp_f32_e32 v229, v229
	v_cmp_eq_u32_e32 vcc, 1, v3
	v_mul_f32_e32 v229, v229, v231
	s_nop 0
	v_cndmask_b32_e32 v229, v229, v222, vcc
	v_cndmask_b32_e32 v230, 0, v224, vcc
	v_fma_f32 v117, v117, v229, v230
	v_cmp_lt_i32_e32 vcc, 2, v3
	s_nop 1
	v_cndmask_b32_e32 v230, v170, v166, vcc
	v_cndmask_b32_e32 v231, v178, v174, vcc
	v_cndmask_b32_e32 v229, v194, v192, vcc
	v_sub_f32_e32 v229, v229, v230
	v_mul_f32_e32 v229, 0x3fb8aa3b, v229
	v_exp_f32_e32 v229, v229
	v_cmp_eq_u32_e32 vcc, 2, v3
	v_mul_f32_e32 v229, v229, v231
	s_nop 0
	v_cndmask_b32_e32 v229, v229, v222, vcc
	v_cndmask_b32_e32 v230, 0, v224, vcc
	v_fma_f32 v118, v118, v229, v230
	v_cmp_lt_i32_e32 vcc, 3, v3
	s_nop 1
	v_cndmask_b32_e32 v230, v171, v167, vcc
	v_cndmask_b32_e32 v231, v179, v175, vcc
	v_cndmask_b32_e32 v229, v194, v192, vcc
	v_sub_f32_e32 v229, v229, v230
	v_mul_f32_e32 v229, 0x3fb8aa3b, v229
	v_exp_f32_e32 v229, v229
	v_cmp_eq_u32_e32 vcc, 3, v3
	v_mul_f32_e32 v229, v229, v231
	s_nop 0
	v_cndmask_b32_e32 v229, v229, v222, vcc
	v_cndmask_b32_e32 v230, 0, v224, vcc
	v_fma_f32 v119, v119, v229, v230
	s_branch .Lssd_j12

.Lssd_j12:
	v_cvt_pk_bf16_f32 v48, v116, v117
	v_cvt_pk_bf16_f32 v49, v118, v119
	s_cmp_ge_u32 s39, 6
	s_cbranch_scc1 .Lssd_f13
	s_cmp_lt_u32 s39, 5
	s_cbranch_scc1 .Lssd_b13
	v_cmp_lt_i32_e32 vcc, 0, v3
	s_nop 1
	v_cndmask_b32_e32 v230, v168, v164, vcc
	v_cndmask_b32_e32 v231, v176, v172, vcc
	v_cndmask_b32_e32 v229, v195, v193, vcc
	v_sub_f32_e32 v229, v229, v230
	v_mul_f32_e32 v229, 0x3fb8aa3b, v229
	v_exp_f32_e32 v229, v229
	v_cmp_eq_u32_e32 vcc, 0, v3
	v_mul_f32_e32 v229, v229, v231
	s_nop 0
	v_cndmask_b32_e32 v229, v229, v223, vcc
	v_cndmask_b32_e32 v230, 0, v224, vcc
	v_fma_f32 v120, v120, v229, v230
	v_cmp_lt_i32_e32 vcc, 1, v3
	s_nop 1
	v_cndmask_b32_e32 v230, v169, v165, vcc
	v_cndmask_b32_e32 v231, v177, v173, vcc
	v_cndmask_b32_e32 v229, v195, v193, vcc
	v_sub_f32_e32 v229, v229, v230
	v_mul_f32_e32 v229, 0x3fb8aa3b, v229
	v_exp_f32_e32 v229, v229
	v_cmp_eq_u32_e32 vcc, 1, v3
	v_mul_f32_e32 v229, v229, v231
	s_nop 0
	v_cndmask_b32_e32 v229, v229, v223, vcc
	v_cndmask_b32_e32 v230, 0, v224, vcc
	v_fma_f32 v121, v121, v229, v230
	v_cmp_lt_i32_e32 vcc, 2, v3
	s_nop 1
	v_cndmask_b32_e32 v230, v170, v166, vcc
	v_cndmask_b32_e32 v231, v178, v174, vcc
	v_cndmask_b32_e32 v229, v195, v193, vcc
	v_sub_f32_e32 v229, v229, v230
	v_mul_f32_e32 v229, 0x3fb8aa3b, v229
	v_exp_f32_e32 v229, v229
	v_cmp_eq_u32_e32 vcc, 2, v3
	v_mul_f32_e32 v229, v229, v231
	s_nop 0
	v_cndmask_b32_e32 v229, v229, v223, vcc
	v_cndmask_b32_e32 v230, 0, v224, vcc
	v_fma_f32 v122, v122, v229, v230
	v_cmp_lt_i32_e32 vcc, 3, v3
	s_nop 1
	v_cndmask_b32_e32 v230, v171, v167, vcc
	v_cndmask_b32_e32 v231, v179, v175, vcc
	v_cndmask_b32_e32 v229, v195, v193, vcc
	v_sub_f32_e32 v229, v229, v230
	v_mul_f32_e32 v229, 0x3fb8aa3b, v229
	v_exp_f32_e32 v229, v229
	v_cmp_eq_u32_e32 vcc, 3, v3
	v_mul_f32_e32 v229, v229, v231
	s_nop 0
	v_cndmask_b32_e32 v229, v229, v223, vcc
	v_cndmask_b32_e32 v230, 0, v224, vcc
	v_fma_f32 v123, v123, v229, v230
	s_branch .Lssd_j13

.Lssd_j13:
	v_cvt_pk_bf16_f32 v64, v120, v121
	v_cvt_pk_bf16_f32 v65, v122, v123
	ds_read_b128 v[164:167], v203 offset:448
	ds_read_b128 v[168:171], v203 offset:960
	ds_read_b128 v[172:175], v203 offset:1472
	ds_read_b128 v[176:179], v203 offset:1984
	s_waitcnt lgkmcnt(0)
	s_nop 7
	s_cmp_gt_u32 s39, 7
	s_cbranch_scc1 .Lssd_f14
	s_cmp_lt_u32 s39, 7
	s_cbranch_scc1 .Lssd_b14
	v_cmp_lt_i32_e32 vcc, 0, v3
	s_nop 1
	v_cndmask_b32_e32 v230, v168, v164, vcc
	v_cndmask_b32_e32 v231, v176, v172, vcc
	v_cndmask_b32_e32 v229, v194, v192, vcc
	v_sub_f32_e32 v229, v229, v230
	v_mul_f32_e32 v229, 0x3fb8aa3b, v229
	v_exp_f32_e32 v229, v229
	v_cmp_eq_u32_e32 vcc, 0, v3
	v_mul_f32_e32 v229, v229, v231
	s_nop 0
	v_cndmask_b32_e32 v229, v229, v222, vcc
	v_cndmask_b32_e32 v230, 0, v224, vcc
	v_fma_f32 v124, v124, v229, v230
	v_cmp_lt_i32_e32 vcc, 1, v3
	s_nop 1
	v_cndmask_b32_e32 v230, v169, v165, vcc
	v_cndmask_b32_e32 v231, v177, v173, vcc
	v_cndmask_b32_e32 v229, v194, v192, vcc
	v_sub_f32_e32 v229, v229, v230
	v_mul_f32_e32 v229, 0x3fb8aa3b, v229
	v_exp_f32_e32 v229, v229
	v_cmp_eq_u32_e32 vcc, 1, v3
	v_mul_f32_e32 v229, v229, v231
	s_nop 0
	v_cndmask_b32_e32 v229, v229, v222, vcc
	v_cndmask_b32_e32 v230, 0, v224, vcc
	v_fma_f32 v125, v125, v229, v230
	v_cmp_lt_i32_e32 vcc, 2, v3
	s_nop 1
	v_cndmask_b32_e32 v230, v170, v166, vcc
	v_cndmask_b32_e32 v231, v178, v174, vcc
	v_cndmask_b32_e32 v229, v194, v192, vcc
	v_sub_f32_e32 v229, v229, v230
	v_mul_f32_e32 v229, 0x3fb8aa3b, v229
	v_exp_f32_e32 v229, v229
	v_cmp_eq_u32_e32 vcc, 2, v3
	v_mul_f32_e32 v229, v229, v231
	s_nop 0
	v_cndmask_b32_e32 v229, v229, v222, vcc
	v_cndmask_b32_e32 v230, 0, v224, vcc
	v_fma_f32 v126, v126, v229, v230
	v_cmp_lt_i32_e32 vcc, 3, v3
	s_nop 1
	v_cndmask_b32_e32 v230, v171, v167, vcc
	v_cndmask_b32_e32 v231, v179, v175, vcc
	v_cndmask_b32_e32 v229, v194, v192, vcc
	v_sub_f32_e32 v229, v229, v230
	v_mul_f32_e32 v229, 0x3fb8aa3b, v229
	v_exp_f32_e32 v229, v229
	v_cmp_eq_u32_e32 vcc, 3, v3
	v_mul_f32_e32 v229, v229, v231
	s_nop 0
	v_cndmask_b32_e32 v229, v229, v222, vcc
	v_cndmask_b32_e32 v230, 0, v224, vcc
	v_fma_f32 v127, v127, v229, v230
	s_branch .Lssd_j14

.Lssd_j14:
	v_cvt_pk_bf16_f32 v50, v124, v125
	v_cvt_pk_bf16_f32 v51, v126, v127
	s_cmp_ge_u32 s39, 7
	s_cbranch_scc1 .Lssd_f15
	s_cmp_lt_u32 s39, 6
	s_cbranch_scc1 .Lssd_b15
	v_cmp_lt_i32_e32 vcc, 0, v3
	s_nop 1
	v_cndmask_b32_e32 v230, v168, v164, vcc
	v_cndmask_b32_e32 v231, v176, v172, vcc
	v_cndmask_b32_e32 v229, v195, v193, vcc
	v_sub_f32_e32 v229, v229, v230
	v_mul_f32_e32 v229, 0x3fb8aa3b, v229
	v_exp_f32_e32 v229, v229
	v_cmp_eq_u32_e32 vcc, 0, v3
	v_mul_f32_e32 v229, v229, v231
	s_nop 0
	v_cndmask_b32_e32 v229, v229, v223, vcc
	v_cndmask_b32_e32 v230, 0, v224, vcc
	v_fma_f32 v128, v128, v229, v230
	v_cmp_lt_i32_e32 vcc, 1, v3
	s_nop 1
	v_cndmask_b32_e32 v230, v169, v165, vcc
	v_cndmask_b32_e32 v231, v177, v173, vcc
	v_cndmask_b32_e32 v229, v195, v193, vcc
	v_sub_f32_e32 v229, v229, v230
	v_mul_f32_e32 v229, 0x3fb8aa3b, v229
	v_exp_f32_e32 v229, v229
	v_cmp_eq_u32_e32 vcc, 1, v3
	v_mul_f32_e32 v229, v229, v231
	s_nop 0
	v_cndmask_b32_e32 v229, v229, v223, vcc
	v_cndmask_b32_e32 v230, 0, v224, vcc
	v_fma_f32 v129, v129, v229, v230
	v_cmp_lt_i32_e32 vcc, 2, v3
	s_nop 1
	v_cndmask_b32_e32 v230, v170, v166, vcc
	v_cndmask_b32_e32 v231, v178, v174, vcc
	v_cndmask_b32_e32 v229, v195, v193, vcc
	v_sub_f32_e32 v229, v229, v230
	v_mul_f32_e32 v229, 0x3fb8aa3b, v229
	v_exp_f32_e32 v229, v229
	v_cmp_eq_u32_e32 vcc, 2, v3
	v_mul_f32_e32 v229, v229, v231
	s_nop 0
	v_cndmask_b32_e32 v229, v229, v223, vcc
	v_cndmask_b32_e32 v230, 0, v224, vcc
	v_fma_f32 v130, v130, v229, v230
	v_cmp_lt_i32_e32 vcc, 3, v3
	s_nop 1
	v_cndmask_b32_e32 v230, v171, v167, vcc
	v_cndmask_b32_e32 v231, v179, v175, vcc
	v_cndmask_b32_e32 v229, v195, v193, vcc
	v_sub_f32_e32 v229, v229, v230
	v_mul_f32_e32 v229, 0x3fb8aa3b, v229
	v_exp_f32_e32 v229, v229
	v_cmp_eq_u32_e32 vcc, 3, v3
	v_mul_f32_e32 v229, v229, v231
	s_nop 0
	v_cndmask_b32_e32 v229, v229, v223, vcc
	v_cndmask_b32_e32 v230, 0, v224, vcc
	v_fma_f32 v131, v131, v229, v230
	s_branch .Lssd_j15

.Lssd_j15:
	v_cvt_pk_bf16_f32 v66, v128, v129
	v_cvt_pk_bf16_f32 v67, v130, v131
	s_barrier
	s_lshl_b32 s100, s35, 2
	v_add_u32_e32 v232, s100, v203
	s_nop 0
	ds_read_b128 v[140:143], v232 offset:0
	ds_read_b128 v[148:151], v232 offset:512
	ds_read_b128 v[144:147], v232 offset:64
	ds_read_b128 v[152:155], v232 offset:576
	v_mov_b32_e32 v156, 0
	v_mov_b32_e32 v157, 0
	v_mov_b32_e32 v158, 0
	v_mov_b32_e32 v159, 0
	v_mov_b32_e32 v160, 0
	v_mov_b32_e32 v161, 0
	v_mov_b32_e32 v162, 0
	v_mov_b32_e32 v163, 0
	s_waitcnt lgkmcnt(0)
	v_mul_f32_e32 v140, 0x3fb8aa3b, v140
	v_mul_f32_e32 v141, 0x3fb8aa3b, v141
	v_mul_f32_e32 v142, 0x3fb8aa3b, v142
	v_mul_f32_e32 v143, 0x3fb8aa3b, v143
	v_mul_f32_e32 v144, 0x3fb8aa3b, v144
	v_mul_f32_e32 v145, 0x3fb8aa3b, v145
	v_mul_f32_e32 v146, 0x3fb8aa3b, v146
	v_mul_f32_e32 v147, 0x3fb8aa3b, v147
	v_exp_f32_e32 v140, v140
	v_exp_f32_e32 v141, v141
	v_exp_f32_e32 v142, v142
	v_exp_f32_e32 v143, v143
	v_exp_f32_e32 v144, v144
	v_exp_f32_e32 v145, v145
	v_exp_f32_e32 v146, v146
	v_exp_f32_e32 v147, v147
	v_mul_f32_e32 v148, 0x3fb8aa3b, v148
	v_mul_f32_e32 v149, 0x3fb8aa3b, v149
	v_mul_f32_e32 v150, 0x3fb8aa3b, v150
	v_mul_f32_e32 v151, 0x3fb8aa3b, v151
	v_mul_f32_e32 v152, 0x3fb8aa3b, v152
	v_mul_f32_e32 v153, 0x3fb8aa3b, v153
	v_mul_f32_e32 v154, 0x3fb8aa3b, v154
	v_mul_f32_e32 v155, 0x3fb8aa3b, v155
	v_exp_f32_e32 v148, v148
	v_exp_f32_e32 v149, v149
	v_exp_f32_e32 v150, v150
	v_exp_f32_e32 v151, v151
	v_exp_f32_e32 v152, v152
	v_exp_f32_e32 v153, v153
	v_exp_f32_e32 v154, v154
	v_exp_f32_e32 v155, v155
	s_waitcnt vmcnt(16)
	v_mfma_f32_16x16x32_bf16 v[116:119], v[36:39], v[68:71], 0
	v_mfma_f32_16x16x32_bf16 v[120:123], v[52:55], v[68:71], 0
	v_mfma_f32_16x16x32_bf16 v[116:119], v[40:43], v[72:75], v[116:119]
	v_mfma_f32_16x16x32_bf16 v[120:123], v[56:59], v[72:75], v[120:123]
	v_mfma_f32_16x16x32_bf16 v[116:119], v[44:47], v[76:79], v[116:119]
	v_mfma_f32_16x16x32_bf16 v[120:123], v[60:63], v[76:79], v[120:123]
	v_mfma_f32_16x16x32_bf16 v[116:119], v[48:51], v[80:83], v[116:119]
	v_mfma_f32_16x16x32_bf16 v[120:123], v[64:67], v[80:83], v[120:123]
	global_load_dwordx2 v[68:69], v204, s[50:51]
	global_load_dwordx2 v[70:71], v204, s[50:51] offset:32
	global_load_dwordx2 v[72:73], v204, s[50:51] offset:64
	global_load_dwordx2 v[74:75], v204, s[50:51] offset:96
	global_load_dwordx2 v[76:77], v204, s[50:51] offset:128
	global_load_dwordx2 v[78:79], v204, s[50:51] offset:160
	global_load_dwordx2 v[80:81], v204, s[50:51] offset:192
	global_load_dwordx2 v[82:83], v204, s[50:51] offset:224
	s_add_u32 s50, s50, 0x1000
	s_addc_u32 s51, s51, 0
	s_waitcnt vmcnt(16)
	v_mfma_f32_16x16x32_bf16 v[124:127], v[4:7], v[84:87], 0
	v_mfma_f32_16x16x32_bf16 v[132:135], v[4:7], v[100:103], 0
	v_mfma_f32_16x16x32_bf16 v[128:131], v[20:23], v[84:87], 0
	v_mfma_f32_16x16x32_bf16 v[136:139], v[20:23], v[100:103], 0
	v_mfma_f32_16x16x32_bf16 v[124:127], v[8:11], v[88:91], v[124:127]
	v_mfma_f32_16x16x32_bf16 v[132:135], v[8:11], v[104:107], v[132:135]
	v_mfma_f32_16x16x32_bf16 v[128:131], v[24:27], v[88:91], v[128:131]
	v_mfma_f32_16x16x32_bf16 v[136:139], v[24:27], v[104:107], v[136:139]
	v_mfma_f32_16x16x32_bf16 v[124:127], v[12:15], v[92:95], v[124:127]
	v_mfma_f32_16x16x32_bf16 v[132:135], v[12:15], v[108:111], v[132:135]
	v_mfma_f32_16x16x32_bf16 v[128:131], v[28:31], v[92:95], v[128:131]
	v_mfma_f32_16x16x32_bf16 v[136:139], v[28:31], v[108:111], v[136:139]
	v_mfma_f32_16x16x32_bf16 v[124:127], v[16:19], v[96:99], v[124:127]
	v_mfma_f32_16x16x32_bf16 v[132:135], v[16:19], v[112:115], v[132:135]
	v_mfma_f32_16x16x32_bf16 v[128:131], v[32:35], v[96:99], v[128:131]
	v_mfma_f32_16x16x32_bf16 v[136:139], v[32:35], v[112:115], v[136:139]
	global_load_dwordx4 v[84:87], v205, s[52:53]
	global_load_dwordx4 v[88:91], v205, s[52:53] offset:64
	global_load_dwordx4 v[92:95], v205, s[52:53] offset:128
	global_load_dwordx4 v[96:99], v205, s[52:53] offset:192
	global_load_dwordx4 v[100:103], v205, s[54:55]
	global_load_dwordx4 v[104:107], v205, s[54:55] offset:64
	global_load_dwordx4 v[108:111], v205, s[54:55] offset:128
	global_load_dwordx4 v[112:115], v205, s[54:55] offset:192
	s_add_u32 s52, s52, 0x1000
	s_addc_u32 s53, s53, 0
	s_add_u32 s54, s54, 0x1000
	s_addc_u32 s55, s55, 0
	global_load_dword v172, v197, s[56:57] offset:64
	v_add_u32_e32 v233, 0x2440, v197
	global_load_dword v173, v233, s[56:57] offset:64
	v_add_u32_e32 v233, 0x4880, v197
	global_load_dword v174, v233, s[56:57] offset:64
	v_add_u32_e32 v233, 0x6cc0, v197
	global_load_dword v175, v233, s[56:57] offset:64
	v_add_u32_e32 v233, 0x24400, v197
	global_load_dword v176, v233, s[56:57] offset:64
	v_add_u32_e32 v233, 0x26840, v197
	global_load_dword v177, v233, s[56:57] offset:64
	v_add_u32_e32 v233, 0x28c80, v197
	global_load_dword v178, v233, s[56:57] offset:64
	v_add_u32_e32 v233, 0x2b0c0, v197
	global_load_dword v179, v233, s[56:57] offset:64
	s_waitcnt vmcnt(24)
	s_nop 7
	v_fma_f32 v164, v140, v124, v116
	v_fma_f32 v165, v141, v125, v117
	v_fma_f32 v166, v142, v126, v118
	v_fma_f32 v167, v143, v127, v119
	v_fma_f32 v164, v148, v132, v164
	v_fma_f32 v165, v149, v133, v165
	v_fma_f32 v166, v150, v134, v166
	v_fma_f32 v167, v151, v135, v167
	v_mul_f32_e32 v227, 0xbfb8aa3b, v180
	v_mul_f32_e32 v228, 0xbfb8aa3b, v181
	v_mul_f32_e32 v229, 0xbfb8aa3b, v182
	v_mul_f32_e32 v230, 0xbfb8aa3b, v183
	v_exp_f32_e32 v227, v227
	v_exp_f32_e32 v228, v228
	v_exp_f32_e32 v229, v229
	v_exp_f32_e32 v230, v230
	s_nop 0
	v_add_f32_e32 v227, 1.0, v227
	v_add_f32_e32 v228, 1.0, v228
	v_add_f32_e32 v229, 1.0, v229
	v_add_f32_e32 v230, 1.0, v230
	v_div_scale_f32 v231, s[100:101], v227, v227, v180
	v_rcp_f32_e32 v232, v231
	s_nop 0
	v_fma_f32 v233, -v231, v232, 1.0
	v_fmac_f32_e32 v232, v233, v232
	v_div_scale_f32 v233, vcc, v180, v227, v180
	v_mul_f32_e32 v192, v233, v232
	v_fma_f32 v193, -v231, v192, v233
	v_fmac_f32_e32 v192, v193, v232
	v_fma_f32 v231, -v231, v192, v233
	v_div_fmas_f32 v231, v231, v232, v192
	v_div_fixup_f32 v227, v231, v227, v180
	v_mul_f32_e32 v164, v164, v227
	v_fmac_f32_e32 v156, v164, v164
	v_div_scale_f32 v231, s[100:101], v228, v228, v181
	v_rcp_f32_e32 v232, v231
	s_nop 0
	v_fma_f32 v233, -v231, v232, 1.0
	v_fmac_f32_e32 v232, v233, v232
	v_div_scale_f32 v233, vcc, v181, v228, v181
	v_mul_f32_e32 v192, v233, v232
	v_fma_f32 v193, -v231, v192, v233
	v_fmac_f32_e32 v192, v193, v232
	v_fma_f32 v231, -v231, v192, v233
	v_div_fmas_f32 v231, v231, v232, v192
	v_div_fixup_f32 v228, v231, v228, v181
	v_mul_f32_e32 v165, v165, v228
	v_fmac_f32_e32 v157, v165, v165
	v_div_scale_f32 v231, s[100:101], v229, v229, v182
	v_rcp_f32_e32 v232, v231
	s_nop 0
	v_fma_f32 v233, -v231, v232, 1.0
	v_fmac_f32_e32 v232, v233, v232
	v_div_scale_f32 v233, vcc, v182, v229, v182
	v_mul_f32_e32 v192, v233, v232
	v_fma_f32 v193, -v231, v192, v233
	v_fmac_f32_e32 v192, v193, v232
	v_fma_f32 v231, -v231, v192, v233
	v_div_fmas_f32 v231, v231, v232, v192
	v_div_fixup_f32 v229, v231, v229, v182
	v_mul_f32_e32 v166, v166, v229
	v_fmac_f32_e32 v158, v166, v166
	v_div_scale_f32 v231, s[100:101], v230, v230, v183
	v_rcp_f32_e32 v232, v231
	s_nop 0
	v_fma_f32 v233, -v231, v232, 1.0
	v_fmac_f32_e32 v232, v233, v232
	v_div_scale_f32 v233, vcc, v183, v230, v183
	v_mul_f32_e32 v192, v233, v232
	v_fma_f32 v193, -v231, v192, v233
	v_fmac_f32_e32 v192, v193, v232
	v_fma_f32 v231, -v231, v192, v233
	v_div_fmas_f32 v231, v231, v232, v192
	v_div_fixup_f32 v230, v231, v230, v183
	v_mul_f32_e32 v167, v167, v230
	v_fmac_f32_e32 v159, v167, v167
	ds_write_b128 v225, v[164:167] offset:0
	v_fma_f32 v168, v144, v128, v120
	v_fma_f32 v169, v145, v129, v121
	v_fma_f32 v170, v146, v130, v122
	v_fma_f32 v171, v147, v131, v123
	v_fma_f32 v168, v152, v136, v168
	v_fma_f32 v169, v153, v137, v169
	v_fma_f32 v170, v154, v138, v170
	v_fma_f32 v171, v155, v139, v171
	v_mul_f32_e32 v227, 0xbfb8aa3b, v184
	v_mul_f32_e32 v228, 0xbfb8aa3b, v185
	v_mul_f32_e32 v229, 0xbfb8aa3b, v186
	v_mul_f32_e32 v230, 0xbfb8aa3b, v187
	v_exp_f32_e32 v227, v227
	v_exp_f32_e32 v228, v228
	v_exp_f32_e32 v229, v229
	v_exp_f32_e32 v230, v230
	s_nop 0
	v_add_f32_e32 v227, 1.0, v227
	v_add_f32_e32 v228, 1.0, v228
	v_add_f32_e32 v229, 1.0, v229
	v_add_f32_e32 v230, 1.0, v230
	v_div_scale_f32 v231, s[100:101], v227, v227, v184
	v_rcp_f32_e32 v232, v231
	s_nop 0
	v_fma_f32 v233, -v231, v232, 1.0
	v_fmac_f32_e32 v232, v233, v232
	v_div_scale_f32 v233, vcc, v184, v227, v184
	v_mul_f32_e32 v192, v233, v232
	v_fma_f32 v193, -v231, v192, v233
	v_fmac_f32_e32 v192, v193, v232
	v_fma_f32 v231, -v231, v192, v233
	v_div_fmas_f32 v231, v231, v232, v192
	v_div_fixup_f32 v227, v231, v227, v184
	v_mul_f32_e32 v168, v168, v227
	v_fmac_f32_e32 v160, v168, v168
	v_div_scale_f32 v231, s[100:101], v228, v228, v185
	v_rcp_f32_e32 v232, v231
	s_nop 0
	v_fma_f32 v233, -v231, v232, 1.0
	v_fmac_f32_e32 v232, v233, v232
	v_div_scale_f32 v233, vcc, v185, v228, v185
	v_mul_f32_e32 v192, v233, v232
	v_fma_f32 v193, -v231, v192, v233
	v_fmac_f32_e32 v192, v193, v232
	v_fma_f32 v231, -v231, v192, v233
	v_div_fmas_f32 v231, v231, v232, v192
	v_div_fixup_f32 v228, v231, v228, v185
	v_mul_f32_e32 v169, v169, v228
	v_fmac_f32_e32 v161, v169, v169
	v_div_scale_f32 v231, s[100:101], v229, v229, v186
	v_rcp_f32_e32 v232, v231
	s_nop 0
	v_fma_f32 v233, -v231, v232, 1.0
	v_fmac_f32_e32 v232, v233, v232
	v_div_scale_f32 v233, vcc, v186, v229, v186
	v_mul_f32_e32 v192, v233, v232
	v_fma_f32 v193, -v231, v192, v233
	v_fmac_f32_e32 v192, v193, v232
	v_fma_f32 v231, -v231, v192, v233
	v_div_fmas_f32 v231, v231, v232, v192
	v_div_fixup_f32 v229, v231, v229, v186
	v_mul_f32_e32 v170, v170, v229
	v_fmac_f32_e32 v162, v170, v170
	v_div_scale_f32 v231, s[100:101], v230, v230, v187
	v_rcp_f32_e32 v232, v231
	s_nop 0
	v_fma_f32 v233, -v231, v232, 1.0
	v_fmac_f32_e32 v232, v233, v232
	v_div_scale_f32 v233, vcc, v187, v230, v187
	v_mul_f32_e32 v192, v233, v232
	v_fma_f32 v193, -v231, v192, v233
	v_fmac_f32_e32 v192, v193, v232
	v_fma_f32 v231, -v231, v192, v233
	v_div_fmas_f32 v231, v231, v232, v192
	v_div_fixup_f32 v230, v231, v230, v187
	v_mul_f32_e32 v171, v171, v230
	v_fmac_f32_e32 v163, v171, v171
	ds_write_b128 v225, v[168:171] offset:1024
	s_waitcnt vmcnt(16)
	v_mfma_f32_16x16x32_bf16 v[116:119], v[36:39], v[68:71], 0
	v_mfma_f32_16x16x32_bf16 v[120:123], v[52:55], v[68:71], 0
	v_mfma_f32_16x16x32_bf16 v[116:119], v[40:43], v[72:75], v[116:119]
	v_mfma_f32_16x16x32_bf16 v[120:123], v[56:59], v[72:75], v[120:123]
	v_mfma_f32_16x16x32_bf16 v[116:119], v[44:47], v[76:79], v[116:119]
	v_mfma_f32_16x16x32_bf16 v[120:123], v[60:63], v[76:79], v[120:123]
	v_mfma_f32_16x16x32_bf16 v[116:119], v[48:51], v[80:83], v[116:119]
	v_mfma_f32_16x16x32_bf16 v[120:123], v[64:67], v[80:83], v[120:123]
	global_load_dwordx2 v[68:69], v204, s[50:51]
	global_load_dwordx2 v[70:71], v204, s[50:51] offset:32
	global_load_dwordx2 v[72:73], v204, s[50:51] offset:64
	global_load_dwordx2 v[74:75], v204, s[50:51] offset:96
	global_load_dwordx2 v[76:77], v204, s[50:51] offset:128
	global_load_dwordx2 v[78:79], v204, s[50:51] offset:160
	global_load_dwordx2 v[80:81], v204, s[50:51] offset:192
	global_load_dwordx2 v[82:83], v204, s[50:51] offset:224
	s_add_u32 s50, s50, 0x1000
	s_addc_u32 s51, s51, 0
	s_waitcnt vmcnt(16)
	v_mfma_f32_16x16x32_bf16 v[124:127], v[4:7], v[84:87], 0
	v_mfma_f32_16x16x32_bf16 v[132:135], v[4:7], v[100:103], 0
	v_mfma_f32_16x16x32_bf16 v[128:131], v[20:23], v[84:87], 0
	v_mfma_f32_16x16x32_bf16 v[136:139], v[20:23], v[100:103], 0
	v_mfma_f32_16x16x32_bf16 v[124:127], v[8:11], v[88:91], v[124:127]
	v_mfma_f32_16x16x32_bf16 v[132:135], v[8:11], v[104:107], v[132:135]
	v_mfma_f32_16x16x32_bf16 v[128:131], v[24:27], v[88:91], v[128:131]
	v_mfma_f32_16x16x32_bf16 v[136:139], v[24:27], v[104:107], v[136:139]
	v_mfma_f32_16x16x32_bf16 v[124:127], v[12:15], v[92:95], v[124:127]
	v_mfma_f32_16x16x32_bf16 v[132:135], v[12:15], v[108:111], v[132:135]
	v_mfma_f32_16x16x32_bf16 v[128:131], v[28:31], v[92:95], v[128:131]
	v_mfma_f32_16x16x32_bf16 v[136:139], v[28:31], v[108:111], v[136:139]
	v_mfma_f32_16x16x32_bf16 v[124:127], v[16:19], v[96:99], v[124:127]
	v_mfma_f32_16x16x32_bf16 v[132:135], v[16:19], v[112:115], v[132:135]
	v_mfma_f32_16x16x32_bf16 v[128:131], v[32:35], v[96:99], v[128:131]
	v_mfma_f32_16x16x32_bf16 v[136:139], v[32:35], v[112:115], v[136:139]
	global_load_dwordx4 v[84:87], v205, s[52:53]
	global_load_dwordx4 v[88:91], v205, s[52:53] offset:64
	global_load_dwordx4 v[92:95], v205, s[52:53] offset:128
	global_load_dwordx4 v[96:99], v205, s[52:53] offset:192
	global_load_dwordx4 v[100:103], v205, s[54:55]
	global_load_dwordx4 v[104:107], v205, s[54:55] offset:64
	global_load_dwordx4 v[108:111], v205, s[54:55] offset:128
	global_load_dwordx4 v[112:115], v205, s[54:55] offset:192
	s_add_u32 s52, s52, 0x1000
	s_addc_u32 s53, s53, 0
	s_add_u32 s54, s54, 0x1000
	s_addc_u32 s55, s55, 0
	global_load_dword v180, v197, s[56:57] offset:128
	v_add_u32_e32 v233, 0x2440, v197
	global_load_dword v181, v233, s[56:57] offset:128
	v_add_u32_e32 v233, 0x4880, v197
	global_load_dword v182, v233, s[56:57] offset:128
	v_add_u32_e32 v233, 0x6cc0, v197
	global_load_dword v183, v233, s[56:57] offset:128
	v_add_u32_e32 v233, 0x24400, v197
	global_load_dword v184, v233, s[56:57] offset:128
	v_add_u32_e32 v233, 0x26840, v197
	global_load_dword v185, v233, s[56:57] offset:128
	v_add_u32_e32 v233, 0x28c80, v197
	global_load_dword v186, v233, s[56:57] offset:128
	v_add_u32_e32 v233, 0x2b0c0, v197
	global_load_dword v187, v233, s[56:57] offset:128
	s_waitcnt vmcnt(24)
	s_nop 7
	v_fma_f32 v164, v140, v124, v116
	v_fma_f32 v165, v141, v125, v117
	v_fma_f32 v166, v142, v126, v118
	v_fma_f32 v167, v143, v127, v119
	v_fma_f32 v164, v148, v132, v164
	v_fma_f32 v165, v149, v133, v165
	v_fma_f32 v166, v150, v134, v166
	v_fma_f32 v167, v151, v135, v167
	v_mul_f32_e32 v227, 0xbfb8aa3b, v172
	v_mul_f32_e32 v228, 0xbfb8aa3b, v173
	v_mul_f32_e32 v229, 0xbfb8aa3b, v174
	v_mul_f32_e32 v230, 0xbfb8aa3b, v175
	v_exp_f32_e32 v227, v227
	v_exp_f32_e32 v228, v228
	v_exp_f32_e32 v229, v229
	v_exp_f32_e32 v230, v230
	s_nop 0
	v_add_f32_e32 v227, 1.0, v227
	v_add_f32_e32 v228, 1.0, v228
	v_add_f32_e32 v229, 1.0, v229
	v_add_f32_e32 v230, 1.0, v230
	v_div_scale_f32 v231, s[100:101], v227, v227, v172
	v_rcp_f32_e32 v232, v231
	s_nop 0
	v_fma_f32 v233, -v231, v232, 1.0
	v_fmac_f32_e32 v232, v233, v232
	v_div_scale_f32 v233, vcc, v172, v227, v172
	v_mul_f32_e32 v192, v233, v232
	v_fma_f32 v193, -v231, v192, v233
	v_fmac_f32_e32 v192, v193, v232
	v_fma_f32 v231, -v231, v192, v233
	v_div_fmas_f32 v231, v231, v232, v192
	v_div_fixup_f32 v227, v231, v227, v172
	v_mul_f32_e32 v164, v164, v227
	v_fmac_f32_e32 v156, v164, v164
	v_div_scale_f32 v231, s[100:101], v228, v228, v173
	v_rcp_f32_e32 v232, v231
	s_nop 0
	v_fma_f32 v233, -v231, v232, 1.0
	v_fmac_f32_e32 v232, v233, v232
	v_div_scale_f32 v233, vcc, v173, v228, v173
	v_mul_f32_e32 v192, v233, v232
	v_fma_f32 v193, -v231, v192, v233
	v_fmac_f32_e32 v192, v193, v232
	v_fma_f32 v231, -v231, v192, v233
	v_div_fmas_f32 v231, v231, v232, v192
	v_div_fixup_f32 v228, v231, v228, v173
	v_mul_f32_e32 v165, v165, v228
	v_fmac_f32_e32 v157, v165, v165
	v_div_scale_f32 v231, s[100:101], v229, v229, v174
	v_rcp_f32_e32 v232, v231
	s_nop 0
	v_fma_f32 v233, -v231, v232, 1.0
	v_fmac_f32_e32 v232, v233, v232
	v_div_scale_f32 v233, vcc, v174, v229, v174
	v_mul_f32_e32 v192, v233, v232
	v_fma_f32 v193, -v231, v192, v233
	v_fmac_f32_e32 v192, v193, v232
	v_fma_f32 v231, -v231, v192, v233
	v_div_fmas_f32 v231, v231, v232, v192
	v_div_fixup_f32 v229, v231, v229, v174
	v_mul_f32_e32 v166, v166, v229
	v_fmac_f32_e32 v158, v166, v166
	v_div_scale_f32 v231, s[100:101], v230, v230, v175
	v_rcp_f32_e32 v232, v231
	s_nop 0
	v_fma_f32 v233, -v231, v232, 1.0
	v_fmac_f32_e32 v232, v233, v232
	v_div_scale_f32 v233, vcc, v175, v230, v175
	v_mul_f32_e32 v192, v233, v232
	v_fma_f32 v193, -v231, v192, v233
	v_fmac_f32_e32 v192, v193, v232
	v_fma_f32 v231, -v231, v192, v233
	v_div_fmas_f32 v231, v231, v232, v192
	v_div_fixup_f32 v230, v231, v230, v175
	v_mul_f32_e32 v167, v167, v230
	v_fmac_f32_e32 v159, v167, v167
	ds_write_b128 v225, v[164:167] offset:2048
	v_fma_f32 v168, v144, v128, v120
	v_fma_f32 v169, v145, v129, v121
	v_fma_f32 v170, v146, v130, v122
	v_fma_f32 v171, v147, v131, v123
	v_fma_f32 v168, v152, v136, v168
	v_fma_f32 v169, v153, v137, v169
	v_fma_f32 v170, v154, v138, v170
	v_fma_f32 v171, v155, v139, v171
	v_mul_f32_e32 v227, 0xbfb8aa3b, v176
	v_mul_f32_e32 v228, 0xbfb8aa3b, v177
	v_mul_f32_e32 v229, 0xbfb8aa3b, v178
	v_mul_f32_e32 v230, 0xbfb8aa3b, v179
	v_exp_f32_e32 v227, v227
	v_exp_f32_e32 v228, v228
	v_exp_f32_e32 v229, v229
	v_exp_f32_e32 v230, v230
	s_nop 0
	v_add_f32_e32 v227, 1.0, v227
	v_add_f32_e32 v228, 1.0, v228
	v_add_f32_e32 v229, 1.0, v229
	v_add_f32_e32 v230, 1.0, v230
	v_div_scale_f32 v231, s[100:101], v227, v227, v176
	v_rcp_f32_e32 v232, v231
	s_nop 0
	v_fma_f32 v233, -v231, v232, 1.0
	v_fmac_f32_e32 v232, v233, v232
	v_div_scale_f32 v233, vcc, v176, v227, v176
	v_mul_f32_e32 v192, v233, v232
	v_fma_f32 v193, -v231, v192, v233
	v_fmac_f32_e32 v192, v193, v232
	v_fma_f32 v231, -v231, v192, v233
	v_div_fmas_f32 v231, v231, v232, v192
	v_div_fixup_f32 v227, v231, v227, v176
	v_mul_f32_e32 v168, v168, v227
	v_fmac_f32_e32 v160, v168, v168
	v_div_scale_f32 v231, s[100:101], v228, v228, v177
	v_rcp_f32_e32 v232, v231
	s_nop 0
	v_fma_f32 v233, -v231, v232, 1.0
	v_fmac_f32_e32 v232, v233, v232
	v_div_scale_f32 v233, vcc, v177, v228, v177
	v_mul_f32_e32 v192, v233, v232
	v_fma_f32 v193, -v231, v192, v233
	v_fmac_f32_e32 v192, v193, v232
	v_fma_f32 v231, -v231, v192, v233
	v_div_fmas_f32 v231, v231, v232, v192
	v_div_fixup_f32 v228, v231, v228, v177
	v_mul_f32_e32 v169, v169, v228
	v_fmac_f32_e32 v161, v169, v169
	v_div_scale_f32 v231, s[100:101], v229, v229, v178
	v_rcp_f32_e32 v232, v231
	s_nop 0
	v_fma_f32 v233, -v231, v232, 1.0
	v_fmac_f32_e32 v232, v233, v232
	v_div_scale_f32 v233, vcc, v178, v229, v178
	v_mul_f32_e32 v192, v233, v232
	v_fma_f32 v193, -v231, v192, v233
	v_fmac_f32_e32 v192, v193, v232
	v_fma_f32 v231, -v231, v192, v233
	v_div_fmas_f32 v231, v231, v232, v192
	v_div_fixup_f32 v229, v231, v229, v178
	v_mul_f32_e32 v170, v170, v229
	v_fmac_f32_e32 v162, v170, v170
	v_div_scale_f32 v231, s[100:101], v230, v230, v179
	v_rcp_f32_e32 v232, v231
	s_nop 0
	v_fma_f32 v233, -v231, v232, 1.0
	v_fmac_f32_e32 v232, v233, v232
	v_div_scale_f32 v233, vcc, v179, v230, v179
	v_mul_f32_e32 v192, v233, v232
	v_fma_f32 v193, -v231, v192, v233
	v_fmac_f32_e32 v192, v193, v232
	v_fma_f32 v231, -v231, v192, v233
	v_div_fmas_f32 v231, v231, v232, v192
	v_div_fixup_f32 v230, v231, v230, v179
	v_mul_f32_e32 v171, v171, v230
	v_fmac_f32_e32 v163, v171, v171
	ds_write_b128 v225, v[168:171] offset:3072
	s_waitcnt vmcnt(16)
	v_mfma_f32_16x16x32_bf16 v[116:119], v[36:39], v[68:71], 0
	v_mfma_f32_16x16x32_bf16 v[120:123], v[52:55], v[68:71], 0
	v_mfma_f32_16x16x32_bf16 v[116:119], v[40:43], v[72:75], v[116:119]
	v_mfma_f32_16x16x32_bf16 v[120:123], v[56:59], v[72:75], v[120:123]
	v_mfma_f32_16x16x32_bf16 v[116:119], v[44:47], v[76:79], v[116:119]
	v_mfma_f32_16x16x32_bf16 v[120:123], v[60:63], v[76:79], v[120:123]
	v_mfma_f32_16x16x32_bf16 v[116:119], v[48:51], v[80:83], v[116:119]
	v_mfma_f32_16x16x32_bf16 v[120:123], v[64:67], v[80:83], v[120:123]
	global_load_dwordx2 v[68:69], v204, s[50:51]
	global_load_dwordx2 v[70:71], v204, s[50:51] offset:32
	global_load_dwordx2 v[72:73], v204, s[50:51] offset:64
	global_load_dwordx2 v[74:75], v204, s[50:51] offset:96
	global_load_dwordx2 v[76:77], v204, s[50:51] offset:128
	global_load_dwordx2 v[78:79], v204, s[50:51] offset:160
	global_load_dwordx2 v[80:81], v204, s[50:51] offset:192
	global_load_dwordx2 v[82:83], v204, s[50:51] offset:224
	s_add_u32 s50, s50, 0x1000
	s_addc_u32 s51, s51, 0
	s_waitcnt vmcnt(16)
	v_mfma_f32_16x16x32_bf16 v[124:127], v[4:7], v[84:87], 0
	v_mfma_f32_16x16x32_bf16 v[132:135], v[4:7], v[100:103], 0
	v_mfma_f32_16x16x32_bf16 v[128:131], v[20:23], v[84:87], 0
	v_mfma_f32_16x16x32_bf16 v[136:139], v[20:23], v[100:103], 0
	v_mfma_f32_16x16x32_bf16 v[124:127], v[8:11], v[88:91], v[124:127]
	v_mfma_f32_16x16x32_bf16 v[132:135], v[8:11], v[104:107], v[132:135]
	v_mfma_f32_16x16x32_bf16 v[128:131], v[24:27], v[88:91], v[128:131]
	v_mfma_f32_16x16x32_bf16 v[136:139], v[24:27], v[104:107], v[136:139]
	v_mfma_f32_16x16x32_bf16 v[124:127], v[12:15], v[92:95], v[124:127]
	v_mfma_f32_16x16x32_bf16 v[132:135], v[12:15], v[108:111], v[132:135]
	v_mfma_f32_16x16x32_bf16 v[128:131], v[28:31], v[92:95], v[128:131]
	v_mfma_f32_16x16x32_bf16 v[136:139], v[28:31], v[108:111], v[136:139]
	v_mfma_f32_16x16x32_bf16 v[124:127], v[16:19], v[96:99], v[124:127]
	v_mfma_f32_16x16x32_bf16 v[132:135], v[16:19], v[112:115], v[132:135]
	v_mfma_f32_16x16x32_bf16 v[128:131], v[32:35], v[96:99], v[128:131]
	v_mfma_f32_16x16x32_bf16 v[136:139], v[32:35], v[112:115], v[136:139]
	global_load_dwordx4 v[84:87], v205, s[52:53]
	global_load_dwordx4 v[88:91], v205, s[52:53] offset:64
	global_load_dwordx4 v[92:95], v205, s[52:53] offset:128
	global_load_dwordx4 v[96:99], v205, s[52:53] offset:192
	global_load_dwordx4 v[100:103], v205, s[54:55]
	global_load_dwordx4 v[104:107], v205, s[54:55] offset:64
	global_load_dwordx4 v[108:111], v205, s[54:55] offset:128
	global_load_dwordx4 v[112:115], v205, s[54:55] offset:192
	s_add_u32 s52, s52, 0x1000
	s_addc_u32 s53, s53, 0
	s_add_u32 s54, s54, 0x1000
	s_addc_u32 s55, s55, 0
	global_load_dword v172, v197, s[56:57] offset:192
	v_add_u32_e32 v233, 0x2440, v197
	global_load_dword v173, v233, s[56:57] offset:192
	v_add_u32_e32 v233, 0x4880, v197
	global_load_dword v174, v233, s[56:57] offset:192
	v_add_u32_e32 v233, 0x6cc0, v197
	global_load_dword v175, v233, s[56:57] offset:192
	v_add_u32_e32 v233, 0x24400, v197
	global_load_dword v176, v233, s[56:57] offset:192
	v_add_u32_e32 v233, 0x26840, v197
	global_load_dword v177, v233, s[56:57] offset:192
	v_add_u32_e32 v233, 0x28c80, v197
	global_load_dword v178, v233, s[56:57] offset:192
	v_add_u32_e32 v233, 0x2b0c0, v197
	global_load_dword v179, v233, s[56:57] offset:192
	s_waitcnt vmcnt(24)
	s_nop 7
	v_fma_f32 v164, v140, v124, v116
	v_fma_f32 v165, v141, v125, v117
	v_fma_f32 v166, v142, v126, v118
	v_fma_f32 v167, v143, v127, v119
	v_fma_f32 v164, v148, v132, v164
	v_fma_f32 v165, v149, v133, v165
	v_fma_f32 v166, v150, v134, v166
	v_fma_f32 v167, v151, v135, v167
	v_mul_f32_e32 v227, 0xbfb8aa3b, v180
	v_mul_f32_e32 v228, 0xbfb8aa3b, v181
	v_mul_f32_e32 v229, 0xbfb8aa3b, v182
	v_mul_f32_e32 v230, 0xbfb8aa3b, v183
	v_exp_f32_e32 v227, v227
	v_exp_f32_e32 v228, v228
	v_exp_f32_e32 v229, v229
	v_exp_f32_e32 v230, v230
	s_nop 0
	v_add_f32_e32 v227, 1.0, v227
	v_add_f32_e32 v228, 1.0, v228
	v_add_f32_e32 v229, 1.0, v229
	v_add_f32_e32 v230, 1.0, v230
	v_div_scale_f32 v231, s[100:101], v227, v227, v180
	v_rcp_f32_e32 v232, v231
	s_nop 0
	v_fma_f32 v233, -v231, v232, 1.0
	v_fmac_f32_e32 v232, v233, v232
	v_div_scale_f32 v233, vcc, v180, v227, v180
	v_mul_f32_e32 v192, v233, v232
	v_fma_f32 v193, -v231, v192, v233
	v_fmac_f32_e32 v192, v193, v232
	v_fma_f32 v231, -v231, v192, v233
	v_div_fmas_f32 v231, v231, v232, v192
	v_div_fixup_f32 v227, v231, v227, v180
	v_mul_f32_e32 v164, v164, v227
	v_fmac_f32_e32 v156, v164, v164
	v_div_scale_f32 v231, s[100:101], v228, v228, v181
	v_rcp_f32_e32 v232, v231
	s_nop 0
	v_fma_f32 v233, -v231, v232, 1.0
	v_fmac_f32_e32 v232, v233, v232
	v_div_scale_f32 v233, vcc, v181, v228, v181
	v_mul_f32_e32 v192, v233, v232
	v_fma_f32 v193, -v231, v192, v233
	v_fmac_f32_e32 v192, v193, v232
	v_fma_f32 v231, -v231, v192, v233
	v_div_fmas_f32 v231, v231, v232, v192
	v_div_fixup_f32 v228, v231, v228, v181
	v_mul_f32_e32 v165, v165, v228
	v_fmac_f32_e32 v157, v165, v165
	v_div_scale_f32 v231, s[100:101], v229, v229, v182
	v_rcp_f32_e32 v232, v231
	s_nop 0
	v_fma_f32 v233, -v231, v232, 1.0
	v_fmac_f32_e32 v232, v233, v232
	v_div_scale_f32 v233, vcc, v182, v229, v182
	v_mul_f32_e32 v192, v233, v232
	v_fma_f32 v193, -v231, v192, v233
	v_fmac_f32_e32 v192, v193, v232
	v_fma_f32 v231, -v231, v192, v233
	v_div_fmas_f32 v231, v231, v232, v192
	v_div_fixup_f32 v229, v231, v229, v182
	v_mul_f32_e32 v166, v166, v229
	v_fmac_f32_e32 v158, v166, v166
	v_div_scale_f32 v231, s[100:101], v230, v230, v183
	v_rcp_f32_e32 v232, v231
	s_nop 0
	v_fma_f32 v233, -v231, v232, 1.0
	v_fmac_f32_e32 v232, v233, v232
	v_div_scale_f32 v233, vcc, v183, v230, v183
	v_mul_f32_e32 v192, v233, v232
	v_fma_f32 v193, -v231, v192, v233
	v_fmac_f32_e32 v192, v193, v232
	v_fma_f32 v231, -v231, v192, v233
	v_div_fmas_f32 v231, v231, v232, v192
	v_div_fixup_f32 v230, v231, v230, v183
	v_mul_f32_e32 v167, v167, v230
	v_fmac_f32_e32 v159, v167, v167
	ds_write_b128 v225, v[164:167] offset:4096
	v_fma_f32 v168, v144, v128, v120
	v_fma_f32 v169, v145, v129, v121
	v_fma_f32 v170, v146, v130, v122
	v_fma_f32 v171, v147, v131, v123
	v_fma_f32 v168, v152, v136, v168
	v_fma_f32 v169, v153, v137, v169
	v_fma_f32 v170, v154, v138, v170
	v_fma_f32 v171, v155, v139, v171
	v_mul_f32_e32 v227, 0xbfb8aa3b, v184
	v_mul_f32_e32 v228, 0xbfb8aa3b, v185
	v_mul_f32_e32 v229, 0xbfb8aa3b, v186
	v_mul_f32_e32 v230, 0xbfb8aa3b, v187
	v_exp_f32_e32 v227, v227
	v_exp_f32_e32 v228, v228
	v_exp_f32_e32 v229, v229
	v_exp_f32_e32 v230, v230
	s_nop 0
	v_add_f32_e32 v227, 1.0, v227
	v_add_f32_e32 v228, 1.0, v228
	v_add_f32_e32 v229, 1.0, v229
	v_add_f32_e32 v230, 1.0, v230
	v_div_scale_f32 v231, s[100:101], v227, v227, v184
	v_rcp_f32_e32 v232, v231
	s_nop 0
	v_fma_f32 v233, -v231, v232, 1.0
	v_fmac_f32_e32 v232, v233, v232
	v_div_scale_f32 v233, vcc, v184, v227, v184
	v_mul_f32_e32 v192, v233, v232
	v_fma_f32 v193, -v231, v192, v233
	v_fmac_f32_e32 v192, v193, v232
	v_fma_f32 v231, -v231, v192, v233
	v_div_fmas_f32 v231, v231, v232, v192
	v_div_fixup_f32 v227, v231, v227, v184
	v_mul_f32_e32 v168, v168, v227
	v_fmac_f32_e32 v160, v168, v168
	v_div_scale_f32 v231, s[100:101], v228, v228, v185
	v_rcp_f32_e32 v232, v231
	s_nop 0
	v_fma_f32 v233, -v231, v232, 1.0
	v_fmac_f32_e32 v232, v233, v232
	v_div_scale_f32 v233, vcc, v185, v228, v185
	v_mul_f32_e32 v192, v233, v232
	v_fma_f32 v193, -v231, v192, v233
	v_fmac_f32_e32 v192, v193, v232
	v_fma_f32 v231, -v231, v192, v233
	v_div_fmas_f32 v231, v231, v232, v192
	v_div_fixup_f32 v228, v231, v228, v185
	v_mul_f32_e32 v169, v169, v228
	v_fmac_f32_e32 v161, v169, v169
	v_div_scale_f32 v231, s[100:101], v229, v229, v186
	v_rcp_f32_e32 v232, v231
	s_nop 0
	v_fma_f32 v233, -v231, v232, 1.0
	v_fmac_f32_e32 v232, v233, v232
	v_div_scale_f32 v233, vcc, v186, v229, v186
	v_mul_f32_e32 v192, v233, v232
	v_fma_f32 v193, -v231, v192, v233
	v_fmac_f32_e32 v192, v193, v232
	v_fma_f32 v231, -v231, v192, v233
	v_div_fmas_f32 v231, v231, v232, v192
	v_div_fixup_f32 v229, v231, v229, v186
	v_mul_f32_e32 v170, v170, v229
	v_fmac_f32_e32 v162, v170, v170
	v_div_scale_f32 v231, s[100:101], v230, v230, v187
	v_rcp_f32_e32 v232, v231
	s_nop 0
	v_fma_f32 v233, -v231, v232, 1.0
	v_fmac_f32_e32 v232, v233, v232
	v_div_scale_f32 v233, vcc, v187, v230, v187
	v_mul_f32_e32 v192, v233, v232
	v_fma_f32 v193, -v231, v192, v233
	v_fmac_f32_e32 v192, v193, v232
	v_fma_f32 v231, -v231, v192, v233
	v_div_fmas_f32 v231, v231, v232, v192
	v_div_fixup_f32 v230, v231, v230, v187
	v_mul_f32_e32 v171, v171, v230
	v_fmac_f32_e32 v163, v171, v171
	ds_write_b128 v225, v[168:171] offset:5120
	s_waitcnt vmcnt(16)
	v_mfma_f32_16x16x32_bf16 v[116:119], v[36:39], v[68:71], 0
	v_mfma_f32_16x16x32_bf16 v[120:123], v[52:55], v[68:71], 0
	v_mfma_f32_16x16x32_bf16 v[116:119], v[40:43], v[72:75], v[116:119]
	v_mfma_f32_16x16x32_bf16 v[120:123], v[56:59], v[72:75], v[120:123]
	v_mfma_f32_16x16x32_bf16 v[116:119], v[44:47], v[76:79], v[116:119]
	v_mfma_f32_16x16x32_bf16 v[120:123], v[60:63], v[76:79], v[120:123]
	v_mfma_f32_16x16x32_bf16 v[116:119], v[48:51], v[80:83], v[116:119]
	v_mfma_f32_16x16x32_bf16 v[120:123], v[64:67], v[80:83], v[120:123]
	s_waitcnt vmcnt(8)
	v_mfma_f32_16x16x32_bf16 v[124:127], v[4:7], v[84:87], 0
	v_mfma_f32_16x16x32_bf16 v[132:135], v[4:7], v[100:103], 0
	v_mfma_f32_16x16x32_bf16 v[128:131], v[20:23], v[84:87], 0
	v_mfma_f32_16x16x32_bf16 v[136:139], v[20:23], v[100:103], 0
	v_mfma_f32_16x16x32_bf16 v[124:127], v[8:11], v[88:91], v[124:127]
	v_mfma_f32_16x16x32_bf16 v[132:135], v[8:11], v[104:107], v[132:135]
	v_mfma_f32_16x16x32_bf16 v[128:131], v[24:27], v[88:91], v[128:131]
	v_mfma_f32_16x16x32_bf16 v[136:139], v[24:27], v[104:107], v[136:139]
	v_mfma_f32_16x16x32_bf16 v[124:127], v[12:15], v[92:95], v[124:127]
	v_mfma_f32_16x16x32_bf16 v[132:135], v[12:15], v[108:111], v[132:135]
	v_mfma_f32_16x16x32_bf16 v[128:131], v[28:31], v[92:95], v[128:131]
	v_mfma_f32_16x16x32_bf16 v[136:139], v[28:31], v[108:111], v[136:139]
	v_mfma_f32_16x16x32_bf16 v[124:127], v[16:19], v[96:99], v[124:127]
	v_mfma_f32_16x16x32_bf16 v[132:135], v[16:19], v[112:115], v[132:135]
	v_mfma_f32_16x16x32_bf16 v[128:131], v[32:35], v[96:99], v[128:131]
	v_mfma_f32_16x16x32_bf16 v[136:139], v[32:35], v[112:115], v[136:139]
	s_waitcnt vmcnt(0)
	s_nop 7
	v_fma_f32 v164, v140, v124, v116
	v_fma_f32 v165, v141, v125, v117
	v_fma_f32 v166, v142, v126, v118
	v_fma_f32 v167, v143, v127, v119
	v_fma_f32 v164, v148, v132, v164
	v_fma_f32 v165, v149, v133, v165
	v_fma_f32 v166, v150, v134, v166
	v_fma_f32 v167, v151, v135, v167
	v_mul_f32_e32 v227, 0xbfb8aa3b, v172
	v_mul_f32_e32 v228, 0xbfb8aa3b, v173
	v_mul_f32_e32 v229, 0xbfb8aa3b, v174
	v_mul_f32_e32 v230, 0xbfb8aa3b, v175
	v_exp_f32_e32 v227, v227
	v_exp_f32_e32 v228, v228
	v_exp_f32_e32 v229, v229
	v_exp_f32_e32 v230, v230
	s_nop 0
	v_add_f32_e32 v227, 1.0, v227
	v_add_f32_e32 v228, 1.0, v228
	v_add_f32_e32 v229, 1.0, v229
	v_add_f32_e32 v230, 1.0, v230
	v_div_scale_f32 v231, s[100:101], v227, v227, v172
	v_rcp_f32_e32 v232, v231
	s_nop 0
	v_fma_f32 v233, -v231, v232, 1.0
	v_fmac_f32_e32 v232, v233, v232
	v_div_scale_f32 v233, vcc, v172, v227, v172
	v_mul_f32_e32 v192, v233, v232
	v_fma_f32 v193, -v231, v192, v233
	v_fmac_f32_e32 v192, v193, v232
	v_fma_f32 v231, -v231, v192, v233
	v_div_fmas_f32 v231, v231, v232, v192
	v_div_fixup_f32 v227, v231, v227, v172
	v_mul_f32_e32 v164, v164, v227
	v_fmac_f32_e32 v156, v164, v164
	v_div_scale_f32 v231, s[100:101], v228, v228, v173
	v_rcp_f32_e32 v232, v231
	s_nop 0
	v_fma_f32 v233, -v231, v232, 1.0
	v_fmac_f32_e32 v232, v233, v232
	v_div_scale_f32 v233, vcc, v173, v228, v173
	v_mul_f32_e32 v192, v233, v232
	v_fma_f32 v193, -v231, v192, v233
	v_fmac_f32_e32 v192, v193, v232
	v_fma_f32 v231, -v231, v192, v233
	v_div_fmas_f32 v231, v231, v232, v192
	v_div_fixup_f32 v228, v231, v228, v173
	v_mul_f32_e32 v165, v165, v228
	v_fmac_f32_e32 v157, v165, v165
	v_div_scale_f32 v231, s[100:101], v229, v229, v174
	v_rcp_f32_e32 v232, v231
	s_nop 0
	v_fma_f32 v233, -v231, v232, 1.0
	v_fmac_f32_e32 v232, v233, v232
	v_div_scale_f32 v233, vcc, v174, v229, v174
	v_mul_f32_e32 v192, v233, v232
	v_fma_f32 v193, -v231, v192, v233
	v_fmac_f32_e32 v192, v193, v232
	v_fma_f32 v231, -v231, v192, v233
	v_div_fmas_f32 v231, v231, v232, v192
	v_div_fixup_f32 v229, v231, v229, v174
	v_mul_f32_e32 v166, v166, v229
	v_fmac_f32_e32 v158, v166, v166
	v_div_scale_f32 v231, s[100:101], v230, v230, v175
	v_rcp_f32_e32 v232, v231
	s_nop 0
	v_fma_f32 v233, -v231, v232, 1.0
	v_fmac_f32_e32 v232, v233, v232
	v_div_scale_f32 v233, vcc, v175, v230, v175
	v_mul_f32_e32 v192, v233, v232
	v_fma_f32 v193, -v231, v192, v233
	v_fmac_f32_e32 v192, v193, v232
	v_fma_f32 v231, -v231, v192, v233
	v_div_fmas_f32 v231, v231, v232, v192
	v_div_fixup_f32 v230, v231, v230, v175
	v_mul_f32_e32 v167, v167, v230
	v_fmac_f32_e32 v159, v167, v167
	ds_write_b128 v225, v[164:167] offset:6144
	v_fma_f32 v168, v144, v128, v120
	v_fma_f32 v169, v145, v129, v121
	v_fma_f32 v170, v146, v130, v122
	v_fma_f32 v171, v147, v131, v123
	v_fma_f32 v168, v152, v136, v168
	v_fma_f32 v169, v153, v137, v169
	v_fma_f32 v170, v154, v138, v170
	v_fma_f32 v171, v155, v139, v171
	v_mul_f32_e32 v227, 0xbfb8aa3b, v176
	v_mul_f32_e32 v228, 0xbfb8aa3b, v177
	v_mul_f32_e32 v229, 0xbfb8aa3b, v178
	v_mul_f32_e32 v230, 0xbfb8aa3b, v179
	v_exp_f32_e32 v227, v227
	v_exp_f32_e32 v228, v228
	v_exp_f32_e32 v229, v229
	v_exp_f32_e32 v230, v230
	s_nop 0
	v_add_f32_e32 v227, 1.0, v227
	v_add_f32_e32 v228, 1.0, v228
	v_add_f32_e32 v229, 1.0, v229
	v_add_f32_e32 v230, 1.0, v230
	v_div_scale_f32 v231, s[100:101], v227, v227, v176
	v_rcp_f32_e32 v232, v231
	s_nop 0
	v_fma_f32 v233, -v231, v232, 1.0
	v_fmac_f32_e32 v232, v233, v232
	v_div_scale_f32 v233, vcc, v176, v227, v176
	v_mul_f32_e32 v192, v233, v232
	v_fma_f32 v193, -v231, v192, v233
	v_fmac_f32_e32 v192, v193, v232
	v_fma_f32 v231, -v231, v192, v233
	v_div_fmas_f32 v231, v231, v232, v192
	v_div_fixup_f32 v227, v231, v227, v176
	v_mul_f32_e32 v168, v168, v227
	v_fmac_f32_e32 v160, v168, v168
	v_div_scale_f32 v231, s[100:101], v228, v228, v177
	v_rcp_f32_e32 v232, v231
	s_nop 0
	v_fma_f32 v233, -v231, v232, 1.0
	v_fmac_f32_e32 v232, v233, v232
	v_div_scale_f32 v233, vcc, v177, v228, v177
	v_mul_f32_e32 v192, v233, v232
	v_fma_f32 v193, -v231, v192, v233
	v_fmac_f32_e32 v192, v193, v232
	v_fma_f32 v231, -v231, v192, v233
	v_div_fmas_f32 v231, v231, v232, v192
	v_div_fixup_f32 v228, v231, v228, v177
	v_mul_f32_e32 v169, v169, v228
	v_fmac_f32_e32 v161, v169, v169
	v_div_scale_f32 v231, s[100:101], v229, v229, v178
	v_rcp_f32_e32 v232, v231
	s_nop 0
	v_fma_f32 v233, -v231, v232, 1.0
	v_fmac_f32_e32 v232, v233, v232
	v_div_scale_f32 v233, vcc, v178, v229, v178
	v_mul_f32_e32 v192, v233, v232
	v_fma_f32 v193, -v231, v192, v233
	v_fmac_f32_e32 v192, v193, v232
	v_fma_f32 v231, -v231, v192, v233
	v_div_fmas_f32 v231, v231, v232, v192
	v_div_fixup_f32 v229, v231, v229, v178
	v_mul_f32_e32 v170, v170, v229
	v_fmac_f32_e32 v162, v170, v170
	v_div_scale_f32 v231, s[100:101], v230, v230, v179
	v_rcp_f32_e32 v232, v231
	s_nop 0
	v_fma_f32 v233, -v231, v232, 1.0
	v_fmac_f32_e32 v232, v233, v232
	v_div_scale_f32 v233, vcc, v179, v230, v179
	v_mul_f32_e32 v192, v233, v232
	v_fma_f32 v193, -v231, v192, v233
	v_fmac_f32_e32 v192, v193, v232
	v_fma_f32 v231, -v231, v192, v233
	v_div_fmas_f32 v231, v231, v232, v192
	v_div_fixup_f32 v230, v231, v230, v179
	v_mul_f32_e32 v171, v171, v230
	v_fmac_f32_e32 v163, v171, v171
	ds_write_b128 v225, v[168:171] offset:7168
	v_add_f32_dpp v156, v156, v156 row_ror:1 row_mask:0xf bank_mask:0xf
	v_add_f32_dpp v157, v157, v157 row_ror:1 row_mask:0xf bank_mask:0xf
	v_add_f32_dpp v158, v158, v158 row_ror:1 row_mask:0xf bank_mask:0xf
	v_add_f32_dpp v159, v159, v159 row_ror:1 row_mask:0xf bank_mask:0xf
	v_add_f32_dpp v160, v160, v160 row_ror:1 row_mask:0xf bank_mask:0xf
	v_add_f32_dpp v161, v161, v161 row_ror:1 row_mask:0xf bank_mask:0xf
	v_add_f32_dpp v162, v162, v162 row_ror:1 row_mask:0xf bank_mask:0xf
	v_add_f32_dpp v163, v163, v163 row_ror:1 row_mask:0xf bank_mask:0xf
	s_nop 1
	v_add_f32_dpp v156, v156, v156 row_ror:2 row_mask:0xf bank_mask:0xf
	v_add_f32_dpp v157, v157, v157 row_ror:2 row_mask:0xf bank_mask:0xf
	v_add_f32_dpp v158, v158, v158 row_ror:2 row_mask:0xf bank_mask:0xf
	v_add_f32_dpp v159, v159, v159 row_ror:2 row_mask:0xf bank_mask:0xf
	v_add_f32_dpp v160, v160, v160 row_ror:2 row_mask:0xf bank_mask:0xf
	v_add_f32_dpp v161, v161, v161 row_ror:2 row_mask:0xf bank_mask:0xf
	v_add_f32_dpp v162, v162, v162 row_ror:2 row_mask:0xf bank_mask:0xf
	v_add_f32_dpp v163, v163, v163 row_ror:2 row_mask:0xf bank_mask:0xf
	s_nop 1
	v_add_f32_dpp v156, v156, v156 row_ror:4 row_mask:0xf bank_mask:0xf
	v_add_f32_dpp v157, v157, v157 row_ror:4 row_mask:0xf bank_mask:0xf
	v_add_f32_dpp v158, v158, v158 row_ror:4 row_mask:0xf bank_mask:0xf
	v_add_f32_dpp v159, v159, v159 row_ror:4 row_mask:0xf bank_mask:0xf
	v_add_f32_dpp v160, v160, v160 row_ror:4 row_mask:0xf bank_mask:0xf
	v_add_f32_dpp v161, v161, v161 row_ror:4 row_mask:0xf bank_mask:0xf
	v_add_f32_dpp v162, v162, v162 row_ror:4 row_mask:0xf bank_mask:0xf
	v_add_f32_dpp v163, v163, v163 row_ror:4 row_mask:0xf bank_mask:0xf
	s_nop 1
	v_add_f32_dpp v156, v156, v156 row_ror:8 row_mask:0xf bank_mask:0xf
	v_add_f32_dpp v157, v157, v157 row_ror:8 row_mask:0xf bank_mask:0xf
	v_add_f32_dpp v158, v158, v158 row_ror:8 row_mask:0xf bank_mask:0xf
	v_add_f32_dpp v159, v159, v159 row_ror:8 row_mask:0xf bank_mask:0xf
	v_add_f32_dpp v160, v160, v160 row_ror:8 row_mask:0xf bank_mask:0xf
	v_add_f32_dpp v161, v161, v161 row_ror:8 row_mask:0xf bank_mask:0xf
	v_add_f32_dpp v162, v162, v162 row_ror:8 row_mask:0xf bank_mask:0xf
	v_add_f32_dpp v163, v163, v163 row_ror:8 row_mask:0xf bank_mask:0xf
	s_nop 1
	v_cmp_eq_u32_e32 vcc, 0, v0
	s_and_saveexec_b64 s[100:101], vcc
	ds_write_b32 v226, v156 offset:0
	ds_write_b32 v226, v157 offset:32
	ds_write_b32 v226, v158 offset:64
	ds_write_b32 v226, v159 offset:96
	ds_write_b32 v226, v160 offset:512
	ds_write_b32 v226, v161 offset:544
	ds_write_b32 v226, v162 offset:576
	ds_write_b32 v226, v163 offset:608
	s_mov_b64 exec, s[100:101]
	s_waitcnt lgkmcnt(0)
	s_barrier
	s_lshl_b32 s100, s40, 2
	v_subrev_u32_e32 v232, s100, v226
	ds_read_b128 v[116:119], v232 offset:0
	ds_read_b128 v[120:123], v232 offset:16
	ds_read_b128 v[124:127], v232 offset:32
	ds_read_b128 v[128:131], v232 offset:48
	ds_read_b128 v[132:135], v232 offset:64
	ds_read_b128 v[136:139], v232 offset:80
	ds_read_b128 v[140:143], v232 offset:96
	ds_read_b128 v[144:147], v232 offset:112
	s_waitcnt lgkmcnt(0)
	v_add_f32_e32 v116, v116, v117
	v_add_f32_e32 v116, v116, v118
	v_add_f32_e32 v116, v116, v119
	v_add_f32_e32 v116, v116, v120
	v_add_f32_e32 v116, v116, v121
	v_add_f32_e32 v116, v116, v122
	v_add_f32_e32 v116, v116, v123
	v_add_f32_e32 v124, v124, v125
	v_add_f32_e32 v124, v124, v126
	v_add_f32_e32 v124, v124, v127
	v_add_f32_e32 v124, v124, v128
	v_add_f32_e32 v124, v124, v129
	v_add_f32_e32 v124, v124, v130
	v_add_f32_e32 v124, v124, v131
	v_add_f32_e32 v132, v132, v133
	v_add_f32_e32 v132, v132, v134
	v_add_f32_e32 v132, v132, v135
	v_add_f32_e32 v132, v132, v136
	v_add_f32_e32 v132, v132, v137
	v_add_f32_e32 v132, v132, v138
	v_add_f32_e32 v132, v132, v139
	v_add_f32_e32 v140, v140, v141
	v_add_f32_e32 v140, v140, v142
	v_add_f32_e32 v140, v140, v143
	v_add_f32_e32 v140, v140, v144
	v_add_f32_e32 v140, v140, v145
	v_add_f32_e32 v140, v140, v146
	v_add_f32_e32 v140, v140, v147
	v_mov_b32_e32 v233, 0x358637bd
	v_mov_b32_e32 v231, 0x3b000000
	v_fma_f32 v156, v116, v231, v233
	v_fma_f32 v157, v124, v231, v233
	v_fma_f32 v158, v132, v231, v233
	v_fma_f32 v159, v140, v231, v233
	v_rsq_f32_e32 v156, v156
	v_rsq_f32_e32 v157, v157
	v_rsq_f32_e32 v158, v158
	v_rsq_f32_e32 v159, v159
	ds_read_b128 v[116:119], v232 offset:512
	ds_read_b128 v[120:123], v232 offset:528
	ds_read_b128 v[124:127], v232 offset:544
	ds_read_b128 v[128:131], v232 offset:560
	ds_read_b128 v[132:135], v232 offset:576
	ds_read_b128 v[136:139], v232 offset:592
	ds_read_b128 v[140:143], v232 offset:608
	ds_read_b128 v[144:147], v232 offset:624
	s_waitcnt lgkmcnt(0)
	v_add_f32_e32 v116, v116, v117
	v_add_f32_e32 v116, v116, v118
	v_add_f32_e32 v116, v116, v119
	v_add_f32_e32 v116, v116, v120
	v_add_f32_e32 v116, v116, v121
	v_add_f32_e32 v116, v116, v122
	v_add_f32_e32 v116, v116, v123
	v_add_f32_e32 v124, v124, v125
	v_add_f32_e32 v124, v124, v126
	v_add_f32_e32 v124, v124, v127
	v_add_f32_e32 v124, v124, v128
	v_add_f32_e32 v124, v124, v129
	v_add_f32_e32 v124, v124, v130
	v_add_f32_e32 v124, v124, v131
	v_add_f32_e32 v132, v132, v133
	v_add_f32_e32 v132, v132, v134
	v_add_f32_e32 v132, v132, v135
	v_add_f32_e32 v132, v132, v136
	v_add_f32_e32 v132, v132, v137
	v_add_f32_e32 v132, v132, v138
	v_add_f32_e32 v132, v132, v139
	v_add_f32_e32 v140, v140, v141
	v_add_f32_e32 v140, v140, v142
	v_add_f32_e32 v140, v140, v143
	v_add_f32_e32 v140, v140, v144
	v_add_f32_e32 v140, v140, v145
	v_add_f32_e32 v140, v140, v146
	v_add_f32_e32 v140, v140, v147
	v_mov_b32_e32 v233, 0x358637bd
	v_mov_b32_e32 v231, 0x3b000000
	v_fma_f32 v160, v116, v231, v233
	v_fma_f32 v161, v124, v231, v233
	v_fma_f32 v162, v132, v231, v233
	v_fma_f32 v163, v140, v231, v233
	v_rsq_f32_e32 v160, v160
	v_rsq_f32_e32 v161, v161
	v_rsq_f32_e32 v162, v162
	v_rsq_f32_e32 v163, v163
	v_mov_b32_e32 v132, v221
	v_add_u32_e32 v133, 0x800, v221
	v_add_u32_e32 v134, 0x1000, v221
	v_add_u32_e32 v135, 0x1800, v221
	v_add_u32_e32 v136, 0x8000, v221
	v_add_u32_e32 v137, 0x8800, v221
	v_add_u32_e32 v138, 0x9000, v221
	v_add_u32_e32 v139, 0x9800, v221
	ds_read_b128 v[116:119], v225 offset:0
	ds_read_b128 v[120:123], v225 offset:1024
	s_waitcnt lgkmcnt(1)
	v_mul_f32_e32 v116, v116, v156
	v_mul_f32_e32 v116, v188, v116
	v_bfe_u32 v227, v116, 16, 1
	v_add3_u32 v116, v116, v227, s27
	global_store_short_d16_hi v132, v116, s[58:59]
	v_mul_f32_e32 v117, v117, v157
	v_mul_f32_e32 v117, v188, v117
	v_bfe_u32 v228, v117, 16, 1
	v_add3_u32 v117, v117, v228, s27
	global_store_short_d16_hi v133, v117, s[58:59]
	v_mul_f32_e32 v118, v118, v158
	v_mul_f32_e32 v118, v188, v118
	v_bfe_u32 v229, v118, 16, 1
	v_add3_u32 v118, v118, v229, s27
	global_store_short_d16_hi v134, v118, s[58:59]
	v_mul_f32_e32 v119, v119, v159
	v_mul_f32_e32 v119, v188, v119
	v_bfe_u32 v230, v119, 16, 1
	v_add3_u32 v119, v119, v230, s27
	global_store_short_d16_hi v135, v119, s[58:59]
	s_waitcnt lgkmcnt(0)
	v_mul_f32_e32 v120, v120, v160
	v_mul_f32_e32 v120, v188, v120
	v_bfe_u32 v227, v120, 16, 1
	v_add3_u32 v120, v120, v227, s27
	global_store_short_d16_hi v136, v120, s[58:59]
	v_mul_f32_e32 v121, v121, v161
	v_mul_f32_e32 v121, v188, v121
	v_bfe_u32 v228, v121, 16, 1
	v_add3_u32 v121, v121, v228, s27
	global_store_short_d16_hi v137, v121, s[58:59]
	v_mul_f32_e32 v122, v122, v162
	v_mul_f32_e32 v122, v188, v122
	v_bfe_u32 v229, v122, 16, 1
	v_add3_u32 v122, v122, v229, s27
	global_store_short_d16_hi v138, v122, s[58:59]
	v_mul_f32_e32 v123, v123, v163
	v_mul_f32_e32 v123, v188, v123
	v_bfe_u32 v230, v123, 16, 1
	v_add3_u32 v123, v123, v230, s27
	global_store_short_d16_hi v139, v123, s[58:59]
	s_nop 0
	ds_read_b128 v[116:119], v225 offset:2048
	ds_read_b128 v[120:123], v225 offset:3072
	s_waitcnt lgkmcnt(1)
	v_mul_f32_e32 v116, v116, v156
	v_mul_f32_e32 v116, v189, v116
	v_bfe_u32 v227, v116, 16, 1
	v_add3_u32 v116, v116, v227, s27
	global_store_short_d16_hi v132, v116, s[58:59] offset:32
	v_mul_f32_e32 v117, v117, v157
	v_mul_f32_e32 v117, v189, v117
	v_bfe_u32 v228, v117, 16, 1
	v_add3_u32 v117, v117, v228, s27
	global_store_short_d16_hi v133, v117, s[58:59] offset:32
	v_mul_f32_e32 v118, v118, v158
	v_mul_f32_e32 v118, v189, v118
	v_bfe_u32 v229, v118, 16, 1
	v_add3_u32 v118, v118, v229, s27
	global_store_short_d16_hi v134, v118, s[58:59] offset:32
	v_mul_f32_e32 v119, v119, v159
	v_mul_f32_e32 v119, v189, v119
	v_bfe_u32 v230, v119, 16, 1
	v_add3_u32 v119, v119, v230, s27
	global_store_short_d16_hi v135, v119, s[58:59] offset:32
	s_waitcnt lgkmcnt(0)
	v_mul_f32_e32 v120, v120, v160
	v_mul_f32_e32 v120, v189, v120
	v_bfe_u32 v227, v120, 16, 1
	v_add3_u32 v120, v120, v227, s27
	global_store_short_d16_hi v136, v120, s[58:59] offset:32
	v_mul_f32_e32 v121, v121, v161
	v_mul_f32_e32 v121, v189, v121
	v_bfe_u32 v228, v121, 16, 1
	v_add3_u32 v121, v121, v228, s27
	global_store_short_d16_hi v137, v121, s[58:59] offset:32
	v_mul_f32_e32 v122, v122, v162
	v_mul_f32_e32 v122, v189, v122
	v_bfe_u32 v229, v122, 16, 1
	v_add3_u32 v122, v122, v229, s27
	global_store_short_d16_hi v138, v122, s[58:59] offset:32
	v_mul_f32_e32 v123, v123, v163
	v_mul_f32_e32 v123, v189, v123
	v_bfe_u32 v230, v123, 16, 1
	v_add3_u32 v123, v123, v230, s27
	global_store_short_d16_hi v139, v123, s[58:59] offset:32
	s_nop 0
	ds_read_b128 v[116:119], v225 offset:4096
	ds_read_b128 v[120:123], v225 offset:5120
	s_waitcnt lgkmcnt(1)
	v_mul_f32_e32 v116, v116, v156
	v_mul_f32_e32 v116, v190, v116
	v_bfe_u32 v227, v116, 16, 1
	v_add3_u32 v116, v116, v227, s27
	global_store_short_d16_hi v132, v116, s[58:59] offset:64
	v_mul_f32_e32 v117, v117, v157
	v_mul_f32_e32 v117, v190, v117
	v_bfe_u32 v228, v117, 16, 1
	v_add3_u32 v117, v117, v228, s27
	global_store_short_d16_hi v133, v117, s[58:59] offset:64
	v_mul_f32_e32 v118, v118, v158
	v_mul_f32_e32 v118, v190, v118
	v_bfe_u32 v229, v118, 16, 1
	v_add3_u32 v118, v118, v229, s27
	global_store_short_d16_hi v134, v118, s[58:59] offset:64
	v_mul_f32_e32 v119, v119, v159
	v_mul_f32_e32 v119, v190, v119
	v_bfe_u32 v230, v119, 16, 1
	v_add3_u32 v119, v119, v230, s27
	global_store_short_d16_hi v135, v119, s[58:59] offset:64
	s_waitcnt lgkmcnt(0)
	v_mul_f32_e32 v120, v120, v160
	v_mul_f32_e32 v120, v190, v120
	v_bfe_u32 v227, v120, 16, 1
	v_add3_u32 v120, v120, v227, s27
	global_store_short_d16_hi v136, v120, s[58:59] offset:64
	v_mul_f32_e32 v121, v121, v161
	v_mul_f32_e32 v121, v190, v121
	v_bfe_u32 v228, v121, 16, 1
	v_add3_u32 v121, v121, v228, s27
	global_store_short_d16_hi v137, v121, s[58:59] offset:64
	v_mul_f32_e32 v122, v122, v162
	v_mul_f32_e32 v122, v190, v122
	v_bfe_u32 v229, v122, 16, 1
	v_add3_u32 v122, v122, v229, s27
	global_store_short_d16_hi v138, v122, s[58:59] offset:64
	v_mul_f32_e32 v123, v123, v163
	v_mul_f32_e32 v123, v190, v123
	v_bfe_u32 v230, v123, 16, 1
	v_add3_u32 v123, v123, v230, s27
	global_store_short_d16_hi v139, v123, s[58:59] offset:64
	s_nop 0
	ds_read_b128 v[116:119], v225 offset:6144
	ds_read_b128 v[120:123], v225 offset:7168
	s_waitcnt lgkmcnt(1)
	v_mul_f32_e32 v116, v116, v156
	v_mul_f32_e32 v116, v191, v116
	v_bfe_u32 v227, v116, 16, 1
	v_add3_u32 v116, v116, v227, s27
	global_store_short_d16_hi v132, v116, s[58:59] offset:96
	v_mul_f32_e32 v117, v117, v157
	v_mul_f32_e32 v117, v191, v117
	v_bfe_u32 v228, v117, 16, 1
	v_add3_u32 v117, v117, v228, s27
	global_store_short_d16_hi v133, v117, s[58:59] offset:96
	v_mul_f32_e32 v118, v118, v158
	v_mul_f32_e32 v118, v191, v118
	v_bfe_u32 v229, v118, 16, 1
	v_add3_u32 v118, v118, v229, s27
	global_store_short_d16_hi v134, v118, s[58:59] offset:96
	v_mul_f32_e32 v119, v119, v159
	v_mul_f32_e32 v119, v191, v119
	v_bfe_u32 v230, v119, 16, 1
	v_add3_u32 v119, v119, v230, s27
	global_store_short_d16_hi v135, v119, s[58:59] offset:96
	s_waitcnt lgkmcnt(0)
	v_mul_f32_e32 v120, v120, v160
	v_mul_f32_e32 v120, v191, v120
	v_bfe_u32 v227, v120, 16, 1
	v_add3_u32 v120, v120, v227, s27
	global_store_short_d16_hi v136, v120, s[58:59] offset:96
	v_mul_f32_e32 v121, v121, v161
	v_mul_f32_e32 v121, v191, v121
	v_bfe_u32 v228, v121, 16, 1
	v_add3_u32 v121, v121, v228, s27
	global_store_short_d16_hi v137, v121, s[58:59] offset:96
	v_mul_f32_e32 v122, v122, v162
	v_mul_f32_e32 v122, v191, v122
	v_bfe_u32 v229, v122, 16, 1
	v_add3_u32 v122, v122, v229, s27
	global_store_short_d16_hi v138, v122, s[58:59] offset:96
	v_mul_f32_e32 v123, v123, v163
	v_mul_f32_e32 v123, v191, v123
	v_bfe_u32 v230, v123, 16, 1
	v_add3_u32 v123, v123, v230, s27
	global_store_short_d16_hi v139, v123, s[58:59] offset:96
	s_nop 0
	s_waitcnt lgkmcnt(0)
	s_barrier
	s_branch .Lssd_back

.LBB0_334:
	ds_read_b128 v[104:107], v94 offset:27648
	ds_read_b128 v[108:111], v94 offset:27712
	ds_read_b128 v[112:115], v94 offset:29952
	ds_read_b128 v[128:131], v94 offset:30016
	ds_read_b128 v[132:135], v94 offset:32256
	ds_read_b128 v[136:139], v94 offset:32320
	ds_read_b128 v[140:143], v103
	ds_read_b128 v[144:147], v103 offset:64
	ds_read_b128 v[148:151], v103 offset:2304
	ds_read_b128 v[152:155], v103 offset:2368
	ds_read_b128 v[156:159], v103 offset:4608
	ds_read_b128 v[160:163], v103 offset:4672
	ds_read_b128 v[164:167], v103 offset:6912
	ds_read_b128 v[168:171], v103 offset:6976
	s_setprio 1
	s_waitcnt lgkmcnt(7)
	v_mfma_f32_16x16x32_bf16 v[88:91], v[104:107], v[140:143], v[88:91]
	v_mfma_f32_16x16x32_bf16 v[72:75], v[112:115], v[140:143], v[72:75]
	v_mfma_f32_16x16x32_bf16 v[56:59], v[132:135], v[140:143], v[56:59]
	s_waitcnt lgkmcnt(5)
	v_mfma_f32_16x16x32_bf16 v[84:87], v[104:107], v[148:151], v[84:87]
	v_mfma_f32_16x16x32_bf16 v[68:71], v[112:115], v[148:151], v[68:71]
	v_mfma_f32_16x16x32_bf16 v[52:55], v[132:135], v[148:151], v[52:55]
	s_waitcnt lgkmcnt(3)
	v_mfma_f32_16x16x32_bf16 v[80:83], v[104:107], v[156:159], v[80:83]
	v_mfma_f32_16x16x32_bf16 v[64:67], v[112:115], v[156:159], v[64:67]
	v_mfma_f32_16x16x32_bf16 v[48:51], v[132:135], v[156:159], v[48:51]
	s_waitcnt lgkmcnt(1)
	v_mfma_f32_16x16x32_bf16 v[76:79], v[104:107], v[164:167], v[76:79]
	v_mfma_f32_16x16x32_bf16 v[60:63], v[112:115], v[164:167], v[60:63]
	v_mfma_f32_16x16x32_bf16 v[44:47], v[132:135], v[164:167], v[44:47]
	v_mfma_f32_16x16x32_bf16 v[88:91], v[108:111], v[144:147], v[88:91]
	v_mfma_f32_16x16x32_bf16 v[72:75], v[128:131], v[144:147], v[72:75]
	v_mfma_f32_16x16x32_bf16 v[56:59], v[136:139], v[144:147], v[56:59]
	v_mfma_f32_16x16x32_bf16 v[84:87], v[108:111], v[152:155], v[84:87]
	v_mfma_f32_16x16x32_bf16 v[68:71], v[128:131], v[152:155], v[68:71]
	v_mfma_f32_16x16x32_bf16 v[52:55], v[136:139], v[152:155], v[52:55]
	v_mfma_f32_16x16x32_bf16 v[80:83], v[108:111], v[160:163], v[80:83]
	v_mfma_f32_16x16x32_bf16 v[64:67], v[128:131], v[160:163], v[64:67]
	v_mfma_f32_16x16x32_bf16 v[48:51], v[136:139], v[160:163], v[48:51]
	s_waitcnt lgkmcnt(0)
	v_mfma_f32_16x16x32_bf16 v[76:79], v[108:111], v[168:171], v[76:79]
	v_mfma_f32_16x16x32_bf16 v[60:63], v[128:131], v[168:171], v[60:63]
	v_mfma_f32_16x16x32_bf16 v[44:47], v[136:139], v[168:171], v[44:47]
	s_setprio 0
	s_and_b32 s40, s45, 3
	s_cmp_lg_u32 s40, 3
	s_cbranch_scc1 .LBB0_323
	s_lshr_b32 s40, s44, 2
	v_cmp_eq_u32_e64 s[46:47], 1, v96
	s_mul_i32 s40, s40, s9
	v_cmp_eq_u32_e64 s[48:49], 2, v96
	v_cndmask_b32_e64 v104, v88, v89, s[46:47]
	s_add_i32 s40, s40, s8
	v_cndmask_b32_e64 v104, v104, v90, s[48:49]
	v_cmp_eq_u32_e64 s[50:51], 3, v96
	s_and_b32 s41, s40, 31
	s_lshl_b32 s40, s40, 2
	v_cndmask_b32_e64 v104, v104, v91, s[50:51]
	v_cmp_eq_u32_e64 s[52:53], 1, v98
	s_and_b32 s40, s40, 0xffffff80
	ds_bpermute_b32 v110, v119, v104
	v_cndmask_b32_e64 v104, v88, v89, s[52:53]
	v_cmp_eq_u32_e64 s[54:55], 2, v98
	v_cmp_eq_u32_e64 s[56:57], 3, v98
	v_or_b32_e32 v112, s40, v120
	v_cndmask_b32_e64 v104, v104, v90, s[54:55]
	v_cndmask_b32_e64 v104, v104, v91, s[56:57]
	v_ashrrev_i32_e32 v113, 31, v112
	ds_bpermute_b32 v130, v119, v104
	v_lshl_add_u64 v[104:105], v[112:113], 2, s[10:11]
	global_load_dwordx2 v[116:117], v[104:105], off
	v_cmp_eq_u32_e64 s[58:59], 1, v100
	v_cmp_eq_u32_e64 s[60:61], 2, v100
	s_mulk_i32 s41, 0xc0
	v_cndmask_b32_e64 v111, v88, v89, s[58:59]
	v_cndmask_b32_e64 v111, v111, v90, s[60:61]
	v_cmp_eq_u32_e64 s[94:95], 3, v100
	v_or_b32_e32 v127, s41, v118
	v_lshlrev_b64 v[106:107], 1, v[112:113]
	v_cndmask_b32_e64 v111, v111, v91, s[94:95]
	v_readlane_b32 s6, v236, 25
	s_waitcnt lgkmcnt(1)
	v_cndmask_b32_e64 v113, v110, v111, s[38:39]
	v_cndmask_b32_e64 v131, v111, v110, s[38:39]
	v_add_u32_e32 v110, v127, v121
	v_readlane_b32 s7, v236, 26
	v_ashrrev_i32_e32 v111, 31, v110
	v_lshlrev_b64 v[114:115], 9, v[110:111]
	v_lshl_add_u64 v[108:109], s[6:7], 0, v[106:107]
	v_lshl_add_u64 v[128:129], v[108:109], 0, v[114:115]
	global_load_dword v128, v[128:129], off
	v_readlane_b32 s4, v236, 23
	v_lshlrev_b64 v[110:111], 11, v[110:111]
	v_readlane_b32 s5, v236, 24
	v_cmp_eq_u32_e64 s[12:13], 1, v102
	v_cmp_eq_u32_e64 s[44:45], 3, v102
	v_lshl_add_u64 v[110:111], s[4:5], 0, v[110:111]
	v_lshl_add_u64 v[110:111], v[110:111], 0, v[106:107]
	v_cndmask_b32_e64 v88, v88, v89, s[12:13]
	v_lshl_add_u64 v[114:115], s[6:7], 0, v[114:115]
	s_waitcnt vmcnt(1)
	v_add_f32_e32 v113, v113, v116
	v_mul_f32_e32 v113, 0xbfb8aa3b, v113
	v_exp_f32_e32 v113, v113
	s_waitcnt vmcnt(0)
	v_lshlrev_b32_e32 v129, 16, v128
	v_add_f32_e32 v113, 1.0, v113
	v_div_scale_f32 v116, s[40:41], v113, v113, 1.0
	v_rcp_f32_e32 v132, v116
	v_and_b32_e32 v128, 0xffff0000, v128
	v_fma_f32 v133, -v116, v132, 1.0
	v_fmac_f32_e32 v132, v133, v132
	v_div_scale_f32 v133, vcc, 1.0, v113, 1.0
	v_mul_f32_e32 v134, v133, v132
	v_fma_f32 v135, -v116, v134, v133
	v_fmac_f32_e32 v134, v135, v132
	v_fma_f32 v116, -v116, v134, v133
	v_div_fmas_f32 v116, v116, v132, v134
	v_div_fixup_f32 v113, v116, v113, 1.0
	v_add_f32_e32 v116, v131, v117
	v_mul_f32_e32 v116, 0xbfb8aa3b, v116
	v_exp_f32_e32 v116, v116
	v_mul_f32_e32 v113, v113, v129
	v_add_f32_e32 v116, 1.0, v116
	v_div_scale_f32 v117, s[40:41], v116, v116, 1.0
	v_rcp_f32_e32 v129, v117
	v_cmp_eq_u32_e64 s[40:41], 2, v102
	v_fma_f32 v131, -v117, v129, 1.0
	v_fmac_f32_e32 v129, v131, v129
	v_div_scale_f32 v131, vcc, 1.0, v116, 1.0
	v_mul_f32_e32 v132, v131, v129
	v_fma_f32 v133, -v117, v132, v131
	v_fmac_f32_e32 v132, v133, v129
	v_fma_f32 v117, -v117, v132, v131
	v_div_fmas_f32 v117, v117, v129, v132
	v_div_fixup_f32 v116, v117, v116, 1.0
	v_mul_f32_e32 v116, v116, v128
	v_bfe_u32 v117, v113, 16, 1
	v_add3_u32 v113, v113, v117, s27
	v_bfe_u32 v117, v116, 16, 1
	v_lshrrev_b32_e32 v113, 16, v113
	v_add3_u32 v116, v116, v117, s27
	v_and_or_b32 v113, v116, s28, v113
	global_store_dword v[110:111], v113, off offset:1536
	v_cndmask_b32_e64 v88, v88, v90, s[40:41]
	v_cndmask_b32_e64 v88, v88, v91, s[44:45]
	global_load_dwordx2 v[90:91], v[104:105], off
	s_waitcnt lgkmcnt(0)
	v_cndmask_b32_e64 v113, v130, v88, s[38:39]
	v_cndmask_b32_e64 v130, v88, v130, s[38:39]
	v_add_u32_e32 v88, v122, v127
	v_ashrrev_i32_e32 v89, 31, v88
	v_lshlrev_b64 v[116:117], 9, v[88:89]
	v_lshl_add_u64 v[128:129], v[108:109], 0, v[116:117]
	global_load_dword v128, v[128:129], off
	v_lshlrev_b64 v[88:89], 11, v[88:89]
	v_lshl_add_u64 v[88:89], s[4:5], 0, v[88:89]
	s_waitcnt vmcnt(1)
	v_add_f32_e32 v90, v113, v90
	v_mul_f32_e32 v90, 0xbfb8aa3b, v90
	v_exp_f32_e32 v90, v90
	v_add_f32_e32 v91, v130, v91
	v_mul_f32_e32 v91, 0xbfb8aa3b, v91
	v_exp_f32_e32 v91, v91
	v_add_f32_e32 v90, 1.0, v90
	v_div_scale_f32 v113, vcc, v90, v90, 1.0
	v_rcp_f32_e32 v131, v113
	v_add_f32_e32 v91, 1.0, v91
	s_waitcnt vmcnt(0)
	v_lshlrev_b32_e32 v129, 16, v128
	v_and_b32_e32 v128, 0xffff0000, v128
	v_fma_f32 v132, -v113, v131, 1.0
	v_fmac_f32_e32 v131, v132, v131
	v_div_scale_f32 v132, vcc, 1.0, v90, 1.0
	v_mul_f32_e32 v133, v132, v131
	v_fma_f32 v134, -v113, v133, v132
	v_fmac_f32_e32 v133, v134, v131
	v_fma_f32 v113, -v113, v133, v132
	v_div_fmas_f32 v113, v113, v131, v133
	v_div_fixup_f32 v90, v113, v90, 1.0
	v_div_scale_f32 v113, vcc, v91, v91, 1.0
	v_mul_f32_e32 v90, v90, v129
	v_rcp_f32_e32 v129, v113
	s_nop 0
	v_fma_f32 v130, -v113, v129, 1.0
	v_fmac_f32_e32 v129, v130, v129
	v_div_scale_f32 v130, vcc, 1.0, v91, 1.0
	v_mul_f32_e32 v131, v130, v129
	v_fma_f32 v132, -v113, v131, v130
	v_fmac_f32_e32 v131, v132, v129
	v_fma_f32 v113, -v113, v131, v130
	v_div_fmas_f32 v113, v113, v129, v131
	v_div_fixup_f32 v91, v113, v91, 1.0
	v_mul_f32_e32 v91, v91, v128
	v_bfe_u32 v113, v90, 16, 1
	v_add3_u32 v90, v90, v113, s27
	v_bfe_u32 v113, v91, 16, 1
	v_lshrrev_b32_e32 v90, 16, v90
	v_add3_u32 v91, v91, v113, s27
	v_and_or_b32 v113, v91, s28, v90
	v_lshl_add_u64 v[90:91], v[88:89], 0, v[106:107]
	v_cndmask_b32_e64 v88, v84, v85, s[46:47]
	v_cndmask_b32_e64 v88, v88, v86, s[48:49]
	v_cndmask_b32_e64 v88, v88, v87, s[50:51]
	global_store_dword v[90:91], v113, off offset:1536
	ds_bpermute_b32 v113, v119, v88
	v_cndmask_b32_e64 v128, v84, v85, s[58:59]
	v_cndmask_b32_e64 v128, v128, v86, s[60:61]
	v_cndmask_b32_e64 v128, v128, v87, s[94:95]
	v_cndmask_b32_e64 v88, v84, v85, s[52:53]
	s_waitcnt lgkmcnt(0)
	v_cndmask_b32_e64 v133, v113, v128, s[38:39]
	v_cndmask_b32_e64 v113, v128, v113, s[38:39]
	global_load_dwordx2 v[128:129], v[104:105], off offset:64
	v_cndmask_b32_e64 v88, v88, v86, s[54:55]
	v_cndmask_b32_e64 v88, v88, v87, s[56:57]
	ds_bpermute_b32 v132, v119, v88
	v_or_b32_e32 v88, 16, v112
	v_ashrrev_i32_e32 v89, 31, v88
	v_lshlrev_b64 v[88:89], 1, v[88:89]
	v_lshl_add_u64 v[130:131], v[114:115], 0, v[88:89]
	global_load_dword v130, v[130:131], off
	v_cndmask_b32_e64 v84, v84, v85, s[12:13]
	v_cndmask_b32_e64 v84, v84, v86, s[40:41]
	v_cndmask_b32_e64 v84, v84, v87, s[44:45]
	v_lshl_add_u64 v[86:87], s[6:7], 0, v[116:117]
	v_lshl_add_u64 v[116:117], v[86:87], 0, v[88:89]
	s_waitcnt vmcnt(1)
	v_add_f32_e32 v128, v133, v128
	v_mul_f32_e32 v128, 0xbfb8aa3b, v128
	v_exp_f32_e32 v128, v128
	v_add_f32_e32 v113, v113, v129
	v_mul_f32_e32 v113, 0xbfb8aa3b, v113
	v_exp_f32_e32 v113, v113
	v_add_f32_e32 v128, 1.0, v128
	v_div_scale_f32 v133, vcc, v128, v128, 1.0
	v_rcp_f32_e32 v134, v133
	v_add_f32_e32 v113, 1.0, v113
	s_waitcnt vmcnt(0)
	v_lshlrev_b32_e32 v131, 16, v130
	v_and_b32_e32 v130, 0xffff0000, v130
	v_fma_f32 v135, -v133, v134, 1.0
	v_fmac_f32_e32 v134, v135, v134
	v_div_scale_f32 v135, vcc, 1.0, v128, 1.0
	v_mul_f32_e32 v136, v135, v134
	v_fma_f32 v137, -v133, v136, v135
	v_fmac_f32_e32 v136, v137, v134
	v_fma_f32 v133, -v133, v136, v135
	v_div_fmas_f32 v133, v133, v134, v136
	v_div_fixup_f32 v128, v133, v128, 1.0
	v_div_scale_f32 v129, vcc, v113, v113, 1.0
	v_mul_f32_e32 v128, v128, v131
	v_rcp_f32_e32 v131, v129
	s_nop 0
	v_fma_f32 v133, -v129, v131, 1.0
	v_fmac_f32_e32 v131, v133, v131
	v_div_scale_f32 v133, vcc, 1.0, v113, 1.0
	v_mul_f32_e32 v134, v133, v131
	v_fma_f32 v135, -v129, v134, v133
	v_fmac_f32_e32 v134, v135, v131
	v_fma_f32 v129, -v129, v134, v133
	v_div_fmas_f32 v129, v129, v131, v134
	v_div_fixup_f32 v113, v129, v113, 1.0
	v_mul_f32_e32 v113, v113, v130
	v_bfe_u32 v129, v128, 16, 1
	v_add3_u32 v128, v128, v129, s27
	v_bfe_u32 v129, v113, 16, 1
	v_lshrrev_b32_e32 v128, 16, v128
	v_add3_u32 v113, v113, v129, s27
	v_and_or_b32 v113, v113, s28, v128
	global_store_dword v[110:111], v113, off offset:1568
	s_waitcnt lgkmcnt(0)
	v_cndmask_b32_e64 v113, v132, v84, s[38:39]
	v_cndmask_b32_e64 v128, v84, v132, s[38:39]
	global_load_dwordx2 v[84:85], v[104:105], off offset:64
	s_waitcnt vmcnt(0)
	v_add_f32_e32 v84, v113, v84
	global_load_dword v116, v[116:117], off
	v_mul_f32_e32 v84, 0xbfb8aa3b, v84
	v_exp_f32_e32 v84, v84
	v_add_f32_e32 v85, v128, v85
	v_mul_f32_e32 v85, 0xbfb8aa3b, v85
	v_exp_f32_e32 v85, v85
	v_add_f32_e32 v84, 1.0, v84
	v_div_scale_f32 v113, vcc, v84, v84, 1.0
	v_rcp_f32_e32 v129, v113
	v_add_f32_e32 v85, 1.0, v85
	v_fma_f32 v130, -v113, v129, 1.0
	v_fmac_f32_e32 v129, v130, v129
	v_div_scale_f32 v130, vcc, 1.0, v84, 1.0
	v_mul_f32_e32 v131, v130, v129
	v_fma_f32 v132, -v113, v131, v130
	v_fmac_f32_e32 v131, v132, v129
	v_fma_f32 v113, -v113, v131, v130
	v_div_fmas_f32 v113, v113, v129, v131
	v_div_fixup_f32 v84, v113, v84, 1.0
	v_div_scale_f32 v113, vcc, v85, v85, 1.0
	s_waitcnt vmcnt(0)
	v_lshlrev_b32_e32 v117, 16, v116
	v_mul_f32_e32 v84, v84, v117
	v_rcp_f32_e32 v117, v113
	v_and_b32_e32 v116, 0xffff0000, v116
	v_fma_f32 v128, -v113, v117, 1.0
	v_fmac_f32_e32 v117, v128, v117
	v_div_scale_f32 v128, vcc, 1.0, v85, 1.0
	v_mul_f32_e32 v129, v128, v117
	v_fma_f32 v130, -v113, v129, v128
	v_fmac_f32_e32 v129, v130, v117
	v_fma_f32 v113, -v113, v129, v128
	v_div_fmas_f32 v113, v113, v117, v129
	v_div_fixup_f32 v85, v113, v85, 1.0
	v_mul_f32_e32 v85, v85, v116
	v_bfe_u32 v113, v84, 16, 1
	v_add3_u32 v84, v84, v113, s27
	v_bfe_u32 v113, v85, 16, 1
	v_lshrrev_b32_e32 v84, 16, v84
	v_add3_u32 v85, v85, v113, s27
	v_and_or_b32 v84, v85, s28, v84
	global_store_dword v[90:91], v84, off offset:1568
	v_cndmask_b32_e64 v84, v80, v81, s[46:47]
	v_cndmask_b32_e64 v84, v84, v82, s[48:49]
	v_cndmask_b32_e64 v84, v84, v83, s[50:51]
	ds_bpermute_b32 v113, v119, v84
	v_cndmask_b32_e64 v116, v80, v81, s[58:59]
	v_cndmask_b32_e64 v116, v116, v82, s[60:61]
	v_cndmask_b32_e64 v116, v116, v83, s[94:95]
	v_cndmask_b32_e64 v84, v80, v81, s[52:53]
	s_waitcnt lgkmcnt(0)
	v_cndmask_b32_e64 v131, v113, v116, s[38:39]
	v_cndmask_b32_e64 v113, v116, v113, s[38:39]
	global_load_dwordx2 v[116:117], v[104:105], off offset:128
	v_cndmask_b32_e64 v84, v84, v82, s[54:55]
	v_cndmask_b32_e64 v84, v84, v83, s[56:57]
	ds_bpermute_b32 v130, v119, v84
	v_or_b32_e32 v84, 32, v112
	v_ashrrev_i32_e32 v85, 31, v84
	v_lshlrev_b64 v[84:85], 1, v[84:85]
	v_lshl_add_u64 v[128:129], v[114:115], 0, v[84:85]
	global_load_dword v128, v[128:129], off
	v_cndmask_b32_e64 v80, v80, v81, s[12:13]
	v_cndmask_b32_e64 v80, v80, v82, s[40:41]
	v_cndmask_b32_e64 v80, v80, v83, s[44:45]
	v_lshl_add_u64 v[82:83], v[86:87], 0, v[84:85]
	s_waitcnt vmcnt(1)
	v_add_f32_e32 v116, v131, v116
	v_mul_f32_e32 v116, 0xbfb8aa3b, v116
	v_exp_f32_e32 v116, v116
	v_add_f32_e32 v113, v113, v117
	v_mul_f32_e32 v113, 0xbfb8aa3b, v113
	v_exp_f32_e32 v113, v113
	v_add_f32_e32 v116, 1.0, v116
	v_div_scale_f32 v131, vcc, v116, v116, 1.0
	v_rcp_f32_e32 v132, v131
	v_add_f32_e32 v113, 1.0, v113
	s_waitcnt vmcnt(0)
	v_lshlrev_b32_e32 v129, 16, v128
	v_and_b32_e32 v128, 0xffff0000, v128
	v_fma_f32 v133, -v131, v132, 1.0
	v_fmac_f32_e32 v132, v133, v132
	v_div_scale_f32 v133, vcc, 1.0, v116, 1.0
	v_mul_f32_e32 v134, v133, v132
	v_fma_f32 v135, -v131, v134, v133
	v_fmac_f32_e32 v134, v135, v132
	v_fma_f32 v131, -v131, v134, v133
	v_div_fmas_f32 v131, v131, v132, v134
	v_div_fixup_f32 v116, v131, v116, 1.0
	v_div_scale_f32 v117, vcc, v113, v113, 1.0
	v_mul_f32_e32 v116, v116, v129
	v_rcp_f32_e32 v129, v117
	s_nop 0
	v_fma_f32 v131, -v117, v129, 1.0
	v_fmac_f32_e32 v129, v131, v129
	v_div_scale_f32 v131, vcc, 1.0, v113, 1.0
	v_mul_f32_e32 v132, v131, v129
	v_fma_f32 v133, -v117, v132, v131
	v_fmac_f32_e32 v132, v133, v129
	v_fma_f32 v117, -v117, v132, v131
	v_div_fmas_f32 v117, v117, v129, v132
	v_div_fixup_f32 v113, v117, v113, 1.0
	v_mul_f32_e32 v113, v113, v128
	v_bfe_u32 v117, v116, 16, 1
	v_add3_u32 v116, v116, v117, s27
	v_bfe_u32 v117, v113, 16, 1
	v_lshrrev_b32_e32 v116, 16, v116
	v_add3_u32 v113, v113, v117, s27
	v_and_or_b32 v113, v113, s28, v116
	global_store_dword v[110:111], v113, off offset:1600
	s_waitcnt lgkmcnt(0)
	v_cndmask_b32_e64 v113, v130, v80, s[38:39]
	v_cndmask_b32_e64 v116, v80, v130, s[38:39]
	global_load_dwordx2 v[80:81], v[104:105], off offset:128
	s_waitcnt vmcnt(0)
	v_add_f32_e32 v80, v113, v80
	global_load_dword v82, v[82:83], off
	v_mul_f32_e32 v80, 0xbfb8aa3b, v80
	v_exp_f32_e32 v80, v80
	v_add_f32_e32 v81, v116, v81
	v_mul_f32_e32 v81, 0xbfb8aa3b, v81
	v_exp_f32_e32 v81, v81
	v_add_f32_e32 v80, 1.0, v80
	v_div_scale_f32 v113, vcc, v80, v80, 1.0
	v_rcp_f32_e32 v117, v113
	v_add_f32_e32 v81, 1.0, v81
	v_fma_f32 v128, -v113, v117, 1.0
	v_fmac_f32_e32 v117, v128, v117
	v_div_scale_f32 v128, vcc, 1.0, v80, 1.0
	v_mul_f32_e32 v129, v128, v117
	v_fma_f32 v130, -v113, v129, v128
	v_fmac_f32_e32 v129, v130, v117
	v_fma_f32 v113, -v113, v129, v128
	v_div_fmas_f32 v113, v113, v117, v129
	v_div_fixup_f32 v80, v113, v80, 1.0
	s_waitcnt vmcnt(0)
	v_lshlrev_b32_e32 v83, 16, v82
	v_mul_f32_e32 v80, v80, v83
	v_div_scale_f32 v83, vcc, v81, v81, 1.0
	v_rcp_f32_e32 v113, v83
	v_and_b32_e32 v82, 0xffff0000, v82
	v_fma_f32 v116, -v83, v113, 1.0
	v_fmac_f32_e32 v113, v116, v113
	v_div_scale_f32 v116, vcc, 1.0, v81, 1.0
	v_mul_f32_e32 v117, v116, v113
	v_fma_f32 v128, -v83, v117, v116
	v_fmac_f32_e32 v117, v128, v113
	v_fma_f32 v83, -v83, v117, v116
	v_div_fmas_f32 v83, v83, v113, v117
	v_div_fixup_f32 v81, v83, v81, 1.0
	v_mul_f32_e32 v81, v81, v82
	v_bfe_u32 v82, v80, 16, 1
	v_add3_u32 v80, v80, v82, s27
	v_bfe_u32 v82, v81, 16, 1
	v_lshrrev_b32_e32 v80, 16, v80
	v_add3_u32 v81, v81, v82, s27
	v_and_or_b32 v80, v81, s28, v80
	global_store_dword v[90:91], v80, off offset:1600
	v_cndmask_b32_e64 v80, v76, v77, s[46:47]
	v_cndmask_b32_e64 v80, v80, v78, s[48:49]
	v_cndmask_b32_e64 v80, v80, v79, s[50:51]
	ds_bpermute_b32 v82, v119, v80
	v_cndmask_b32_e64 v80, v76, v77, s[52:53]
	v_cndmask_b32_e64 v83, v76, v77, s[58:59]
	v_cndmask_b32_e64 v80, v80, v78, s[54:55]
	v_cndmask_b32_e64 v83, v83, v78, s[60:61]
	v_cndmask_b32_e64 v80, v80, v79, s[56:57]
	v_cndmask_b32_e64 v83, v83, v79, s[94:95]
	ds_bpermute_b32 v113, v119, v80
	v_or_b32_e32 v80, 48, v112
	s_waitcnt lgkmcnt(1)
	v_cndmask_b32_e64 v112, v82, v83, s[38:39]
	v_cndmask_b32_e64 v116, v83, v82, s[38:39]
	global_load_dwordx2 v[82:83], v[104:105], off offset:192
	v_ashrrev_i32_e32 v81, 31, v80
	v_lshlrev_b64 v[80:81], 1, v[80:81]
	v_lshl_add_u64 v[114:115], v[114:115], 0, v[80:81]
	global_load_dword v114, v[114:115], off
	v_cndmask_b32_e64 v76, v76, v77, s[12:13]
	v_cndmask_b32_e64 v76, v76, v78, s[40:41]
	v_cndmask_b32_e64 v76, v76, v79, s[44:45]
	v_lshl_add_u64 v[78:79], v[86:87], 0, v[80:81]
	s_waitcnt vmcnt(1)
	v_add_f32_e32 v82, v112, v82
	v_mul_f32_e32 v82, 0xbfb8aa3b, v82
	v_exp_f32_e32 v82, v82
	v_add_f32_e32 v83, v116, v83
	v_mul_f32_e32 v83, 0xbfb8aa3b, v83
	v_exp_f32_e32 v83, v83
	v_add_f32_e32 v82, 1.0, v82
	v_div_scale_f32 v112, vcc, v82, v82, 1.0
	v_rcp_f32_e32 v117, v112
	v_add_f32_e32 v83, 1.0, v83
	s_waitcnt vmcnt(0)
	v_lshlrev_b32_e32 v115, 16, v114
	v_and_b32_e32 v114, 0xffff0000, v114
	v_fma_f32 v128, -v112, v117, 1.0
	v_fmac_f32_e32 v117, v128, v117
	v_div_scale_f32 v128, vcc, 1.0, v82, 1.0
	v_mul_f32_e32 v129, v128, v117
	v_fma_f32 v130, -v112, v129, v128
	v_fmac_f32_e32 v129, v130, v117
	v_fma_f32 v112, -v112, v129, v128
	v_div_fmas_f32 v112, v112, v117, v129
	v_div_fixup_f32 v82, v112, v82, 1.0
	v_div_scale_f32 v112, vcc, v83, v83, 1.0
	v_mul_f32_e32 v82, v82, v115
	v_rcp_f32_e32 v115, v112
	s_nop 0
	v_fma_f32 v116, -v112, v115, 1.0
	v_fmac_f32_e32 v115, v116, v115
	v_div_scale_f32 v116, vcc, 1.0, v83, 1.0
	v_mul_f32_e32 v117, v116, v115
	v_fma_f32 v128, -v112, v117, v116
	v_fmac_f32_e32 v117, v128, v115
	v_fma_f32 v112, -v112, v117, v116
	v_div_fmas_f32 v112, v112, v115, v117
	v_div_fixup_f32 v83, v112, v83, 1.0
	v_mul_f32_e32 v83, v83, v114
	v_bfe_u32 v112, v82, 16, 1
	v_add3_u32 v82, v82, v112, s27
	v_bfe_u32 v112, v83, 16, 1
	v_lshrrev_b32_e32 v82, 16, v82
	v_add3_u32 v83, v83, v112, s27
	v_and_or_b32 v82, v83, s28, v82
	global_store_dword v[110:111], v82, off offset:1632
	s_waitcnt lgkmcnt(0)
	v_cndmask_b32_e64 v82, v113, v76, s[38:39]
	v_cndmask_b32_e64 v83, v76, v113, s[38:39]
	global_load_dwordx2 v[76:77], v[104:105], off offset:192
	s_waitcnt vmcnt(0)
	v_add_f32_e32 v76, v82, v76
	global_load_dword v78, v[78:79], off
	v_mul_f32_e32 v76, 0xbfb8aa3b, v76
	v_exp_f32_e32 v76, v76
	v_add_f32_e32 v77, v83, v77
	v_mul_f32_e32 v77, 0xbfb8aa3b, v77
	v_exp_f32_e32 v77, v77
	v_add_f32_e32 v76, 1.0, v76
	v_div_scale_f32 v82, vcc, v76, v76, 1.0
	v_rcp_f32_e32 v86, v82
	v_add_f32_e32 v77, 1.0, v77
	v_fma_f32 v87, -v82, v86, 1.0
	v_fmac_f32_e32 v86, v87, v86
	v_div_scale_f32 v87, vcc, 1.0, v76, 1.0
	v_mul_f32_e32 v110, v87, v86
	v_fma_f32 v111, -v82, v110, v87
	v_fmac_f32_e32 v110, v111, v86
	v_fma_f32 v82, -v82, v110, v87
	v_div_fmas_f32 v82, v82, v86, v110
	v_div_fixup_f32 v76, v82, v76, 1.0
	s_waitcnt vmcnt(0)
	v_lshlrev_b32_e32 v79, 16, v78
	v_mul_f32_e32 v76, v76, v79
	v_div_scale_f32 v79, vcc, v77, v77, 1.0
	v_rcp_f32_e32 v82, v79
	v_and_b32_e32 v78, 0xffff0000, v78
	v_fma_f32 v83, -v79, v82, 1.0
	v_fmac_f32_e32 v82, v83, v82
	v_div_scale_f32 v83, vcc, 1.0, v77, 1.0
	v_mul_f32_e32 v86, v83, v82
	v_fma_f32 v87, -v79, v86, v83
	v_fmac_f32_e32 v86, v87, v82
	v_fma_f32 v79, -v79, v86, v83
	v_div_fmas_f32 v79, v79, v82, v86
	v_div_fixup_f32 v77, v79, v77, 1.0
	v_mul_f32_e32 v77, v77, v78
	v_bfe_u32 v78, v76, 16, 1
	v_add3_u32 v76, v76, v78, s27
	v_bfe_u32 v78, v77, 16, 1
	v_lshrrev_b32_e32 v76, 16, v76
	v_add3_u32 v77, v77, v78, s27
	v_and_or_b32 v76, v77, s28, v76
	global_store_dword v[90:91], v76, off offset:1632
	global_load_dwordx2 v[82:83], v[104:105], off
	v_cndmask_b32_e64 v76, v72, v73, s[46:47]
	v_cndmask_b32_e64 v76, v76, v74, s[48:49]
	v_cndmask_b32_e64 v76, v76, v75, s[50:51]
	v_cndmask_b32_e64 v77, v72, v73, s[52:53]
	ds_bpermute_b32 v76, v119, v76
	v_cndmask_b32_e64 v77, v77, v74, s[54:55]
	v_cndmask_b32_e64 v77, v77, v75, s[56:57]
	ds_bpermute_b32 v86, v119, v77
	v_cndmask_b32_e64 v77, v72, v73, s[58:59]
	v_cndmask_b32_e64 v77, v77, v74, s[60:61]
	v_cndmask_b32_e64 v77, v77, v75, s[94:95]
	s_waitcnt lgkmcnt(1)
	v_cndmask_b32_e64 v90, v76, v77, s[38:39]
	v_cndmask_b32_e64 v87, v77, v76, s[38:39]
	v_add_u32_e32 v76, v123, v127
	v_ashrrev_i32_e32 v77, 31, v76
	v_lshlrev_b64 v[78:79], 9, v[76:77]
	v_lshl_add_u64 v[110:111], v[108:109], 0, v[78:79]
	global_load_dword v91, v[110:111], off
	v_lshlrev_b64 v[76:77], 11, v[76:77]
	v_lshl_add_u64 v[76:77], s[4:5], 0, v[76:77]
	v_lshl_add_u64 v[76:77], v[76:77], 0, v[106:107]
	v_cndmask_b32_e64 v72, v72, v73, s[12:13]
	v_cndmask_b32_e64 v72, v72, v74, s[40:41]
	v_cndmask_b32_e64 v72, v72, v75, s[44:45]
	s_waitcnt vmcnt(1)
	v_add_f32_e32 v82, v90, v82
	v_mul_f32_e32 v82, 0xbfb8aa3b, v82
	v_exp_f32_e32 v82, v82
	v_add_f32_e32 v83, v87, v83
	v_mul_f32_e32 v83, 0xbfb8aa3b, v83
	v_exp_f32_e32 v83, v83
	v_add_f32_e32 v82, 1.0, v82
	v_div_scale_f32 v90, vcc, v82, v82, 1.0
	v_rcp_f32_e32 v111, v90
	v_add_f32_e32 v83, 1.0, v83
	v_fma_f32 v112, -v90, v111, 1.0
	v_fmac_f32_e32 v111, v112, v111
	v_div_scale_f32 v112, vcc, 1.0, v82, 1.0
	v_mul_f32_e32 v113, v112, v111
	v_fma_f32 v114, -v90, v113, v112
	v_fmac_f32_e32 v113, v114, v111
	v_fma_f32 v90, -v90, v113, v112
	v_div_fmas_f32 v90, v90, v111, v113
	v_div_scale_f32 v87, vcc, v83, v83, 1.0
	v_div_fixup_f32 v82, v90, v82, 1.0
	v_rcp_f32_e32 v90, v87
	s_waitcnt vmcnt(0)
	v_lshlrev_b32_e32 v110, 16, v91
	v_mul_f32_e32 v82, v82, v110
	v_and_b32_e32 v91, 0xffff0000, v91
	v_fma_f32 v110, -v87, v90, 1.0
	v_fmac_f32_e32 v90, v110, v90
	v_div_scale_f32 v110, vcc, 1.0, v83, 1.0
	v_mul_f32_e32 v111, v110, v90
	v_fma_f32 v112, -v87, v111, v110
	v_fmac_f32_e32 v111, v112, v90
	v_fma_f32 v87, -v87, v111, v110
	v_div_fmas_f32 v87, v87, v90, v111
	v_div_fixup_f32 v83, v87, v83, 1.0
	v_mul_f32_e32 v83, v83, v91
	v_bfe_u32 v87, v82, 16, 1
	v_add3_u32 v82, v82, v87, s27
	v_bfe_u32 v87, v83, 16, 1
	v_lshrrev_b32_e32 v82, 16, v82
	v_add3_u32 v83, v83, v87, s27
	v_and_or_b32 v82, v83, s28, v82
	global_store_dword v[76:77], v82, off offset:1536
	global_load_dwordx2 v[74:75], v[104:105], off
	s_waitcnt lgkmcnt(0)
	v_cndmask_b32_e64 v90, v86, v72, s[38:39]
	v_cndmask_b32_e64 v91, v72, v86, s[38:39]
	v_add_u32_e32 v72, v124, v127
	v_ashrrev_i32_e32 v73, 31, v72
	v_lshlrev_b64 v[82:83], 9, v[72:73]
	v_lshl_add_u64 v[86:87], v[108:109], 0, v[82:83]
	global_load_dword v86, v[86:87], off
	v_lshlrev_b64 v[72:73], 11, v[72:73]
	v_lshl_add_u64 v[72:73], s[4:5], 0, v[72:73]
	v_lshl_add_u64 v[72:73], v[72:73], 0, v[106:107]
	s_waitcnt vmcnt(1)
	v_add_f32_e32 v74, v90, v74
	v_mul_f32_e32 v74, 0xbfb8aa3b, v74
	v_exp_f32_e32 v74, v74
	v_add_f32_e32 v75, v91, v75
	v_mul_f32_e32 v75, 0xbfb8aa3b, v75
	v_exp_f32_e32 v75, v75
	v_add_f32_e32 v74, 1.0, v74
	v_div_scale_f32 v90, vcc, v74, v74, 1.0
	v_rcp_f32_e32 v110, v90
	s_waitcnt vmcnt(0)
	v_lshlrev_b32_e32 v87, 16, v86
	v_add_f32_e32 v75, 1.0, v75
	v_and_b32_e32 v86, 0xffff0000, v86
	v_fma_f32 v111, -v90, v110, 1.0
	v_fmac_f32_e32 v110, v111, v110
	v_div_scale_f32 v111, vcc, 1.0, v74, 1.0
	v_mul_f32_e32 v112, v111, v110
	v_fma_f32 v113, -v90, v112, v111
	v_fmac_f32_e32 v112, v113, v110
	v_fma_f32 v90, -v90, v112, v111
	v_div_fmas_f32 v90, v90, v110, v112
	v_div_fixup_f32 v74, v90, v74, 1.0
	v_mul_f32_e32 v74, v74, v87
	v_div_scale_f32 v87, vcc, v75, v75, 1.0
	v_rcp_f32_e32 v90, v87
	s_nop 0
	v_fma_f32 v91, -v87, v90, 1.0
	v_fmac_f32_e32 v90, v91, v90
	v_div_scale_f32 v91, vcc, 1.0, v75, 1.0
	v_mul_f32_e32 v110, v91, v90
	v_fma_f32 v111, -v87, v110, v91
	v_fmac_f32_e32 v110, v111, v90
	v_fma_f32 v87, -v87, v110, v91
	v_div_fmas_f32 v87, v87, v90, v110
	v_div_fixup_f32 v75, v87, v75, 1.0
	v_mul_f32_e32 v75, v75, v86
	v_bfe_u32 v86, v74, 16, 1
	v_add3_u32 v74, v74, v86, s27
	v_bfe_u32 v86, v75, 16, 1
	v_lshrrev_b32_e32 v74, 16, v74
	v_add3_u32 v75, v75, v86, s27
	v_and_or_b32 v74, v75, s28, v74
	global_store_dword v[72:73], v74, off offset:1536
	global_load_dwordx2 v[86:87], v[104:105], off offset:64
	v_cndmask_b32_e64 v74, v68, v69, s[46:47]
	v_cndmask_b32_e64 v74, v74, v70, s[48:49]
	v_cndmask_b32_e64 v74, v74, v71, s[50:51]
	v_cndmask_b32_e64 v75, v68, v69, s[52:53]
	ds_bpermute_b32 v74, v119, v74
	v_cndmask_b32_e64 v75, v75, v70, s[54:55]
	v_cndmask_b32_e64 v75, v75, v71, s[56:57]
	ds_bpermute_b32 v90, v119, v75
	v_cndmask_b32_e64 v75, v68, v69, s[58:59]
	v_cndmask_b32_e64 v75, v75, v70, s[60:61]
	v_cndmask_b32_e64 v75, v75, v71, s[94:95]
	s_waitcnt lgkmcnt(1)
	v_cndmask_b32_e64 v110, v74, v75, s[38:39]
	v_cndmask_b32_e64 v91, v75, v74, s[38:39]
	v_lshl_add_u64 v[74:75], s[6:7], 0, v[78:79]
	v_lshl_add_u64 v[78:79], v[74:75], 0, v[88:89]
	global_load_dword v78, v[78:79], off
	v_cndmask_b32_e64 v68, v68, v69, s[12:13]
	v_cndmask_b32_e64 v68, v68, v70, s[40:41]
	v_cndmask_b32_e64 v68, v68, v71, s[44:45]
	s_waitcnt vmcnt(1)
	v_add_f32_e32 v86, v110, v86
	v_mul_f32_e32 v86, 0xbfb8aa3b, v86
	v_exp_f32_e32 v86, v86
	s_waitcnt vmcnt(0)
	v_lshlrev_b32_e32 v79, 16, v78
	v_add_f32_e32 v86, 1.0, v86
	v_div_scale_f32 v110, vcc, v86, v86, 1.0
	v_rcp_f32_e32 v111, v110
	v_and_b32_e32 v78, 0xffff0000, v78
	v_fma_f32 v112, -v110, v111, 1.0
	v_fmac_f32_e32 v111, v112, v111
	v_div_scale_f32 v112, vcc, 1.0, v86, 1.0
	v_mul_f32_e32 v113, v112, v111
	v_fma_f32 v114, -v110, v113, v112
	v_fmac_f32_e32 v113, v114, v111
	v_fma_f32 v110, -v110, v113, v112
	v_div_fmas_f32 v110, v110, v111, v113
	v_div_fixup_f32 v86, v110, v86, 1.0
	v_mul_f32_e32 v79, v86, v79
	v_add_f32_e32 v86, v91, v87
	v_mul_f32_e32 v86, 0xbfb8aa3b, v86
	v_exp_f32_e32 v86, v86
	s_nop 0
	v_add_f32_e32 v86, 1.0, v86
	v_div_scale_f32 v87, vcc, v86, v86, 1.0
	v_rcp_f32_e32 v91, v87
	s_nop 0
	v_fma_f32 v110, -v87, v91, 1.0
	v_fmac_f32_e32 v91, v110, v91
	v_div_scale_f32 v110, vcc, 1.0, v86, 1.0
	v_mul_f32_e32 v111, v110, v91
	v_fma_f32 v112, -v87, v111, v110
	v_fmac_f32_e32 v111, v112, v91
	v_fma_f32 v87, -v87, v111, v110
	v_div_fmas_f32 v87, v87, v91, v111
	v_div_fixup_f32 v86, v87, v86, 1.0
	v_mul_f32_e32 v78, v86, v78
	v_bfe_u32 v86, v79, 16, 1
	v_add3_u32 v79, v79, v86, s27
	v_bfe_u32 v86, v78, 16, 1
	v_lshrrev_b32_e32 v79, 16, v79
	v_add3_u32 v78, v78, v86, s27
	v_and_or_b32 v78, v78, s28, v79
	global_store_dword v[76:77], v78, off offset:1568
	global_load_dwordx2 v[70:71], v[104:105], off offset:64
	s_waitcnt lgkmcnt(0)
	v_cndmask_b32_e64 v86, v90, v68, s[38:39]
	v_cndmask_b32_e64 v87, v68, v90, s[38:39]
	v_lshl_add_u64 v[68:69], s[6:7], 0, v[82:83]
	v_lshl_add_u64 v[78:79], v[68:69], 0, v[88:89]
	global_load_dword v78, v[78:79], off
	s_waitcnt vmcnt(1)
	v_add_f32_e32 v70, v86, v70
	v_mul_f32_e32 v70, 0xbfb8aa3b, v70
	v_exp_f32_e32 v70, v70
	v_add_f32_e32 v71, v87, v71
	v_mul_f32_e32 v71, 0xbfb8aa3b, v71
	v_exp_f32_e32 v71, v71
	v_add_f32_e32 v70, 1.0, v70
	v_div_scale_f32 v82, vcc, v70, v70, 1.0
	v_rcp_f32_e32 v83, v82
	s_waitcnt vmcnt(0)
	v_lshlrev_b32_e32 v79, 16, v78
	v_add_f32_e32 v71, 1.0, v71
	v_and_b32_e32 v78, 0xffff0000, v78
	v_fma_f32 v86, -v82, v83, 1.0
	v_fmac_f32_e32 v83, v86, v83
	v_div_scale_f32 v86, vcc, 1.0, v70, 1.0
	v_mul_f32_e32 v90, v86, v83
	v_fma_f32 v91, -v82, v90, v86
	v_fmac_f32_e32 v90, v91, v83
	v_fma_f32 v82, -v82, v90, v86
	v_div_fmas_f32 v82, v82, v83, v90
	v_div_fixup_f32 v70, v82, v70, 1.0
	v_mul_f32_e32 v70, v70, v79
	v_div_scale_f32 v79, vcc, v71, v71, 1.0
	v_rcp_f32_e32 v82, v79
	s_nop 0
	v_fma_f32 v83, -v79, v82, 1.0
	v_fmac_f32_e32 v82, v83, v82
	v_div_scale_f32 v83, vcc, 1.0, v71, 1.0
	v_mul_f32_e32 v86, v83, v82
	v_fma_f32 v87, -v79, v86, v83
	v_fmac_f32_e32 v86, v87, v82
	v_fma_f32 v79, -v79, v86, v83
	v_div_fmas_f32 v79, v79, v82, v86
	v_div_fixup_f32 v71, v79, v71, 1.0
	v_mul_f32_e32 v71, v71, v78
	v_bfe_u32 v78, v70, 16, 1
	v_add3_u32 v70, v70, v78, s27
	v_bfe_u32 v78, v71, 16, 1
	v_lshrrev_b32_e32 v70, 16, v70
	v_add3_u32 v71, v71, v78, s27
	v_and_or_b32 v70, v71, s28, v70
	global_store_dword v[72:73], v70, off offset:1568
	v_cndmask_b32_e64 v70, v64, v65, s[46:47]
	v_cndmask_b32_e64 v70, v70, v66, s[48:49]
	v_cndmask_b32_e64 v70, v70, v67, s[50:51]
	v_cndmask_b32_e64 v71, v64, v65, s[52:53]
	ds_bpermute_b32 v70, v119, v70
	v_cndmask_b32_e64 v71, v71, v66, s[54:55]
	v_cndmask_b32_e64 v71, v71, v67, s[56:57]
	ds_bpermute_b32 v78, v119, v71
	v_cndmask_b32_e64 v71, v64, v65, s[58:59]
	v_cndmask_b32_e64 v71, v71, v66, s[60:61]
	v_cndmask_b32_e64 v71, v71, v67, s[94:95]
	s_waitcnt lgkmcnt(1)
	v_cndmask_b32_e64 v82, v70, v71, s[38:39]
	v_cndmask_b32_e64 v79, v71, v70, s[38:39]
	global_load_dwordx2 v[70:71], v[104:105], off offset:128
	v_lshl_add_u64 v[86:87], v[74:75], 0, v[84:85]
	global_load_dword v83, v[86:87], off
	v_cndmask_b32_e64 v64, v64, v65, s[12:13]
	v_cndmask_b32_e64 v64, v64, v66, s[40:41]
	v_cndmask_b32_e64 v64, v64, v67, s[44:45]
	v_lshl_add_u64 v[66:67], v[68:69], 0, v[84:85]
	v_lshl_add_u64 v[74:75], v[74:75], 0, v[80:81]
	s_waitcnt vmcnt(1)
	v_add_f32_e32 v70, v82, v70
	v_mul_f32_e32 v70, 0xbfb8aa3b, v70
	v_exp_f32_e32 v70, v70
	v_add_f32_e32 v71, v79, v71
	v_mul_f32_e32 v71, 0xbfb8aa3b, v71
	v_exp_f32_e32 v71, v71
	v_add_f32_e32 v70, 1.0, v70
	v_div_scale_f32 v82, vcc, v70, v70, 1.0
	v_rcp_f32_e32 v87, v82
	v_add_f32_e32 v71, 1.0, v71
	s_waitcnt vmcnt(0)
	v_lshlrev_b32_e32 v86, 16, v83
	v_and_b32_e32 v83, 0xffff0000, v83
	v_fma_f32 v90, -v82, v87, 1.0
	v_fmac_f32_e32 v87, v90, v87
	v_div_scale_f32 v90, vcc, 1.0, v70, 1.0
	v_mul_f32_e32 v91, v90, v87
	v_fma_f32 v110, -v82, v91, v90
	v_fmac_f32_e32 v91, v110, v87
	v_fma_f32 v82, -v82, v91, v90
	v_div_fmas_f32 v82, v82, v87, v91
	v_div_scale_f32 v79, vcc, v71, v71, 1.0
	v_div_fixup_f32 v70, v82, v70, 1.0
	v_rcp_f32_e32 v82, v79
	v_mul_f32_e32 v70, v70, v86
	v_fma_f32 v86, -v79, v82, 1.0
	v_fmac_f32_e32 v82, v86, v82
	v_div_scale_f32 v86, vcc, 1.0, v71, 1.0
	v_mul_f32_e32 v87, v86, v82
	v_fma_f32 v90, -v79, v87, v86
	v_fmac_f32_e32 v87, v90, v82
	v_fma_f32 v79, -v79, v87, v86
	v_div_fmas_f32 v79, v79, v82, v87
	v_div_fixup_f32 v71, v79, v71, 1.0
	v_mul_f32_e32 v71, v71, v83
	v_bfe_u32 v79, v70, 16, 1
	v_add3_u32 v70, v70, v79, s27
	v_bfe_u32 v79, v71, 16, 1
	v_lshrrev_b32_e32 v70, 16, v70
	v_add3_u32 v71, v71, v79, s27
	v_and_or_b32 v70, v71, s28, v70
	global_store_dword v[76:77], v70, off offset:1600
	s_waitcnt lgkmcnt(0)
	v_cndmask_b32_e64 v70, v78, v64, s[38:39]
	v_cndmask_b32_e64 v71, v64, v78, s[38:39]
	global_load_dwordx2 v[64:65], v[104:105], off offset:128
	s_waitcnt vmcnt(0)
	v_add_f32_e32 v64, v70, v64
	global_load_dword v66, v[66:67], off
	v_mul_f32_e32 v64, 0xbfb8aa3b, v64
	v_exp_f32_e32 v64, v64
	v_add_f32_e32 v65, v71, v65
	v_mul_f32_e32 v65, 0xbfb8aa3b, v65
	v_exp_f32_e32 v65, v65
	v_add_f32_e32 v64, 1.0, v64
	v_div_scale_f32 v70, vcc, v64, v64, 1.0
	v_rcp_f32_e32 v78, v70
	v_add_f32_e32 v65, 1.0, v65
	v_fma_f32 v79, -v70, v78, 1.0
	v_fmac_f32_e32 v78, v79, v78
	v_div_scale_f32 v79, vcc, 1.0, v64, 1.0
	v_mul_f32_e32 v82, v79, v78
	v_fma_f32 v83, -v70, v82, v79
	v_fmac_f32_e32 v82, v83, v78
	v_fma_f32 v70, -v70, v82, v79
	v_div_fmas_f32 v70, v70, v78, v82
	v_div_fixup_f32 v64, v70, v64, 1.0
	s_waitcnt vmcnt(0)
	v_lshlrev_b32_e32 v67, 16, v66
	v_mul_f32_e32 v64, v64, v67
	v_div_scale_f32 v67, vcc, v65, v65, 1.0
	v_rcp_f32_e32 v70, v67
	v_and_b32_e32 v66, 0xffff0000, v66
	v_fma_f32 v71, -v67, v70, 1.0
	v_fmac_f32_e32 v70, v71, v70
	v_div_scale_f32 v71, vcc, 1.0, v65, 1.0
	v_mul_f32_e32 v78, v71, v70
	v_fma_f32 v79, -v67, v78, v71
	v_fmac_f32_e32 v78, v79, v70
	v_fma_f32 v67, -v67, v78, v71
	v_div_fmas_f32 v67, v67, v70, v78
	v_div_fixup_f32 v65, v67, v65, 1.0
	v_mul_f32_e32 v65, v65, v66
	v_bfe_u32 v66, v64, 16, 1
	v_add3_u32 v64, v64, v66, s27
	v_bfe_u32 v66, v65, 16, 1
	v_lshrrev_b32_e32 v64, 16, v64
	v_add3_u32 v65, v65, v66, s27
	v_and_or_b32 v64, v65, s28, v64
	global_store_dword v[72:73], v64, off offset:1600
	v_cndmask_b32_e64 v64, v60, v61, s[46:47]
	v_cndmask_b32_e64 v64, v64, v62, s[48:49]
	v_cndmask_b32_e64 v64, v64, v63, s[50:51]
	v_cndmask_b32_e64 v65, v60, v61, s[52:53]
	ds_bpermute_b32 v64, v119, v64
	v_cndmask_b32_e64 v65, v65, v62, s[54:55]
	v_cndmask_b32_e64 v65, v65, v63, s[56:57]
	ds_bpermute_b32 v66, v119, v65
	v_cndmask_b32_e64 v65, v60, v61, s[58:59]
	v_cndmask_b32_e64 v65, v65, v62, s[60:61]
	v_cndmask_b32_e64 v65, v65, v63, s[94:95]
	s_waitcnt lgkmcnt(1)
	v_cndmask_b32_e64 v70, v64, v65, s[38:39]
	v_cndmask_b32_e64 v67, v65, v64, s[38:39]
	global_load_dwordx2 v[64:65], v[104:105], off offset:192
	global_load_dword v71, v[74:75], off
	v_cndmask_b32_e64 v60, v60, v61, s[12:13]
	v_cndmask_b32_e64 v60, v60, v62, s[40:41]
	v_cndmask_b32_e64 v60, v60, v63, s[44:45]
	v_lshl_add_u64 v[62:63], v[68:69], 0, v[80:81]
	s_waitcnt vmcnt(1)
	v_add_f32_e32 v64, v70, v64
	v_mul_f32_e32 v64, 0xbfb8aa3b, v64
	v_exp_f32_e32 v64, v64
	v_add_f32_e32 v65, v67, v65
	v_mul_f32_e32 v65, 0xbfb8aa3b, v65
	v_exp_f32_e32 v65, v65
	v_add_f32_e32 v64, 1.0, v64
	v_div_scale_f32 v70, vcc, v64, v64, 1.0
	v_rcp_f32_e32 v75, v70
	v_add_f32_e32 v65, 1.0, v65
	s_waitcnt vmcnt(0)
	v_lshlrev_b32_e32 v74, 16, v71
	v_and_b32_e32 v71, 0xffff0000, v71
	v_fma_f32 v78, -v70, v75, 1.0
	v_fmac_f32_e32 v75, v78, v75
	v_div_scale_f32 v78, vcc, 1.0, v64, 1.0
	v_mul_f32_e32 v79, v78, v75
	v_fma_f32 v82, -v70, v79, v78
	v_fmac_f32_e32 v79, v82, v75
	v_fma_f32 v70, -v70, v79, v78
	v_div_fmas_f32 v70, v70, v75, v79
	v_div_scale_f32 v67, vcc, v65, v65, 1.0
	v_div_fixup_f32 v64, v70, v64, 1.0
	v_rcp_f32_e32 v70, v67
	v_mul_f32_e32 v64, v64, v74
	v_fma_f32 v74, -v67, v70, 1.0
	v_fmac_f32_e32 v70, v74, v70
	v_div_scale_f32 v74, vcc, 1.0, v65, 1.0
	v_mul_f32_e32 v75, v74, v70
	v_fma_f32 v78, -v67, v75, v74
	v_fmac_f32_e32 v75, v78, v70
	v_fma_f32 v67, -v67, v75, v74
	v_div_fmas_f32 v67, v67, v70, v75
	v_div_fixup_f32 v65, v67, v65, 1.0
	v_mul_f32_e32 v65, v65, v71
	v_bfe_u32 v67, v64, 16, 1
	v_add3_u32 v64, v64, v67, s27
	v_bfe_u32 v67, v65, 16, 1
	v_lshrrev_b32_e32 v64, 16, v64
	v_add3_u32 v65, v65, v67, s27
	v_and_or_b32 v64, v65, s28, v64
	global_store_dword v[76:77], v64, off offset:1632
	s_waitcnt lgkmcnt(0)
	v_cndmask_b32_e64 v64, v66, v60, s[38:39]
	v_cndmask_b32_e64 v65, v60, v66, s[38:39]
	global_load_dwordx2 v[60:61], v[104:105], off offset:192
	s_waitcnt vmcnt(0)
	v_add_f32_e32 v60, v64, v60
	global_load_dword v62, v[62:63], off
	v_mul_f32_e32 v60, 0xbfb8aa3b, v60
	v_exp_f32_e32 v60, v60
	v_add_f32_e32 v61, v65, v61
	v_mul_f32_e32 v61, 0xbfb8aa3b, v61
	v_exp_f32_e32 v61, v61
	v_add_f32_e32 v60, 1.0, v60
	v_div_scale_f32 v64, vcc, v60, v60, 1.0
	v_rcp_f32_e32 v66, v64
	v_add_f32_e32 v61, 1.0, v61
	v_fma_f32 v67, -v64, v66, 1.0
	v_fmac_f32_e32 v66, v67, v66
	v_div_scale_f32 v67, vcc, 1.0, v60, 1.0
	v_mul_f32_e32 v68, v67, v66
	v_fma_f32 v69, -v64, v68, v67
	v_fmac_f32_e32 v68, v69, v66
	v_fma_f32 v64, -v64, v68, v67
	v_div_fmas_f32 v64, v64, v66, v68
	v_div_fixup_f32 v60, v64, v60, 1.0
	s_waitcnt vmcnt(0)
	v_lshlrev_b32_e32 v63, 16, v62
	v_mul_f32_e32 v60, v60, v63
	v_div_scale_f32 v63, vcc, v61, v61, 1.0
	v_rcp_f32_e32 v64, v63
	v_and_b32_e32 v62, 0xffff0000, v62
	v_fma_f32 v65, -v63, v64, 1.0
	v_fmac_f32_e32 v64, v65, v64
	v_div_scale_f32 v65, vcc, 1.0, v61, 1.0
	v_mul_f32_e32 v66, v65, v64
	v_fma_f32 v67, -v63, v66, v65
	v_fmac_f32_e32 v66, v67, v64
	v_fma_f32 v63, -v63, v66, v65
	v_div_fmas_f32 v63, v63, v64, v66
	v_div_fixup_f32 v61, v63, v61, 1.0
	v_mul_f32_e32 v61, v61, v62
	v_bfe_u32 v62, v60, 16, 1
	v_add3_u32 v60, v60, v62, s27
	v_bfe_u32 v62, v61, 16, 1
	v_lshrrev_b32_e32 v60, 16, v60
	v_add3_u32 v61, v61, v62, s27
	v_and_or_b32 v60, v61, s28, v60
	global_store_dword v[72:73], v60, off offset:1632
	global_load_dwordx2 v[64:65], v[104:105], off
	v_cndmask_b32_e64 v60, v56, v57, s[46:47]
	v_cndmask_b32_e64 v60, v60, v58, s[48:49]
	v_cndmask_b32_e64 v60, v60, v59, s[50:51]
	v_cndmask_b32_e64 v61, v56, v57, s[52:53]
	ds_bpermute_b32 v60, v119, v60
	v_cndmask_b32_e64 v61, v61, v58, s[54:55]
	v_cndmask_b32_e64 v61, v61, v59, s[56:57]
	ds_bpermute_b32 v66, v119, v61
	v_cndmask_b32_e64 v61, v56, v57, s[58:59]
	v_cndmask_b32_e64 v61, v61, v58, s[60:61]
	v_cndmask_b32_e64 v61, v61, v59, s[94:95]
	s_waitcnt lgkmcnt(1)
	v_cndmask_b32_e64 v68, v60, v61, s[38:39]
	v_cndmask_b32_e64 v67, v61, v60, s[38:39]
	v_add_u32_e32 v60, v125, v127
	v_ashrrev_i32_e32 v61, 31, v60
	v_lshlrev_b64 v[62:63], 9, v[60:61]
	v_lshl_add_u64 v[70:71], v[108:109], 0, v[62:63]
	global_load_dword v69, v[70:71], off
	v_lshlrev_b64 v[60:61], 11, v[60:61]
	v_lshl_add_u64 v[60:61], s[4:5], 0, v[60:61]
	v_lshl_add_u64 v[60:61], v[60:61], 0, v[106:107]
	v_cndmask_b32_e64 v56, v56, v57, s[12:13]
	v_cndmask_b32_e64 v56, v56, v58, s[40:41]
	v_cndmask_b32_e64 v56, v56, v59, s[44:45]
	s_waitcnt vmcnt(1)
	v_add_f32_e32 v64, v68, v64
	v_mul_f32_e32 v64, 0xbfb8aa3b, v64
	v_exp_f32_e32 v64, v64
	v_add_f32_e32 v65, v67, v65
	v_mul_f32_e32 v65, 0xbfb8aa3b, v65
	v_exp_f32_e32 v65, v65
	v_add_f32_e32 v64, 1.0, v64
	v_div_scale_f32 v68, vcc, v64, v64, 1.0
	v_rcp_f32_e32 v71, v68
	v_add_f32_e32 v65, 1.0, v65
	v_fma_f32 v72, -v68, v71, 1.0
	v_fmac_f32_e32 v71, v72, v71
	v_div_scale_f32 v72, vcc, 1.0, v64, 1.0
	v_mul_f32_e32 v73, v72, v71
	v_fma_f32 v74, -v68, v73, v72
	v_fmac_f32_e32 v73, v74, v71
	v_fma_f32 v68, -v68, v73, v72
	v_div_fmas_f32 v68, v68, v71, v73
	v_div_scale_f32 v67, vcc, v65, v65, 1.0
	v_div_fixup_f32 v64, v68, v64, 1.0
	v_rcp_f32_e32 v68, v67
	s_waitcnt vmcnt(0)
	v_lshlrev_b32_e32 v70, 16, v69
	v_mul_f32_e32 v64, v64, v70
	v_and_b32_e32 v69, 0xffff0000, v69
	v_fma_f32 v70, -v67, v68, 1.0
	v_fmac_f32_e32 v68, v70, v68
	v_div_scale_f32 v70, vcc, 1.0, v65, 1.0
	v_mul_f32_e32 v71, v70, v68
	v_fma_f32 v72, -v67, v71, v70
	v_fmac_f32_e32 v71, v72, v68
	v_fma_f32 v67, -v67, v71, v70
	v_div_fmas_f32 v67, v67, v68, v71
	v_div_fixup_f32 v65, v67, v65, 1.0
	v_mul_f32_e32 v65, v65, v69
	v_bfe_u32 v67, v64, 16, 1
	v_add3_u32 v64, v64, v67, s27
	v_bfe_u32 v67, v65, 16, 1
	v_lshrrev_b32_e32 v64, 16, v64
	v_add3_u32 v65, v65, v67, s27
	v_and_or_b32 v64, v65, s28, v64
	global_store_dword v[60:61], v64, off offset:1536
	global_load_dwordx2 v[58:59], v[104:105], off
	s_waitcnt lgkmcnt(0)
	v_cndmask_b32_e64 v68, v66, v56, s[38:39]
	v_cndmask_b32_e64 v69, v56, v66, s[38:39]
	v_add_u32_e32 v56, v126, v127
	v_ashrrev_i32_e32 v57, 31, v56
	v_lshlrev_b64 v[64:65], 9, v[56:57]
	v_lshl_add_u64 v[66:67], v[108:109], 0, v[64:65]
	global_load_dword v66, v[66:67], off
	v_lshlrev_b64 v[56:57], 11, v[56:57]
	v_lshl_add_u64 v[56:57], s[4:5], 0, v[56:57]
	v_lshl_add_u64 v[56:57], v[56:57], 0, v[106:107]
	s_waitcnt vmcnt(1)
	v_add_f32_e32 v58, v68, v58
	v_mul_f32_e32 v58, 0xbfb8aa3b, v58
	v_exp_f32_e32 v58, v58
	v_add_f32_e32 v59, v69, v59
	v_mul_f32_e32 v59, 0xbfb8aa3b, v59
	v_exp_f32_e32 v59, v59
	v_add_f32_e32 v58, 1.0, v58
	v_div_scale_f32 v68, vcc, v58, v58, 1.0
	v_rcp_f32_e32 v70, v68
	s_waitcnt vmcnt(0)
	v_lshlrev_b32_e32 v67, 16, v66
	v_add_f32_e32 v59, 1.0, v59
	v_and_b32_e32 v66, 0xffff0000, v66
	v_fma_f32 v71, -v68, v70, 1.0
	v_fmac_f32_e32 v70, v71, v70
	v_div_scale_f32 v71, vcc, 1.0, v58, 1.0
	v_mul_f32_e32 v72, v71, v70
	v_fma_f32 v73, -v68, v72, v71
	v_fmac_f32_e32 v72, v73, v70
	v_fma_f32 v68, -v68, v72, v71
	v_div_fmas_f32 v68, v68, v70, v72
	v_div_fixup_f32 v58, v68, v58, 1.0
	v_mul_f32_e32 v58, v58, v67
	v_div_scale_f32 v67, vcc, v59, v59, 1.0
	v_rcp_f32_e32 v68, v67
	s_nop 0
	v_fma_f32 v69, -v67, v68, 1.0
	v_fmac_f32_e32 v68, v69, v68
	v_div_scale_f32 v69, vcc, 1.0, v59, 1.0
	v_mul_f32_e32 v70, v69, v68
	v_fma_f32 v71, -v67, v70, v69
	v_fmac_f32_e32 v70, v71, v68
	v_fma_f32 v67, -v67, v70, v69
	v_div_fmas_f32 v67, v67, v68, v70
	v_div_fixup_f32 v59, v67, v59, 1.0
	v_mul_f32_e32 v59, v59, v66
	v_bfe_u32 v66, v58, 16, 1
	v_add3_u32 v58, v58, v66, s27
	v_bfe_u32 v66, v59, 16, 1
	v_lshrrev_b32_e32 v58, 16, v58
	v_add3_u32 v59, v59, v66, s27
	v_and_or_b32 v58, v59, s28, v58
	global_store_dword v[56:57], v58, off offset:1536
	global_load_dwordx2 v[66:67], v[104:105], off offset:64
	v_cndmask_b32_e64 v58, v52, v53, s[46:47]
	v_cndmask_b32_e64 v58, v58, v54, s[48:49]
	v_cndmask_b32_e64 v58, v58, v55, s[50:51]
	v_cndmask_b32_e64 v59, v52, v53, s[52:53]
	ds_bpermute_b32 v58, v119, v58
	v_cndmask_b32_e64 v59, v59, v54, s[54:55]
	v_cndmask_b32_e64 v59, v59, v55, s[56:57]
	ds_bpermute_b32 v68, v119, v59
	v_cndmask_b32_e64 v59, v52, v53, s[58:59]
	v_cndmask_b32_e64 v59, v59, v54, s[60:61]
	v_cndmask_b32_e64 v59, v59, v55, s[94:95]
	s_waitcnt lgkmcnt(1)
	v_cndmask_b32_e64 v70, v58, v59, s[38:39]
	v_cndmask_b32_e64 v69, v59, v58, s[38:39]
	v_lshl_add_u64 v[58:59], s[6:7], 0, v[62:63]
	v_lshl_add_u64 v[62:63], v[58:59], 0, v[88:89]
	global_load_dword v62, v[62:63], off
	v_cndmask_b32_e64 v52, v52, v53, s[12:13]
	v_cndmask_b32_e64 v52, v52, v54, s[40:41]
	v_cndmask_b32_e64 v52, v52, v55, s[44:45]
	s_waitcnt vmcnt(1)
	v_add_f32_e32 v66, v70, v66
	v_mul_f32_e32 v66, 0xbfb8aa3b, v66
	v_exp_f32_e32 v66, v66
	s_waitcnt vmcnt(0)
	v_lshlrev_b32_e32 v63, 16, v62
	v_add_f32_e32 v66, 1.0, v66
	v_div_scale_f32 v70, vcc, v66, v66, 1.0
	v_rcp_f32_e32 v71, v70
	v_and_b32_e32 v62, 0xffff0000, v62
	v_fma_f32 v72, -v70, v71, 1.0
	v_fmac_f32_e32 v71, v72, v71
	v_div_scale_f32 v72, vcc, 1.0, v66, 1.0
	v_mul_f32_e32 v73, v72, v71
	v_fma_f32 v74, -v70, v73, v72
	v_fmac_f32_e32 v73, v74, v71
	v_fma_f32 v70, -v70, v73, v72
	v_div_fmas_f32 v70, v70, v71, v73
	v_div_fixup_f32 v66, v70, v66, 1.0
	v_mul_f32_e32 v63, v66, v63
	v_add_f32_e32 v66, v69, v67
	v_mul_f32_e32 v66, 0xbfb8aa3b, v66
	v_exp_f32_e32 v66, v66
	s_nop 0
	v_add_f32_e32 v66, 1.0, v66
	v_div_scale_f32 v67, vcc, v66, v66, 1.0
	v_rcp_f32_e32 v69, v67
	s_nop 0
	v_fma_f32 v70, -v67, v69, 1.0
	v_fmac_f32_e32 v69, v70, v69
	v_div_scale_f32 v70, vcc, 1.0, v66, 1.0
	v_mul_f32_e32 v71, v70, v69
	v_fma_f32 v72, -v67, v71, v70
	v_fmac_f32_e32 v71, v72, v69
	v_fma_f32 v67, -v67, v71, v70
	v_div_fmas_f32 v67, v67, v69, v71
	v_div_fixup_f32 v66, v67, v66, 1.0
	v_mul_f32_e32 v62, v66, v62
	v_bfe_u32 v66, v63, 16, 1
	v_add3_u32 v63, v63, v66, s27
	v_bfe_u32 v66, v62, 16, 1
	v_lshrrev_b32_e32 v63, 16, v63
	v_add3_u32 v62, v62, v66, s27
	v_and_or_b32 v62, v62, s28, v63
	global_store_dword v[60:61], v62, off offset:1568
	global_load_dwordx2 v[54:55], v[104:105], off offset:64
	s_waitcnt lgkmcnt(0)
	v_cndmask_b32_e64 v66, v68, v52, s[38:39]
	v_cndmask_b32_e64 v67, v52, v68, s[38:39]
	v_lshl_add_u64 v[52:53], s[6:7], 0, v[64:65]
	v_lshl_add_u64 v[62:63], v[52:53], 0, v[88:89]
	global_load_dword v62, v[62:63], off
	s_waitcnt vmcnt(1)
	v_add_f32_e32 v54, v66, v54
	v_mul_f32_e32 v54, 0xbfb8aa3b, v54
	v_exp_f32_e32 v54, v54
	v_add_f32_e32 v55, v67, v55
	v_mul_f32_e32 v55, 0xbfb8aa3b, v55
	v_exp_f32_e32 v55, v55
	v_add_f32_e32 v54, 1.0, v54
	v_div_scale_f32 v64, vcc, v54, v54, 1.0
	v_rcp_f32_e32 v65, v64
	s_waitcnt vmcnt(0)
	v_lshlrev_b32_e32 v63, 16, v62
	v_add_f32_e32 v55, 1.0, v55
	v_and_b32_e32 v62, 0xffff0000, v62
	v_fma_f32 v66, -v64, v65, 1.0
	v_fmac_f32_e32 v65, v66, v65
	v_div_scale_f32 v66, vcc, 1.0, v54, 1.0
	v_mul_f32_e32 v68, v66, v65
	v_fma_f32 v69, -v64, v68, v66
	v_fmac_f32_e32 v68, v69, v65
	v_fma_f32 v64, -v64, v68, v66
	v_div_fmas_f32 v64, v64, v65, v68
	v_div_fixup_f32 v54, v64, v54, 1.0
	v_mul_f32_e32 v54, v54, v63
	v_div_scale_f32 v63, vcc, v55, v55, 1.0
	v_rcp_f32_e32 v64, v63
	s_nop 0
	v_fma_f32 v65, -v63, v64, 1.0
	v_fmac_f32_e32 v64, v65, v64
	v_div_scale_f32 v65, vcc, 1.0, v55, 1.0
	v_mul_f32_e32 v66, v65, v64
	v_fma_f32 v67, -v63, v66, v65
	v_fmac_f32_e32 v66, v67, v64
	v_fma_f32 v63, -v63, v66, v65
	v_div_fmas_f32 v63, v63, v64, v66
	v_div_fixup_f32 v55, v63, v55, 1.0
	v_mul_f32_e32 v55, v55, v62
	v_bfe_u32 v62, v54, 16, 1
	v_add3_u32 v54, v54, v62, s27
	v_bfe_u32 v62, v55, 16, 1
	v_lshrrev_b32_e32 v54, 16, v54
	v_add3_u32 v55, v55, v62, s27
	v_and_or_b32 v54, v55, s28, v54
	global_store_dword v[56:57], v54, off offset:1568
	v_cndmask_b32_e64 v54, v48, v49, s[46:47]
	v_cndmask_b32_e64 v54, v54, v50, s[48:49]
	v_cndmask_b32_e64 v54, v54, v51, s[50:51]
	v_cndmask_b32_e64 v55, v48, v49, s[52:53]
	ds_bpermute_b32 v54, v119, v54
	v_cndmask_b32_e64 v55, v55, v50, s[54:55]
	v_cndmask_b32_e64 v55, v55, v51, s[56:57]
	ds_bpermute_b32 v62, v119, v55
	v_cndmask_b32_e64 v55, v48, v49, s[58:59]
	v_cndmask_b32_e64 v55, v55, v50, s[60:61]
	v_cndmask_b32_e64 v55, v55, v51, s[94:95]
	s_waitcnt lgkmcnt(1)
	v_cndmask_b32_e64 v64, v54, v55, s[38:39]
	v_cndmask_b32_e64 v63, v55, v54, s[38:39]
	global_load_dwordx2 v[54:55], v[104:105], off offset:128
	v_lshl_add_u64 v[66:67], v[58:59], 0, v[84:85]
	global_load_dword v65, v[66:67], off
	v_cndmask_b32_e64 v48, v48, v49, s[12:13]
	v_cndmask_b32_e64 v48, v48, v50, s[40:41]
	v_cndmask_b32_e64 v48, v48, v51, s[44:45]
	v_lshl_add_u64 v[50:51], v[52:53], 0, v[84:85]
	v_lshl_add_u64 v[58:59], v[58:59], 0, v[80:81]
	s_waitcnt vmcnt(1)
	v_add_f32_e32 v54, v64, v54
	v_mul_f32_e32 v54, 0xbfb8aa3b, v54
	v_exp_f32_e32 v54, v54
	v_add_f32_e32 v55, v63, v55
	v_mul_f32_e32 v55, 0xbfb8aa3b, v55
	v_exp_f32_e32 v55, v55
	v_add_f32_e32 v54, 1.0, v54
	v_div_scale_f32 v64, vcc, v54, v54, 1.0
	v_rcp_f32_e32 v67, v64
	v_add_f32_e32 v55, 1.0, v55
	s_waitcnt vmcnt(0)
	v_lshlrev_b32_e32 v66, 16, v65
	v_and_b32_e32 v65, 0xffff0000, v65
	v_fma_f32 v68, -v64, v67, 1.0
	v_fmac_f32_e32 v67, v68, v67
	v_div_scale_f32 v68, vcc, 1.0, v54, 1.0
	v_mul_f32_e32 v69, v68, v67
	v_fma_f32 v70, -v64, v69, v68
	v_fmac_f32_e32 v69, v70, v67
	v_fma_f32 v64, -v64, v69, v68
	v_div_fmas_f32 v64, v64, v67, v69
	v_div_scale_f32 v63, vcc, v55, v55, 1.0
	v_div_fixup_f32 v54, v64, v54, 1.0
	v_rcp_f32_e32 v64, v63
	v_mul_f32_e32 v54, v54, v66
	v_fma_f32 v66, -v63, v64, 1.0
	v_fmac_f32_e32 v64, v66, v64
	v_div_scale_f32 v66, vcc, 1.0, v55, 1.0
	v_mul_f32_e32 v67, v66, v64
	v_fma_f32 v68, -v63, v67, v66
	v_fmac_f32_e32 v67, v68, v64
	v_fma_f32 v63, -v63, v67, v66
	v_div_fmas_f32 v63, v63, v64, v67
	v_div_fixup_f32 v55, v63, v55, 1.0
	v_mul_f32_e32 v55, v55, v65
	v_bfe_u32 v63, v54, 16, 1
	v_add3_u32 v54, v54, v63, s27
	v_bfe_u32 v63, v55, 16, 1
	v_lshrrev_b32_e32 v54, 16, v54
	v_add3_u32 v55, v55, v63, s27
	v_and_or_b32 v54, v55, s28, v54
	global_store_dword v[60:61], v54, off offset:1600
	s_waitcnt lgkmcnt(0)
	v_cndmask_b32_e64 v54, v62, v48, s[38:39]
	v_cndmask_b32_e64 v55, v48, v62, s[38:39]
	global_load_dwordx2 v[48:49], v[104:105], off offset:128
	s_waitcnt vmcnt(0)
	v_add_f32_e32 v48, v54, v48
	global_load_dword v50, v[50:51], off
	v_mul_f32_e32 v48, 0xbfb8aa3b, v48
	v_exp_f32_e32 v48, v48
	v_add_f32_e32 v49, v55, v49
	v_mul_f32_e32 v49, 0xbfb8aa3b, v49
	v_exp_f32_e32 v49, v49
	v_add_f32_e32 v48, 1.0, v48
	v_div_scale_f32 v54, vcc, v48, v48, 1.0
	v_rcp_f32_e32 v62, v54
	v_add_f32_e32 v49, 1.0, v49
	v_fma_f32 v63, -v54, v62, 1.0
	v_fmac_f32_e32 v62, v63, v62
	v_div_scale_f32 v63, vcc, 1.0, v48, 1.0
	v_mul_f32_e32 v64, v63, v62
	v_fma_f32 v65, -v54, v64, v63
	v_fmac_f32_e32 v64, v65, v62
	v_fma_f32 v54, -v54, v64, v63
	v_div_fmas_f32 v54, v54, v62, v64
	v_div_fixup_f32 v48, v54, v48, 1.0
	s_waitcnt vmcnt(0)
	v_lshlrev_b32_e32 v51, 16, v50
	v_mul_f32_e32 v48, v48, v51
	v_div_scale_f32 v51, vcc, v49, v49, 1.0
	v_rcp_f32_e32 v54, v51
	v_and_b32_e32 v50, 0xffff0000, v50
	v_fma_f32 v55, -v51, v54, 1.0
	v_fmac_f32_e32 v54, v55, v54
	v_div_scale_f32 v55, vcc, 1.0, v49, 1.0
	v_mul_f32_e32 v62, v55, v54
	v_fma_f32 v63, -v51, v62, v55
	v_fmac_f32_e32 v62, v63, v54
	v_fma_f32 v51, -v51, v62, v55
	v_div_fmas_f32 v51, v51, v54, v62
	v_div_fixup_f32 v49, v51, v49, 1.0
	v_mul_f32_e32 v49, v49, v50
	v_bfe_u32 v50, v48, 16, 1
	v_add3_u32 v48, v48, v50, s27
	v_bfe_u32 v50, v49, 16, 1
	v_lshrrev_b32_e32 v48, 16, v48
	v_add3_u32 v49, v49, v50, s27
	v_and_or_b32 v48, v49, s28, v48
	global_store_dword v[56:57], v48, off offset:1600
	v_cndmask_b32_e64 v48, v44, v45, s[46:47]
	v_cndmask_b32_e64 v48, v48, v46, s[48:49]
	v_cndmask_b32_e64 v48, v48, v47, s[50:51]
	v_cndmask_b32_e64 v49, v44, v45, s[52:53]
	ds_bpermute_b32 v48, v119, v48
	v_cndmask_b32_e64 v49, v49, v46, s[54:55]
	v_cndmask_b32_e64 v49, v49, v47, s[56:57]
	ds_bpermute_b32 v50, v119, v49
	v_cndmask_b32_e64 v49, v44, v45, s[58:59]
	v_cndmask_b32_e64 v49, v49, v46, s[60:61]
	v_cndmask_b32_e64 v49, v49, v47, s[94:95]
	s_waitcnt lgkmcnt(1)
	v_cndmask_b32_e64 v54, v48, v49, s[38:39]
	v_cndmask_b32_e64 v51, v49, v48, s[38:39]
	global_load_dwordx2 v[48:49], v[104:105], off offset:192
	global_load_dword v55, v[58:59], off
	v_cndmask_b32_e64 v44, v44, v45, s[12:13]
	v_cndmask_b32_e64 v44, v44, v46, s[40:41]
	v_cndmask_b32_e64 v44, v44, v47, s[44:45]
	v_lshl_add_u64 v[46:47], v[52:53], 0, v[80:81]
	v_readlane_b32 s94, v235, 51
	v_readlane_b32 s61, v235, 55
	s_movk_i32 s60, 0x17ff
	v_readlane_b32 s95, v235, 52
	s_waitcnt vmcnt(1)
	v_add_f32_e32 v48, v54, v48
	v_mul_f32_e32 v48, 0xbfb8aa3b, v48
	v_exp_f32_e32 v48, v48
	v_add_f32_e32 v49, v51, v49
	v_mul_f32_e32 v49, 0xbfb8aa3b, v49
	v_exp_f32_e32 v49, v49
	v_add_f32_e32 v48, 1.0, v48
	v_div_scale_f32 v54, s[46:47], v48, v48, 1.0
	v_rcp_f32_e32 v59, v54
	v_add_f32_e32 v49, 1.0, v49
	v_div_scale_f32 v51, s[46:47], v49, v49, 1.0
	v_fma_f32 v62, -v54, v59, 1.0
	v_fmac_f32_e32 v59, v62, v59
	v_div_scale_f32 v62, vcc, 1.0, v48, 1.0
	v_mul_f32_e32 v63, v62, v59
	v_fma_f32 v64, -v54, v63, v62
	v_fmac_f32_e32 v63, v64, v59
	v_fma_f32 v54, -v54, v63, v62
	v_div_fmas_f32 v54, v54, v59, v63
	v_div_fixup_f32 v48, v54, v48, 1.0
	v_rcp_f32_e32 v54, v51
	s_waitcnt vmcnt(0)
	v_lshlrev_b32_e32 v58, 16, v55
	v_mul_f32_e32 v48, v48, v58
	v_and_b32_e32 v55, 0xffff0000, v55
	v_fma_f32 v58, -v51, v54, 1.0
	v_fmac_f32_e32 v54, v58, v54
	v_div_scale_f32 v58, vcc, 1.0, v49, 1.0
	v_mul_f32_e32 v59, v58, v54
	v_fma_f32 v62, -v51, v59, v58
	v_fmac_f32_e32 v59, v62, v54
	v_fma_f32 v51, -v51, v59, v58
	v_div_fmas_f32 v51, v51, v54, v59
	v_div_fixup_f32 v49, v51, v49, 1.0
	v_mul_f32_e32 v49, v49, v55
	v_bfe_u32 v51, v48, 16, 1
	v_add3_u32 v48, v48, v51, s27
	v_bfe_u32 v51, v49, 16, 1
	v_lshrrev_b32_e32 v48, 16, v48
	v_add3_u32 v49, v49, v51, s27
	v_and_or_b32 v48, v49, s28, v48
	global_store_dword v[60:61], v48, off offset:1632
	s_waitcnt lgkmcnt(0)
	v_cndmask_b32_e64 v48, v50, v44, s[38:39]
	v_cndmask_b32_e64 v49, v44, v50, s[38:39]
	global_load_dwordx2 v[44:45], v[104:105], off offset:192
	s_waitcnt vmcnt(0)
	v_add_f32_e32 v44, v48, v44
	global_load_dword v46, v[46:47], off
	v_mul_f32_e32 v44, 0xbfb8aa3b, v44
	v_exp_f32_e32 v44, v44
	v_add_f32_e32 v45, v49, v45
	v_mul_f32_e32 v45, 0xbfb8aa3b, v45
	v_exp_f32_e32 v45, v45
	v_add_f32_e32 v44, 1.0, v44
	v_div_scale_f32 v48, s[40:41], v44, v44, 1.0
	v_rcp_f32_e32 v50, v48
	v_add_f32_e32 v45, 1.0, v45
	v_fma_f32 v51, -v48, v50, 1.0
	v_fmac_f32_e32 v50, v51, v50
	v_div_scale_f32 v51, vcc, 1.0, v44, 1.0
	v_mul_f32_e32 v52, v51, v50
	v_fma_f32 v53, -v48, v52, v51
	v_fmac_f32_e32 v52, v53, v50
	v_fma_f32 v48, -v48, v52, v51
	v_div_fmas_f32 v48, v48, v50, v52
	v_div_fixup_f32 v44, v48, v44, 1.0
	s_waitcnt vmcnt(0)
	v_lshlrev_b32_e32 v47, 16, v46
	v_mul_f32_e32 v44, v44, v47
	v_div_scale_f32 v47, s[40:41], v45, v45, 1.0
	v_rcp_f32_e32 v48, v47
	v_and_b32_e32 v46, 0xffff0000, v46
	v_fma_f32 v49, -v47, v48, 1.0
	v_fmac_f32_e32 v48, v49, v48
	v_div_scale_f32 v49, vcc, 1.0, v45, 1.0
	v_mul_f32_e32 v50, v49, v48
	v_fma_f32 v51, -v47, v50, v49
	v_fmac_f32_e32 v50, v51, v48
	v_fma_f32 v47, -v47, v50, v49
	v_div_fmas_f32 v47, v47, v48, v50
	v_div_fixup_f32 v45, v47, v45, 1.0
	v_mul_f32_e32 v45, v45, v46
	v_bfe_u32 v46, v44, 16, 1
	v_add3_u32 v44, v44, v46, s27
	v_bfe_u32 v46, v45, 16, 1
	v_lshrrev_b32_e32 v44, 16, v44
	v_add3_u32 v45, v45, v46, s27
	v_and_or_b32 v44, v45, s28, v44
	global_store_dword v[56:57], v44, off offset:1632
	v_mov_b32_e32 v44, 0
	v_mov_b32_e32 v45, v44
	v_mov_b32_e32 v46, v44
	v_mov_b32_e32 v47, v44
	v_mov_b32_e32 v48, v44
	v_mov_b32_e32 v49, v44
	v_mov_b32_e32 v50, v44
	v_mov_b32_e32 v51, v44
	v_mov_b32_e32 v52, v44
	v_mov_b32_e32 v53, v44
	v_mov_b32_e32 v54, v44
	v_mov_b32_e32 v55, v44
	v_mov_b32_e32 v56, v44
	v_mov_b32_e32 v57, v44
	v_mov_b32_e32 v58, v44
	v_mov_b32_e32 v59, v44
	v_mov_b32_e32 v60, v44
	v_mov_b32_e32 v61, v44
	v_mov_b32_e32 v62, v44
	v_mov_b32_e32 v63, v44
	v_mov_b32_e32 v64, v44
	v_mov_b32_e32 v65, v44
	v_mov_b32_e32 v66, v44
	v_mov_b32_e32 v67, v44
	v_mov_b32_e32 v68, v44
	v_mov_b32_e32 v69, v44
	v_mov_b32_e32 v70, v44
	v_mov_b32_e32 v71, v44
	v_mov_b32_e32 v72, v44
	v_mov_b32_e32 v73, v44
	v_mov_b32_e32 v74, v44
	v_mov_b32_e32 v75, v44
	v_mov_b32_e32 v76, v44
	v_mov_b32_e32 v77, v44
	v_mov_b32_e32 v78, v44
	v_mov_b32_e32 v79, v44
	v_mov_b32_e32 v80, v44
	v_mov_b32_e32 v81, v44
	v_mov_b32_e32 v82, v44
	v_mov_b32_e32 v83, v44
	v_mov_b32_e32 v84, v44
	v_mov_b32_e32 v85, v44
	v_mov_b32_e32 v86, v44
	v_mov_b32_e32 v87, v44
	v_mov_b32_e32 v88, v44
	v_mov_b32_e32 v89, v44
	v_mov_b32_e32 v90, v44
	v_mov_b32_e32 v91, v44
	s_branch .LBB0_323
.LBB0_336:
	s_branch .LBB0_560
.LBB0_559:
	v_readlane_b32 s16, v234, 0
	v_readlane_b32 s17, v234, 1
